# convert_weights: read-once f32 weight loads use the nt policy (on top of nt residual-stream stores)
# speedup vs baseline: 1.0480x; 1.0066x over previous
; #define LAS __attribute__((address_space(3)))
; __device__ __forceinline__ void transpose_item(const float* W, int K, int N, bf16_t* WT, int mode, LAS float* scr, int item, int lane) {
;     const int nblk = N / 32, kb = item / nblk, nb = item % nblk, k0 = 64 * kb, n0 = 32 * nb;
; #pragma unroll
;     for (int i = 0; i < 32; ++i) { const int kk = 2 * i + (lane >> 5); scr[kk * 33 + (lane & 31)] = W[(size_t)(k0 + kk) * N + n0 + (lane & 31)]; }
; __device__ __forceinline__ void convert_weights(PPtr P, int li, LAS unsigned char* lds, int gw, int NGW, int wave, int lane) {
;     ...
;     for (int it = gw; it < NIT; it += NGW) {
;         int r = it;
;         if (r < I_IN) { transpose_item(P->in[5] + (size_t)li * 1024 * 3232, 1024, 3232, Wb + W_IN, 0, scr, r, lane); continue; } r -= I_IN;
;         if (r < I_GATE) { transpose_item(P->in[6] + (size_t)li * 1024 * 4096, 1024, 4096, Wb + W_GATE, 0, scr, r, lane); continue; } r -= I_GATE;
;         if (r < I_UQ) { transpose_item(P->in[16] + (size_t)li * 256 * 768, 256, 768, Wb + W_UQ, 1, scr, r, lane); continue; } r -= I_UQ;
;         if (r < I_UKV) { transpose_item(P->in[17] + (size_t)li * 128 * 1024, 128, 1024, Wb + W_UKV, 0, scr, r, lane); continue; } r -= I_UKV;
;         if (r < I_GLU) { transpose_item(P->in[26] + (size_t)li * 512 * 1024, 512, 1024, Wb + W_GLU, 2, scr, r, lane); continue; } r -= I_GLU;
;         if (r < 4 * I_BR) { const int b = r / I_BR; transpose_item(P->in[27 + b] + (size_t)li * 512 * 1024, 512, 1024, Wb + W_BR + (size_t)b * 524288, 0, scr, r % I_BR, lane); continue; } r -= 4 * I_BR;
;         if (r < I_OUT) { transpose_item(P->in[31] + (size_t)li * 1024 * 1024, 1024, 1024, Wb + W_OUT, 0, scr, r, lane); continue; } r -= I_OUT;
;         if (r < I_F1) { transpose_item(P->in[32] + (size_t)li * 1024 * 4096, 1024, 4096, Wb + W_F1, 0, scr, r, lane); continue; } r -= I_F1;
;         transpose_item(P->in[33] + (size_t)li * 4096 * 1024, 4096, 1024, Wb + W_F2, 0, scr, r, lane);
.LBB0_14:
	s_cmpk_gt_i32 s38, 0x64f
	s_mov_b64 s[10:11], -1
	s_cbranch_scc0 .LBB0_60
	s_cmpk_gt_u32 s38, 0xe4f
	s_cbranch_scc0 .LBB0_57
	s_cmpk_gt_u32 s38, 0xeaf
	s_cbranch_scc0 .LBB0_38
	s_cmpk_gt_u32 s38, 0xeef
	s_cbranch_scc0 .LBB0_35
	s_cmpk_gt_u32 s38, 0xfef
	s_cbranch_scc0 .LBB0_32
	s_cmpk_gt_u32 s38, 0x13ef
	s_cbranch_scc0 .LBB0_29
	s_cmpk_gt_u32 s38, 0x15ef
	s_cbranch_scc0 .LBB0_26
	s_cmpk_gt_u32 s38, 0x1def
	s_cbranch_scc0 .LBB0_23
	s_load_dwordx2 s[16:17], s[6:7], 0x108
	s_add_i32 s10, s20, 0xfffc4200
	s_and_b32 s10, s10, 0x3e0
	s_and_b32 s8, s22, 0x1ffc0
	s_lshl_b32 s11, s10, 2
	s_waitcnt lgkmcnt(0)
	s_add_u32 s16, s16, s11
	s_addc_u32 s17, s17, 0
	v_lshlrev_b32_e32 v4, 2, v2
	v_lshl_add_u64 v[28:29], s[16:17], 0, v[4:5]
	v_or_b32_e32 v4, s8, v3
	v_lshlrev_b32_e32 v4, 12, v4
	v_lshl_add_u64 v[30:31], v[28:29], 0, v[4:5]
	v_or_b32_e32 v4, s8, v39
	v_lshlrev_b32_e32 v4, 12, v4
	v_lshl_add_u64 v[32:33], v[28:29], 0, v[4:5]
	v_or_b32_e32 v4, s8, v40
	v_lshlrev_b32_e32 v4, 12, v4
	v_lshl_add_u64 v[34:35], v[28:29], 0, v[4:5]
	v_or_b32_e32 v4, s8, v41
	v_lshlrev_b32_e32 v4, 12, v4
	v_lshl_add_u64 v[36:37], v[28:29], 0, v[4:5]
	v_or_b32_e32 v4, s8, v42
	v_lshlrev_b32_e32 v4, 12, v4
	v_lshl_add_u64 v[80:81], v[28:29], 0, v[4:5]
	v_or_b32_e32 v4, s8, v43
	v_lshlrev_b32_e32 v4, 12, v4
	v_lshl_add_u64 v[82:83], v[28:29], 0, v[4:5]
	v_or_b32_e32 v4, s8, v44
	v_lshlrev_b32_e32 v4, 12, v4
	v_lshl_add_u64 v[84:85], v[28:29], 0, v[4:5]
	v_or_b32_e32 v4, s8, v46
	v_lshlrev_b32_e32 v4, 12, v4
	v_lshl_add_u64 v[86:87], v[28:29], 0, v[4:5]
	v_or_b32_e32 v4, s8, v47
	v_lshlrev_b32_e32 v4, 12, v4
	global_load_dword v27, v[30:31], off nt
	global_load_dword v79, v[32:33], off nt
	global_load_dword v88, v[34:35], off nt
	global_load_dword v89, v[36:37], off nt
	global_load_dword v90, v[80:81], off nt
	global_load_dword v91, v[82:83], off nt
	global_load_dword v92, v[84:85], off nt
	global_load_dword v93, v[86:87], off nt
	v_lshl_add_u64 v[30:31], v[28:29], 0, v[4:5]
	v_or_b32_e32 v4, s8, v48
	v_lshlrev_b32_e32 v4, 12, v4
	v_lshl_add_u64 v[32:33], v[28:29], 0, v[4:5]
	v_or_b32_e32 v4, s8, v49
	v_lshlrev_b32_e32 v4, 12, v4
	v_lshl_add_u64 v[34:35], v[28:29], 0, v[4:5]
	v_or_b32_e32 v4, s8, v50
	v_lshlrev_b32_e32 v4, 12, v4
	v_lshl_add_u64 v[36:37], v[28:29], 0, v[4:5]
	v_or_b32_e32 v4, s8, v51
	v_lshlrev_b32_e32 v4, 12, v4
	v_lshl_add_u64 v[80:81], v[28:29], 0, v[4:5]
	v_or_b32_e32 v4, s8, v53
	v_lshlrev_b32_e32 v4, 12, v4
	v_lshl_add_u64 v[82:83], v[28:29], 0, v[4:5]
	v_or_b32_e32 v4, s8, v54
	v_lshlrev_b32_e32 v4, 12, v4
	v_lshl_add_u64 v[84:85], v[28:29], 0, v[4:5]
	v_or_b32_e32 v4, s8, v55
	v_lshlrev_b32_e32 v4, 12, v4
	v_lshl_add_u64 v[86:87], v[28:29], 0, v[4:5]
	v_or_b32_e32 v4, s8, v56
	v_lshlrev_b32_e32 v4, 12, v4
	global_load_dword v94, v[30:31], off nt
	global_load_dword v95, v[32:33], off nt
	global_load_dword v96, v[34:35], off nt
	global_load_dword v97, v[36:37], off nt
	global_load_dword v98, v[80:81], off nt
	global_load_dword v99, v[82:83], off nt
	global_load_dword v100, v[84:85], off nt
	global_load_dword v101, v[86:87], off nt
	v_lshl_add_u64 v[30:31], v[28:29], 0, v[4:5]
	v_or_b32_e32 v4, s8, v57
	v_lshlrev_b32_e32 v4, 12, v4
	v_lshl_add_u64 v[32:33], v[28:29], 0, v[4:5]
	v_or_b32_e32 v4, s8, v58
	v_lshlrev_b32_e32 v4, 12, v4
	v_lshl_add_u64 v[34:35], v[28:29], 0, v[4:5]
	v_or_b32_e32 v4, s8, v60
	v_lshlrev_b32_e32 v4, 12, v4
	v_lshl_add_u64 v[36:37], v[28:29], 0, v[4:5]
	v_or_b32_e32 v4, s8, v61
	v_lshlrev_b32_e32 v4, 12, v4
	v_lshl_add_u64 v[80:81], v[28:29], 0, v[4:5]
	v_or_b32_e32 v4, s8, v62
	v_lshlrev_b32_e32 v4, 12, v4
	v_lshl_add_u64 v[82:83], v[28:29], 0, v[4:5]
	v_or_b32_e32 v4, s8, v63
	v_lshlrev_b32_e32 v4, 12, v4
	v_lshl_add_u64 v[84:85], v[28:29], 0, v[4:5]
	v_or_b32_e32 v4, s8, v64
	v_lshlrev_b32_e32 v4, 12, v4
	v_lshl_add_u64 v[86:87], v[28:29], 0, v[4:5]
	v_or_b32_e32 v4, s8, v65
	v_lshlrev_b32_e32 v4, 12, v4
	global_load_dword v102, v[30:31], off nt
	global_load_dword v103, v[32:33], off nt
	global_load_dword v104, v[34:35], off nt
	global_load_dword v105, v[36:37], off nt
	global_load_dword v106, v[80:81], off nt
	global_load_dword v107, v[82:83], off nt
	global_load_dword v108, v[84:85], off nt
	global_load_dword v109, v[86:87], off nt
	v_lshl_add_u64 v[30:31], v[28:29], 0, v[4:5]
	v_or_b32_e32 v4, s8, v67
	v_lshlrev_b32_e32 v4, 12, v4
	v_lshl_add_u64 v[32:33], v[28:29], 0, v[4:5]
	v_or_b32_e32 v4, s8, v68
	v_lshlrev_b32_e32 v4, 12, v4
	v_lshl_add_u64 v[34:35], v[28:29], 0, v[4:5]
	v_or_b32_e32 v4, s8, v71
	v_lshlrev_b32_e32 v4, 12, v4
	v_lshl_add_u64 v[36:37], v[28:29], 0, v[4:5]
	v_or_b32_e32 v4, s8, v72
	v_lshlrev_b32_e32 v4, 12, v4
	v_lshl_add_u64 v[80:81], v[28:29], 0, v[4:5]
	v_or_b32_e32 v4, s8, v73
	v_lshlrev_b32_e32 v4, 12, v4
	v_lshl_add_u64 v[82:83], v[28:29], 0, v[4:5]
	v_or_b32_e32 v4, s8, v74
	v_lshlrev_b32_e32 v4, 12, v4
	v_lshl_add_u64 v[84:85], v[28:29], 0, v[4:5]
	v_or_b32_e32 v4, s8, v75
	v_lshlrev_b32_e32 v4, 12, v4
	v_lshl_add_u64 v[28:29], v[28:29], 0, v[4:5]
	global_load_dword v4, v[30:31], off nt
	global_load_dword v86, v[32:33], off nt
	global_load_dword v87, v[34:35], off nt
	global_load_dword v110, v[36:37], off nt
	global_load_dword v111, v[80:81], off nt
	global_load_dword v112, v[82:83], off nt
	global_load_dword v113, v[84:85], off nt
	global_load_dword v114, v[28:29], off nt
	v_add_u32_e32 v28, v7, v9
	s_waitcnt vmcnt(30)
	ds_write2_b32 v28, v27, v79 offset1:66
	s_waitcnt vmcnt(28)
	ds_write2_b32 v28, v88, v89 offset0:132 offset1:198
	v_add_u32_e32 v27, 0x400, v28
	s_waitcnt vmcnt(26)
	ds_write2_b32 v27, v90, v91 offset0:8 offset1:74
	v_add_u32_e32 v27, v7, v45
	s_waitcnt vmcnt(24)
; #define LAS __attribute__((address_space(3)))
; __device__ __forceinline__ void transpose_item(const float* W, int K, int N, bf16_t* WT, int mode, LAS float* scr, int item, int lane) {
;     ...
;     for (int i = 0; i < 32; ++i) { const int kk = 2 * i + (lane >> 5); scr[kk * 33 + (lane & 31)] = W[(size_t)(k0 + kk) * N + n0 + (lane & 31)]; }
;     asm volatile("s_waitcnt lgkmcnt(0)" ::: "memory");
;     const int c = lane & 7;
; #pragma unroll
;     for (int j = 0; j < 4; ++j) { const int n = (lane >> 3) + 8 * j; const LAS float* s = scr + (8 * c) * 33 + n;
;         u32x4 o; o.x = cvtpk(s[0 * 33], s[1 * 33]); o.y = cvtpk(s[2 * 33], s[3 * 33]); o.z = cvtpk(s[4 * 33], s[5 * 33]); o.w = cvtpk(s[6 * 33], s[7 * 33]);
;         *(u32x4*)(WT + (size_t)wrow_map(mode, n0 + n) * K + k0 + 8 * c) = o; }
;     asm volatile("s_waitcnt lgkmcnt(0)" ::: "memory");
; __device__ __forceinline__ void convert_weights(PPtr P, int li, LAS unsigned char* lds, int gw, int NGW, int wave, int lane) {
;     ...
;     for (int it = gw; it < NIT; it += NGW) {
;         int r = it;
;         if (r < I_IN) { transpose_item(P->in[5] + (size_t)li * 1024 * 3232, 1024, 3232, Wb + W_IN, 0, scr, r, lane); continue; } r -= I_IN;
;         if (r < I_GATE) { transpose_item(P->in[6] + (size_t)li * 1024 * 4096, 1024, 4096, Wb + W_GATE, 0, scr, r, lane); continue; } r -= I_GATE;
;         if (r < I_UQ) { transpose_item(P->in[16] + (size_t)li * 256 * 768, 256, 768, Wb + W_UQ, 1, scr, r, lane); continue; } r -= I_UQ;
;         if (r < I_UKV) { transpose_item(P->in[17] + (size_t)li * 128 * 1024, 128, 1024, Wb + W_UKV, 0, scr, r, lane); continue; } r -= I_UKV;
;         if (r < I_GLU) { transpose_item(P->in[26] + (size_t)li * 512 * 1024, 512, 1024, Wb + W_GLU, 2, scr, r, lane); continue; } r -= I_GLU;
;         if (r < 4 * I_BR) { const int b = r / I_BR; transpose_item(P->in[27 + b] + (size_t)li * 512 * 1024, 512, 1024, Wb + W_BR + (size_t)b * 524288, 0, scr, r % I_BR, lane); continue; } r -= 4 * I_BR;
;         if (r < I_OUT) { transpose_item(P->in[31] + (size_t)li * 1024 * 1024, 1024, 1024, Wb + W_OUT, 0, scr, r, lane); continue; } r -= I_OUT;
;         if (r < I_F1) { transpose_item(P->in[32] + (size_t)li * 1024 * 4096, 1024, 4096, Wb + W_F1, 0, scr, r, lane); continue; } r -= I_F1;
	ds_write2_b32 v27, v92, v93 offset1:66
	s_waitcnt vmcnt(22)
	ds_write2_b32 v27, v94, v95 offset0:132 offset1:198
	v_add_u32_e32 v27, 0x400, v27
	s_waitcnt vmcnt(20)
	ds_write2_b32 v27, v96, v97 offset0:8 offset1:74
	v_add_u32_e32 v27, v7, v52
	s_waitcnt vmcnt(18)
	ds_write2_b32 v27, v98, v99 offset1:66
	s_waitcnt vmcnt(16)
	ds_write2_b32 v27, v100, v101 offset0:132 offset1:198
	v_add_u32_e32 v27, 0x400, v27
	s_lshl_b32 s8, s8, 1
	v_lshl_add_u64 v[90:91], v[10:11], 0, s[8:9]
	s_waitcnt vmcnt(14)
	ds_write2_b32 v27, v102, v103 offset0:8 offset1:74
	v_add_u32_e32 v27, v7, v59
	s_waitcnt vmcnt(12)
	ds_write2_b32 v27, v104, v105 offset1:66
	s_waitcnt vmcnt(10)
	ds_write2_b32 v27, v106, v107 offset0:132 offset1:198
	v_add_u32_e32 v27, 0x400, v27
	s_waitcnt vmcnt(8)
	ds_write2_b32 v27, v108, v109 offset0:8 offset1:74
	v_add_u32_e32 v27, v7, v66
	s_waitcnt vmcnt(6)
	ds_write2_b32 v27, v4, v86 offset1:66
	s_waitcnt vmcnt(4)
	ds_write2_b32 v27, v87, v110 offset0:132 offset1:198
	v_add_u32_e32 v4, 0x400, v27
	s_waitcnt vmcnt(2)
	ds_write2_b32 v4, v111, v112 offset0:8 offset1:74
	s_waitcnt vmcnt(0)
	ds_write2_b32 v4, v113, v114 offset0:140 offset1:206
	s_waitcnt lgkmcnt(0)
	ds_read2_b32 v[32:33], v70 offset0:33 offset1:41
	ds_read2_b32 v[34:35], v70 offset1:8
	ds_read2_b32 v[36:37], v70 offset0:66 offset1:74
	ds_read2_b32 v[80:81], v70 offset0:99 offset1:107
	ds_read2_b32 v[82:83], v70 offset0:132 offset1:140
	ds_read2_b32 v[84:85], v70 offset0:165 offset1:173
	ds_read2_b32 v[86:87], v70 offset0:198 offset1:206
	ds_read2_b32 v[88:89], v70 offset0:231 offset1:239
	v_or_b32_e32 v4, s10, v69
	v_lshlrev_b32_e32 v4, 13, v4
	s_waitcnt lgkmcnt(6)
	v_cvt_pk_bf16_f32 v28, v34, v32
	s_waitcnt lgkmcnt(4)
	v_cvt_pk_bf16_f32 v29, v36, v80
	s_waitcnt lgkmcnt(2)
	v_cvt_pk_bf16_f32 v30, v82, v84
	s_waitcnt lgkmcnt(0)
	v_cvt_pk_bf16_f32 v31, v86, v88
	v_lshl_add_u64 v[92:93], v[90:91], 0, v[4:5]
	global_store_dwordx4 v[92:93], v[28:31], off
	v_or_b32_e32 v4, s10, v76
	v_lshlrev_b32_e32 v4, 13, v4
	v_cvt_pk_bf16_f32 v28, v35, v33
	v_cvt_pk_bf16_f32 v29, v37, v81
	v_cvt_pk_bf16_f32 v30, v83, v85
	v_cvt_pk_bf16_f32 v31, v87, v89
	ds_read2_b32 v[34:35], v70 offset0:49 offset1:57
	ds_read2_b32 v[36:37], v70 offset0:16 offset1:24
	ds_read2_b32 v[80:81], v70 offset0:82 offset1:90
	ds_read2_b32 v[82:83], v70 offset0:115 offset1:123
	ds_read2_b32 v[84:85], v70 offset0:148 offset1:156
	ds_read2_b32 v[86:87], v70 offset0:181 offset1:189
	ds_read2_b32 v[88:89], v70 offset0:214 offset1:222
	ds_read2_b32 v[92:93], v70 offset0:247 offset1:255
	v_lshl_add_u64 v[32:33], v[90:91], 0, v[4:5]
	v_or_b32_e32 v4, s10, v77
	v_lshlrev_b32_e32 v4, 13, v4
	global_store_dwordx4 v[32:33], v[28:31], off
	v_lshl_add_u64 v[32:33], v[90:91], 0, v[4:5]
	v_or_b32_e32 v4, s10, v78
	s_waitcnt lgkmcnt(6)
	v_cvt_pk_bf16_f32 v28, v36, v34
	s_waitcnt lgkmcnt(4)
	v_cvt_pk_bf16_f32 v29, v80, v82
	s_waitcnt lgkmcnt(2)
	v_cvt_pk_bf16_f32 v30, v84, v86
	s_waitcnt lgkmcnt(0)
	v_cvt_pk_bf16_f32 v31, v88, v92
	v_lshlrev_b32_e32 v4, 13, v4
	global_store_dwordx4 v[32:33], v[28:31], off
	v_lshl_add_u64 v[32:33], v[90:91], 0, v[4:5]
	s_mov_b64 s[10:11], 0
	v_cvt_pk_bf16_f32 v28, v37, v35
	v_cvt_pk_bf16_f32 v29, v81, v83
	v_cvt_pk_bf16_f32 v30, v85, v87
	v_cvt_pk_bf16_f32 v31, v89, v93
	global_store_dwordx4 v[32:33], v[28:31], off
	s_waitcnt lgkmcnt(0)
.LBB0_23:
	s_andn2_b64 vcc, exec, s[10:11]
	s_cbranch_vccnz .LBB0_25
	s_load_dwordx2 s[16:17], s[6:7], 0x100
	s_add_i32 s8, s38, 0xffffea10
	s_add_i32 s10, s20, 0xfffd4200
	s_lshr_b32 s8, s8, 1
	s_and_b32 s10, s10, 0xfe0
	s_and_b32 s8, s8, 0x7fc0
	s_lshl_b32 s11, s10, 2
	s_waitcnt lgkmcnt(0)
	s_add_u32 s16, s16, s11
	s_addc_u32 s17, s17, 0
	v_lshlrev_b32_e32 v4, 2, v2
	v_lshl_add_u64 v[28:29], s[16:17], 0, v[4:5]
	v_or_b32_e32 v4, s8, v3
	v_lshlrev_b32_e32 v4, 14, v4
	v_lshl_add_u64 v[30:31], v[28:29], 0, v[4:5]
	v_or_b32_e32 v4, s8, v39
	v_lshlrev_b32_e32 v4, 14, v4
	v_lshl_add_u64 v[32:33], v[28:29], 0, v[4:5]
	v_or_b32_e32 v4, s8, v40
	v_lshlrev_b32_e32 v4, 14, v4
	v_lshl_add_u64 v[34:35], v[28:29], 0, v[4:5]
	v_or_b32_e32 v4, s8, v41
	v_lshlrev_b32_e32 v4, 14, v4
	v_lshl_add_u64 v[36:37], v[28:29], 0, v[4:5]
	v_or_b32_e32 v4, s8, v42
	v_lshlrev_b32_e32 v4, 14, v4
	v_lshl_add_u64 v[80:81], v[28:29], 0, v[4:5]
	v_or_b32_e32 v4, s8, v43
	v_lshlrev_b32_e32 v4, 14, v4
	v_lshl_add_u64 v[82:83], v[28:29], 0, v[4:5]
	v_or_b32_e32 v4, s8, v44
	v_lshlrev_b32_e32 v4, 14, v4
	v_lshl_add_u64 v[84:85], v[28:29], 0, v[4:5]
	v_or_b32_e32 v4, s8, v46
	v_lshlrev_b32_e32 v4, 14, v4
	v_lshl_add_u64 v[86:87], v[28:29], 0, v[4:5]
	v_or_b32_e32 v4, s8, v47
	v_lshlrev_b32_e32 v4, 14, v4
	global_load_dword v27, v[30:31], off nt
	global_load_dword v79, v[32:33], off nt
	global_load_dword v88, v[34:35], off nt
	global_load_dword v89, v[36:37], off nt
	global_load_dword v90, v[80:81], off nt
	global_load_dword v91, v[82:83], off nt
	global_load_dword v92, v[84:85], off nt
	global_load_dword v93, v[86:87], off nt
	v_lshl_add_u64 v[30:31], v[28:29], 0, v[4:5]
	v_or_b32_e32 v4, s8, v48
	v_lshlrev_b32_e32 v4, 14, v4
	v_lshl_add_u64 v[32:33], v[28:29], 0, v[4:5]
	v_or_b32_e32 v4, s8, v49
	v_lshlrev_b32_e32 v4, 14, v4
	v_lshl_add_u64 v[34:35], v[28:29], 0, v[4:5]
	v_or_b32_e32 v4, s8, v50
	v_lshlrev_b32_e32 v4, 14, v4
	v_lshl_add_u64 v[36:37], v[28:29], 0, v[4:5]
	v_or_b32_e32 v4, s8, v51
	v_lshlrev_b32_e32 v4, 14, v4
	v_lshl_add_u64 v[80:81], v[28:29], 0, v[4:5]
	v_or_b32_e32 v4, s8, v53
	v_lshlrev_b32_e32 v4, 14, v4
	v_lshl_add_u64 v[82:83], v[28:29], 0, v[4:5]
	v_or_b32_e32 v4, s8, v54
	v_lshlrev_b32_e32 v4, 14, v4
	v_lshl_add_u64 v[84:85], v[28:29], 0, v[4:5]
	v_or_b32_e32 v4, s8, v55
; #define LAS __attribute__((address_space(3)))
; __device__ __forceinline__ unsigned cvtpk(float lo, float hi) { typedef __bf16 bf2 __attribute__((ext_vector_type(2))); f32x2 v = {lo, hi}; bf2 b = __builtin_convertvector(v, bf2); return __builtin_bit_cast(unsigned, b); }
; __device__ __forceinline__ void transpose_item(const float* W, int K, int N, bf16_t* WT, int mode, LAS float* scr, int item, int lane) {
;     ...
;     for (int i = 0; i < 32; ++i) { const int kk = 2 * i + (lane >> 5); scr[kk * 33 + (lane & 31)] = W[(size_t)(k0 + kk) * N + n0 + (lane & 31)]; }
;     asm volatile("s_waitcnt lgkmcnt(0)" ::: "memory");
;     const int c = lane & 7;
; #pragma unroll
;     for (int j = 0; j < 4; ++j) { const int n = (lane >> 3) + 8 * j; const LAS float* s = scr + (8 * c) * 33 + n;
;         u32x4 o; o.x = cvtpk(s[0 * 33], s[1 * 33]); o.y = cvtpk(s[2 * 33], s[3 * 33]); o.z = cvtpk(s[4 * 33], s[5 * 33]); o.w = cvtpk(s[6 * 33], s[7 * 33]);
;         *(u32x4*)(WT + (size_t)wrow_map(mode, n0 + n) * K + k0 + 8 * c) = o; }
;     asm volatile("s_waitcnt lgkmcnt(0)" ::: "memory");
	v_lshlrev_b32_e32 v4, 14, v4
	v_lshl_add_u64 v[86:87], v[28:29], 0, v[4:5]
	v_or_b32_e32 v4, s8, v56
	v_lshlrev_b32_e32 v4, 14, v4
	global_load_dword v94, v[30:31], off nt
	global_load_dword v95, v[32:33], off nt
	global_load_dword v96, v[34:35], off nt
	global_load_dword v97, v[36:37], off nt
	global_load_dword v98, v[80:81], off nt
	global_load_dword v99, v[82:83], off nt
	global_load_dword v100, v[84:85], off nt
	global_load_dword v101, v[86:87], off nt
	v_lshl_add_u64 v[30:31], v[28:29], 0, v[4:5]
	v_or_b32_e32 v4, s8, v57
	v_lshlrev_b32_e32 v4, 14, v4
	v_lshl_add_u64 v[32:33], v[28:29], 0, v[4:5]
	v_or_b32_e32 v4, s8, v58
	v_lshlrev_b32_e32 v4, 14, v4
	v_lshl_add_u64 v[34:35], v[28:29], 0, v[4:5]
	v_or_b32_e32 v4, s8, v60
	v_lshlrev_b32_e32 v4, 14, v4
	v_lshl_add_u64 v[36:37], v[28:29], 0, v[4:5]
	v_or_b32_e32 v4, s8, v61
	v_lshlrev_b32_e32 v4, 14, v4
	v_lshl_add_u64 v[80:81], v[28:29], 0, v[4:5]
	v_or_b32_e32 v4, s8, v62
	v_lshlrev_b32_e32 v4, 14, v4
	v_lshl_add_u64 v[82:83], v[28:29], 0, v[4:5]
	v_or_b32_e32 v4, s8, v63
	v_lshlrev_b32_e32 v4, 14, v4
	v_lshl_add_u64 v[84:85], v[28:29], 0, v[4:5]
	v_or_b32_e32 v4, s8, v64
	v_lshlrev_b32_e32 v4, 14, v4
	v_lshl_add_u64 v[86:87], v[28:29], 0, v[4:5]
	v_or_b32_e32 v4, s8, v65
	v_lshlrev_b32_e32 v4, 14, v4
	global_load_dword v102, v[30:31], off nt
	global_load_dword v103, v[32:33], off nt
	global_load_dword v104, v[34:35], off nt
	global_load_dword v105, v[36:37], off nt
	global_load_dword v106, v[80:81], off nt
	global_load_dword v107, v[82:83], off nt
	global_load_dword v108, v[84:85], off nt
	global_load_dword v109, v[86:87], off nt
	v_lshl_add_u64 v[30:31], v[28:29], 0, v[4:5]
	v_or_b32_e32 v4, s8, v67
	v_lshlrev_b32_e32 v4, 14, v4
	v_lshl_add_u64 v[32:33], v[28:29], 0, v[4:5]
	v_or_b32_e32 v4, s8, v68
	v_lshlrev_b32_e32 v4, 14, v4
	v_lshl_add_u64 v[34:35], v[28:29], 0, v[4:5]
	v_or_b32_e32 v4, s8, v71
	v_lshlrev_b32_e32 v4, 14, v4
	v_lshl_add_u64 v[36:37], v[28:29], 0, v[4:5]
	v_or_b32_e32 v4, s8, v72
	v_lshlrev_b32_e32 v4, 14, v4
	v_lshl_add_u64 v[80:81], v[28:29], 0, v[4:5]
	v_or_b32_e32 v4, s8, v73
	v_lshlrev_b32_e32 v4, 14, v4
	v_lshl_add_u64 v[82:83], v[28:29], 0, v[4:5]
	v_or_b32_e32 v4, s8, v74
	v_lshlrev_b32_e32 v4, 14, v4
	v_lshl_add_u64 v[84:85], v[28:29], 0, v[4:5]
	v_or_b32_e32 v4, s8, v75
	v_lshlrev_b32_e32 v4, 14, v4
	v_lshl_add_u64 v[28:29], v[28:29], 0, v[4:5]
	global_load_dword v4, v[30:31], off nt
	global_load_dword v86, v[32:33], off nt
	global_load_dword v87, v[34:35], off nt
	global_load_dword v110, v[36:37], off nt
	global_load_dword v111, v[80:81], off nt
	global_load_dword v112, v[82:83], off nt
	global_load_dword v113, v[84:85], off nt
	global_load_dword v114, v[28:29], off nt
	v_add_u32_e32 v28, v7, v9
	s_waitcnt vmcnt(30)
	ds_write2_b32 v28, v27, v79 offset1:66
	s_waitcnt vmcnt(28)
	ds_write2_b32 v28, v88, v89 offset0:132 offset1:198
	v_add_u32_e32 v27, 0x400, v28
	s_waitcnt vmcnt(26)
	ds_write2_b32 v27, v90, v91 offset0:8 offset1:74
	v_add_u32_e32 v27, v7, v45
	s_waitcnt vmcnt(24)
	ds_write2_b32 v27, v92, v93 offset1:66
	s_waitcnt vmcnt(22)
	ds_write2_b32 v27, v94, v95 offset0:132 offset1:198
	v_add_u32_e32 v27, 0x400, v27
	s_waitcnt vmcnt(20)
	ds_write2_b32 v27, v96, v97 offset0:8 offset1:74
	v_add_u32_e32 v27, v7, v52
	s_waitcnt vmcnt(18)
	ds_write2_b32 v27, v98, v99 offset1:66
	s_waitcnt vmcnt(16)
	ds_write2_b32 v27, v100, v101 offset0:132 offset1:198
	v_add_u32_e32 v27, 0x400, v27
	s_lshl_b32 s8, s8, 1
	v_lshl_add_u64 v[90:91], v[12:13], 0, s[8:9]
	s_waitcnt vmcnt(14)
	ds_write2_b32 v27, v102, v103 offset0:8 offset1:74
	v_add_u32_e32 v27, v7, v59
	s_waitcnt vmcnt(12)
	ds_write2_b32 v27, v104, v105 offset1:66
	s_waitcnt vmcnt(10)
	ds_write2_b32 v27, v106, v107 offset0:132 offset1:198
	v_add_u32_e32 v27, 0x400, v27
	s_waitcnt vmcnt(8)
	ds_write2_b32 v27, v108, v109 offset0:8 offset1:74
	v_add_u32_e32 v27, v7, v66
	s_waitcnt vmcnt(6)
	ds_write2_b32 v27, v4, v86 offset1:66
	s_waitcnt vmcnt(4)
	ds_write2_b32 v27, v87, v110 offset0:132 offset1:198
	v_add_u32_e32 v4, 0x400, v27
	s_waitcnt vmcnt(2)
	ds_write2_b32 v4, v111, v112 offset0:8 offset1:74
	s_waitcnt vmcnt(0)
	ds_write2_b32 v4, v113, v114 offset0:140 offset1:206
	s_waitcnt lgkmcnt(0)
	ds_read2_b32 v[32:33], v70 offset0:33 offset1:41
	ds_read2_b32 v[34:35], v70 offset1:8
	ds_read2_b32 v[36:37], v70 offset0:66 offset1:74
	ds_read2_b32 v[80:81], v70 offset0:99 offset1:107
	ds_read2_b32 v[82:83], v70 offset0:132 offset1:140
	ds_read2_b32 v[84:85], v70 offset0:165 offset1:173
	ds_read2_b32 v[86:87], v70 offset0:198 offset1:206
	ds_read2_b32 v[88:89], v70 offset0:231 offset1:239
	v_or_b32_e32 v4, s10, v69
	v_lshlrev_b32_e32 v4, 11, v4
	s_waitcnt lgkmcnt(6)
	v_cvt_pk_bf16_f32 v28, v34, v32
	s_waitcnt lgkmcnt(4)
	v_cvt_pk_bf16_f32 v29, v36, v80
	s_waitcnt lgkmcnt(2)
	v_cvt_pk_bf16_f32 v30, v82, v84
	s_waitcnt lgkmcnt(0)
	v_cvt_pk_bf16_f32 v31, v86, v88
	v_lshl_add_u64 v[92:93], v[90:91], 0, v[4:5]
	global_store_dwordx4 v[92:93], v[28:31], off
	v_or_b32_e32 v4, s10, v76
	v_lshlrev_b32_e32 v4, 11, v4
	v_cvt_pk_bf16_f32 v28, v35, v33
	v_cvt_pk_bf16_f32 v29, v37, v81
	v_cvt_pk_bf16_f32 v30, v83, v85
	v_cvt_pk_bf16_f32 v31, v87, v89
	ds_read2_b32 v[34:35], v70 offset0:49 offset1:57
	ds_read2_b32 v[36:37], v70 offset0:16 offset1:24
	ds_read2_b32 v[80:81], v70 offset0:82 offset1:90
	ds_read2_b32 v[82:83], v70 offset0:115 offset1:123
	ds_read2_b32 v[84:85], v70 offset0:148 offset1:156
	ds_read2_b32 v[86:87], v70 offset0:181 offset1:189
	ds_read2_b32 v[88:89], v70 offset0:214 offset1:222
	ds_read2_b32 v[92:93], v70 offset0:247 offset1:255
	v_lshl_add_u64 v[32:33], v[90:91], 0, v[4:5]
	v_or_b32_e32 v4, s10, v77
	v_lshlrev_b32_e32 v4, 11, v4
	global_store_dwordx4 v[32:33], v[28:31], off
	v_lshl_add_u64 v[32:33], v[90:91], 0, v[4:5]
	v_or_b32_e32 v4, s10, v78
	s_waitcnt lgkmcnt(6)
	v_cvt_pk_bf16_f32 v28, v36, v34
	s_waitcnt lgkmcnt(4)
	v_cvt_pk_bf16_f32 v29, v80, v82
	s_waitcnt lgkmcnt(2)
	v_cvt_pk_bf16_f32 v30, v84, v86
	s_waitcnt lgkmcnt(0)
	v_cvt_pk_bf16_f32 v31, v88, v92
	v_lshlrev_b32_e32 v4, 11, v4
	global_store_dwordx4 v[32:33], v[28:31], off
	v_lshl_add_u64 v[32:33], v[90:91], 0, v[4:5]
	s_nop 0
	v_cvt_pk_bf16_f32 v28, v37, v35
	v_cvt_pk_bf16_f32 v29, v81, v83
	v_cvt_pk_bf16_f32 v30, v85, v87
	v_cvt_pk_bf16_f32 v31, v89, v93
	global_store_dwordx4 v[32:33], v[28:31], off
	s_waitcnt lgkmcnt(0)

; __device__ __forceinline__ void transpose_item(const float* W, int K, int N, bf16_t* WT, int mode, LAS float* scr, int item, int lane) {
;     ...
;     for (int i = 0; i < 32; ++i) { const int kk = 2 * i + (lane >> 5); scr[kk * 33 + (lane & 31)] = W[(size_t)(k0 + kk) * N + n0 + (lane & 31)]; }
; __device__ __forceinline__ void convert_weights(PPtr P, int li, LAS unsigned char* lds, int gw, int NGW, int wave, int lane) {
;     ...
;         if (r < I_OUT) { transpose_item(P->in[31] + (size_t)li * 1024 * 1024, 1024, 1024, Wb + W_OUT, 0, scr, r, lane); continue; } r -= I_OUT;
.LBB0_26:
	s_andn2_b64 vcc, exec, s[10:11]
	s_cbranch_vccnz .LBB0_28
	s_load_dwordx2 s[16:17], s[6:7], 0xf8
	s_add_i32 s10, s20, 0xfffd8200
	s_add_i32 s8, s22, 0x1400
	s_and_b32 s10, s10, 0x3e0
	s_and_b32 s8, s8, 0x1ffc0
	s_lshl_b32 s11, s10, 2
	s_waitcnt lgkmcnt(0)
	s_add_u32 s16, s16, s11
	s_addc_u32 s17, s17, 0
	v_lshlrev_b32_e32 v4, 2, v2
	v_lshl_add_u64 v[28:29], s[16:17], 0, v[4:5]
	v_or_b32_e32 v4, s8, v3
	v_lshlrev_b32_e32 v4, 12, v4
	v_lshl_add_u64 v[30:31], v[28:29], 0, v[4:5]
	v_or_b32_e32 v4, s8, v39
	v_lshlrev_b32_e32 v4, 12, v4
	v_lshl_add_u64 v[32:33], v[28:29], 0, v[4:5]
	v_or_b32_e32 v4, s8, v40
	v_lshlrev_b32_e32 v4, 12, v4
	v_lshl_add_u64 v[34:35], v[28:29], 0, v[4:5]
	v_or_b32_e32 v4, s8, v41
	v_lshlrev_b32_e32 v4, 12, v4
	v_lshl_add_u64 v[36:37], v[28:29], 0, v[4:5]
	v_or_b32_e32 v4, s8, v42
	v_lshlrev_b32_e32 v4, 12, v4
	v_lshl_add_u64 v[80:81], v[28:29], 0, v[4:5]
	v_or_b32_e32 v4, s8, v43
	v_lshlrev_b32_e32 v4, 12, v4
	v_lshl_add_u64 v[82:83], v[28:29], 0, v[4:5]
	v_or_b32_e32 v4, s8, v44
	v_lshlrev_b32_e32 v4, 12, v4
	v_lshl_add_u64 v[84:85], v[28:29], 0, v[4:5]
	v_or_b32_e32 v4, s8, v46
	v_lshlrev_b32_e32 v4, 12, v4
	v_lshl_add_u64 v[86:87], v[28:29], 0, v[4:5]
	v_or_b32_e32 v4, s8, v47
	v_lshlrev_b32_e32 v4, 12, v4
	global_load_dword v27, v[30:31], off nt
	global_load_dword v79, v[32:33], off nt
	global_load_dword v88, v[34:35], off nt
	global_load_dword v89, v[36:37], off nt
	global_load_dword v90, v[80:81], off nt
	global_load_dword v91, v[82:83], off nt
	global_load_dword v92, v[84:85], off nt
	global_load_dword v93, v[86:87], off nt
	v_lshl_add_u64 v[30:31], v[28:29], 0, v[4:5]
	v_or_b32_e32 v4, s8, v48
	v_lshlrev_b32_e32 v4, 12, v4
	v_lshl_add_u64 v[32:33], v[28:29], 0, v[4:5]
	v_or_b32_e32 v4, s8, v49
	v_lshlrev_b32_e32 v4, 12, v4
	v_lshl_add_u64 v[34:35], v[28:29], 0, v[4:5]
	v_or_b32_e32 v4, s8, v50
	v_lshlrev_b32_e32 v4, 12, v4
	v_lshl_add_u64 v[36:37], v[28:29], 0, v[4:5]
	v_or_b32_e32 v4, s8, v51
	v_lshlrev_b32_e32 v4, 12, v4
	v_lshl_add_u64 v[80:81], v[28:29], 0, v[4:5]
	v_or_b32_e32 v4, s8, v53
	v_lshlrev_b32_e32 v4, 12, v4
	v_lshl_add_u64 v[82:83], v[28:29], 0, v[4:5]
	v_or_b32_e32 v4, s8, v54
	v_lshlrev_b32_e32 v4, 12, v4
	v_lshl_add_u64 v[84:85], v[28:29], 0, v[4:5]
	v_or_b32_e32 v4, s8, v55
	v_lshlrev_b32_e32 v4, 12, v4
	v_lshl_add_u64 v[86:87], v[28:29], 0, v[4:5]
	v_or_b32_e32 v4, s8, v56
	v_lshlrev_b32_e32 v4, 12, v4
	global_load_dword v94, v[30:31], off nt
	global_load_dword v95, v[32:33], off nt
	global_load_dword v96, v[34:35], off nt
	global_load_dword v97, v[36:37], off nt
	global_load_dword v98, v[80:81], off nt
	global_load_dword v99, v[82:83], off nt
	global_load_dword v100, v[84:85], off nt
	global_load_dword v101, v[86:87], off nt
	v_lshl_add_u64 v[30:31], v[28:29], 0, v[4:5]
	v_or_b32_e32 v4, s8, v57
	v_lshlrev_b32_e32 v4, 12, v4
	v_lshl_add_u64 v[32:33], v[28:29], 0, v[4:5]
	v_or_b32_e32 v4, s8, v58
	v_lshlrev_b32_e32 v4, 12, v4
	v_lshl_add_u64 v[34:35], v[28:29], 0, v[4:5]
	v_or_b32_e32 v4, s8, v60
	v_lshlrev_b32_e32 v4, 12, v4
	v_lshl_add_u64 v[36:37], v[28:29], 0, v[4:5]
	v_or_b32_e32 v4, s8, v61
	v_lshlrev_b32_e32 v4, 12, v4
	v_lshl_add_u64 v[80:81], v[28:29], 0, v[4:5]
	v_or_b32_e32 v4, s8, v62
	v_lshlrev_b32_e32 v4, 12, v4
	v_lshl_add_u64 v[82:83], v[28:29], 0, v[4:5]
	v_or_b32_e32 v4, s8, v63
	v_lshlrev_b32_e32 v4, 12, v4
	v_lshl_add_u64 v[84:85], v[28:29], 0, v[4:5]
	v_or_b32_e32 v4, s8, v64
	v_lshlrev_b32_e32 v4, 12, v4
	v_lshl_add_u64 v[86:87], v[28:29], 0, v[4:5]
	v_or_b32_e32 v4, s8, v65
	v_lshlrev_b32_e32 v4, 12, v4
	global_load_dword v102, v[30:31], off nt
	global_load_dword v103, v[32:33], off nt
	global_load_dword v104, v[34:35], off nt
	global_load_dword v105, v[36:37], off nt
	global_load_dword v106, v[80:81], off nt
	global_load_dword v107, v[82:83], off nt
	global_load_dword v108, v[84:85], off nt
	global_load_dword v109, v[86:87], off nt
	v_lshl_add_u64 v[30:31], v[28:29], 0, v[4:5]
	v_or_b32_e32 v4, s8, v67
	v_lshlrev_b32_e32 v4, 12, v4
	v_lshl_add_u64 v[32:33], v[28:29], 0, v[4:5]
	v_or_b32_e32 v4, s8, v68
	v_lshlrev_b32_e32 v4, 12, v4
	v_lshl_add_u64 v[34:35], v[28:29], 0, v[4:5]
	v_or_b32_e32 v4, s8, v71
	v_lshlrev_b32_e32 v4, 12, v4
	v_lshl_add_u64 v[36:37], v[28:29], 0, v[4:5]
	v_or_b32_e32 v4, s8, v72
	v_lshlrev_b32_e32 v4, 12, v4
	v_lshl_add_u64 v[80:81], v[28:29], 0, v[4:5]
	v_or_b32_e32 v4, s8, v73
	v_lshlrev_b32_e32 v4, 12, v4
	v_lshl_add_u64 v[82:83], v[28:29], 0, v[4:5]
	v_or_b32_e32 v4, s8, v74
	v_lshlrev_b32_e32 v4, 12, v4
	v_lshl_add_u64 v[84:85], v[28:29], 0, v[4:5]
	v_or_b32_e32 v4, s8, v75
	v_lshlrev_b32_e32 v4, 12, v4
	v_lshl_add_u64 v[28:29], v[28:29], 0, v[4:5]
	global_load_dword v4, v[30:31], off nt
	global_load_dword v86, v[32:33], off nt
	global_load_dword v87, v[34:35], off nt
	global_load_dword v110, v[36:37], off nt
	global_load_dword v111, v[80:81], off nt
	global_load_dword v112, v[82:83], off nt
	global_load_dword v113, v[84:85], off nt
	global_load_dword v114, v[28:29], off nt
	v_add_u32_e32 v28, v7, v9
	s_waitcnt vmcnt(30)
; #define LAS __attribute__((address_space(3)))
; __device__ __forceinline__ unsigned cvtpk(float lo, float hi) { typedef __bf16 bf2 __attribute__((ext_vector_type(2))); f32x2 v = {lo, hi}; bf2 b = __builtin_convertvector(v, bf2); return __builtin_bit_cast(unsigned, b); }
; __device__ __forceinline__ void transpose_item(const float* W, int K, int N, bf16_t* WT, int mode, LAS float* scr, int item, int lane) {
;     ...
;     for (int i = 0; i < 32; ++i) { const int kk = 2 * i + (lane >> 5); scr[kk * 33 + (lane & 31)] = W[(size_t)(k0 + kk) * N + n0 + (lane & 31)]; }
;     asm volatile("s_waitcnt lgkmcnt(0)" ::: "memory");
;     const int c = lane & 7;
; #pragma unroll
;     for (int j = 0; j < 4; ++j) { const int n = (lane >> 3) + 8 * j; const LAS float* s = scr + (8 * c) * 33 + n;
;         u32x4 o; o.x = cvtpk(s[0 * 33], s[1 * 33]); o.y = cvtpk(s[2 * 33], s[3 * 33]); o.z = cvtpk(s[4 * 33], s[5 * 33]); o.w = cvtpk(s[6 * 33], s[7 * 33]);
;         *(u32x4*)(WT + (size_t)wrow_map(mode, n0 + n) * K + k0 + 8 * c) = o; }
;     asm volatile("s_waitcnt lgkmcnt(0)" ::: "memory");
	ds_write2_b32 v28, v27, v79 offset1:66
	s_waitcnt vmcnt(28)
	ds_write2_b32 v28, v88, v89 offset0:132 offset1:198
	v_add_u32_e32 v27, 0x400, v28
	s_waitcnt vmcnt(26)
	ds_write2_b32 v27, v90, v91 offset0:8 offset1:74
	v_add_u32_e32 v27, v7, v45
	s_waitcnt vmcnt(24)
	ds_write2_b32 v27, v92, v93 offset1:66
	s_waitcnt vmcnt(22)
	ds_write2_b32 v27, v94, v95 offset0:132 offset1:198
	v_add_u32_e32 v27, 0x400, v27
	s_waitcnt vmcnt(20)
	ds_write2_b32 v27, v96, v97 offset0:8 offset1:74
	v_add_u32_e32 v27, v7, v52
	s_waitcnt vmcnt(18)
	ds_write2_b32 v27, v98, v99 offset1:66
	s_waitcnt vmcnt(16)
	ds_write2_b32 v27, v100, v101 offset0:132 offset1:198
	v_add_u32_e32 v27, 0x400, v27
	s_lshl_b32 s8, s8, 1
	v_lshl_add_u64 v[90:91], v[14:15], 0, s[8:9]
	s_waitcnt vmcnt(14)
	ds_write2_b32 v27, v102, v103 offset0:8 offset1:74
	v_add_u32_e32 v27, v7, v59
	s_waitcnt vmcnt(12)
	ds_write2_b32 v27, v104, v105 offset1:66
	s_waitcnt vmcnt(10)
	ds_write2_b32 v27, v106, v107 offset0:132 offset1:198
	v_add_u32_e32 v27, 0x400, v27
	s_waitcnt vmcnt(8)
	ds_write2_b32 v27, v108, v109 offset0:8 offset1:74
	v_add_u32_e32 v27, v7, v66
	s_waitcnt vmcnt(6)
	ds_write2_b32 v27, v4, v86 offset1:66
	s_waitcnt vmcnt(4)
	ds_write2_b32 v27, v87, v110 offset0:132 offset1:198
	v_add_u32_e32 v4, 0x400, v27
	s_waitcnt vmcnt(2)
	ds_write2_b32 v4, v111, v112 offset0:8 offset1:74
	s_waitcnt vmcnt(0)
	ds_write2_b32 v4, v113, v114 offset0:140 offset1:206
	s_waitcnt lgkmcnt(0)
	ds_read2_b32 v[32:33], v70 offset0:33 offset1:41
	ds_read2_b32 v[34:35], v70 offset1:8
	ds_read2_b32 v[36:37], v70 offset0:66 offset1:74
	ds_read2_b32 v[80:81], v70 offset0:99 offset1:107
	ds_read2_b32 v[82:83], v70 offset0:132 offset1:140
	ds_read2_b32 v[84:85], v70 offset0:165 offset1:173
	ds_read2_b32 v[86:87], v70 offset0:198 offset1:206
	ds_read2_b32 v[88:89], v70 offset0:231 offset1:239
	v_or_b32_e32 v4, s10, v69
	v_lshlrev_b32_e32 v4, 11, v4
	s_waitcnt lgkmcnt(6)
	v_cvt_pk_bf16_f32 v28, v34, v32
	s_waitcnt lgkmcnt(4)
	v_cvt_pk_bf16_f32 v29, v36, v80
	s_waitcnt lgkmcnt(2)
	v_cvt_pk_bf16_f32 v30, v82, v84
	s_waitcnt lgkmcnt(0)
	v_cvt_pk_bf16_f32 v31, v86, v88
	v_lshl_add_u64 v[92:93], v[90:91], 0, v[4:5]
	global_store_dwordx4 v[92:93], v[28:31], off
	v_or_b32_e32 v4, s10, v76
	v_lshlrev_b32_e32 v4, 11, v4
	v_cvt_pk_bf16_f32 v28, v35, v33
	v_cvt_pk_bf16_f32 v29, v37, v81
	v_cvt_pk_bf16_f32 v30, v83, v85
	v_cvt_pk_bf16_f32 v31, v87, v89
	ds_read2_b32 v[34:35], v70 offset0:49 offset1:57
	ds_read2_b32 v[36:37], v70 offset0:16 offset1:24
	ds_read2_b32 v[80:81], v70 offset0:82 offset1:90
	ds_read2_b32 v[82:83], v70 offset0:115 offset1:123
	ds_read2_b32 v[84:85], v70 offset0:148 offset1:156
	ds_read2_b32 v[86:87], v70 offset0:181 offset1:189
	ds_read2_b32 v[88:89], v70 offset0:214 offset1:222
	ds_read2_b32 v[92:93], v70 offset0:247 offset1:255
	v_lshl_add_u64 v[32:33], v[90:91], 0, v[4:5]
	v_or_b32_e32 v4, s10, v77
	v_lshlrev_b32_e32 v4, 11, v4
	global_store_dwordx4 v[32:33], v[28:31], off
	v_lshl_add_u64 v[32:33], v[90:91], 0, v[4:5]
	v_or_b32_e32 v4, s10, v78
	s_waitcnt lgkmcnt(6)
	v_cvt_pk_bf16_f32 v28, v36, v34
	s_waitcnt lgkmcnt(4)
	v_cvt_pk_bf16_f32 v29, v80, v82
	s_waitcnt lgkmcnt(2)
	v_cvt_pk_bf16_f32 v30, v84, v86
	s_waitcnt lgkmcnt(0)
	v_cvt_pk_bf16_f32 v31, v88, v92
	v_lshlrev_b32_e32 v4, 11, v4
	global_store_dwordx4 v[32:33], v[28:31], off
	v_lshl_add_u64 v[32:33], v[90:91], 0, v[4:5]
	s_nop 0
	v_cvt_pk_bf16_f32 v28, v37, v35
	v_cvt_pk_bf16_f32 v29, v81, v83
	v_cvt_pk_bf16_f32 v30, v85, v87
	v_cvt_pk_bf16_f32 v31, v89, v93
	global_store_dwordx4 v[32:33], v[28:31], off
	s_waitcnt lgkmcnt(0)

; #define LAS __attribute__((address_space(3)))
; __device__ __forceinline__ void transpose_item(const float* W, int K, int N, bf16_t* WT, int mode, LAS float* scr, int item, int lane) {
;     const int nblk = N / 32, kb = item / nblk, nb = item % nblk, k0 = 64 * kb, n0 = 32 * nb;
; #pragma unroll
;     for (int i = 0; i < 32; ++i) { const int kk = 2 * i + (lane >> 5); scr[kk * 33 + (lane & 31)] = W[(size_t)(k0 + kk) * N + n0 + (lane & 31)]; }
; __device__ __forceinline__ void convert_weights(PPtr P, int li, LAS unsigned char* lds, int gw, int NGW, int wave, int lane) {
;     ...
;         if (r < 4 * I_BR) { const int b = r / I_BR; transpose_item(P->in[27 + b] + (size_t)li * 512 * 1024, 512, 1024, Wb + W_BR + (size_t)b * 524288, 0, scr, r % I_BR, lane); continue; } r -= 4 * I_BR;
.LBB0_29:
	s_andn2_b64 vcc, exec, s[10:11]
	s_cbranch_vccnz .LBB0_31
	s_add_i32 s8, s38, 0xfffff010
	s_lshr_b32 s8, s8, 8
	s_lshl_b32 s10, s8, 3
	s_load_dwordx2 s[40:41], s[6:7], s10 offset:0xd8
	s_lshl_b64 s[10:11], s[8:9], 20
	s_add_u32 s10, s18, s10
	s_addc_u32 s11, s19, s11
	s_add_i32 s8, s22, 0x1c00
	s_and_b32 s16, s8, 0x1c0
	s_add_i32 s8, s20, 0xfffe0200
	s_and_b32 s8, s8, 0x3e0
	s_lshl_b32 s17, s8, 2
	s_waitcnt lgkmcnt(0)
	s_add_u32 s40, s40, s17
	s_addc_u32 s41, s41, 0
	v_lshlrev_b32_e32 v4, 2, v2
	v_lshl_add_u64 v[28:29], s[40:41], 0, v[4:5]
	v_or_b32_e32 v4, s16, v3
	v_lshlrev_b32_e32 v4, 12, v4
	v_lshl_add_u64 v[30:31], v[28:29], 0, v[4:5]
	v_or_b32_e32 v4, s16, v39
	v_lshlrev_b32_e32 v4, 12, v4
	v_lshl_add_u64 v[32:33], v[28:29], 0, v[4:5]
	v_or_b32_e32 v4, s16, v40
	v_lshlrev_b32_e32 v4, 12, v4
	v_lshl_add_u64 v[34:35], v[28:29], 0, v[4:5]
	v_or_b32_e32 v4, s16, v41
	v_lshlrev_b32_e32 v4, 12, v4
	v_lshl_add_u64 v[36:37], v[28:29], 0, v[4:5]
	v_or_b32_e32 v4, s16, v42
	v_lshlrev_b32_e32 v4, 12, v4
	v_lshl_add_u64 v[80:81], v[28:29], 0, v[4:5]
	v_or_b32_e32 v4, s16, v43
	v_lshlrev_b32_e32 v4, 12, v4
	v_lshl_add_u64 v[82:83], v[28:29], 0, v[4:5]
	v_or_b32_e32 v4, s16, v44
	v_lshlrev_b32_e32 v4, 12, v4
	v_lshl_add_u64 v[84:85], v[28:29], 0, v[4:5]
	v_or_b32_e32 v4, s16, v46
	v_lshlrev_b32_e32 v4, 12, v4
	v_lshl_add_u64 v[86:87], v[28:29], 0, v[4:5]
	v_or_b32_e32 v4, s16, v47
	v_lshlrev_b32_e32 v4, 12, v4
	global_load_dword v27, v[30:31], off nt
	global_load_dword v79, v[32:33], off nt
	global_load_dword v88, v[34:35], off nt
	global_load_dword v89, v[36:37], off nt
	global_load_dword v90, v[80:81], off nt
	global_load_dword v91, v[82:83], off nt
	global_load_dword v92, v[84:85], off nt
	global_load_dword v93, v[86:87], off nt
	v_lshl_add_u64 v[30:31], v[28:29], 0, v[4:5]
	v_or_b32_e32 v4, s16, v48
	v_lshlrev_b32_e32 v4, 12, v4
	v_lshl_add_u64 v[32:33], v[28:29], 0, v[4:5]
	v_or_b32_e32 v4, s16, v49
	v_lshlrev_b32_e32 v4, 12, v4
	v_lshl_add_u64 v[34:35], v[28:29], 0, v[4:5]
	v_or_b32_e32 v4, s16, v50
	v_lshlrev_b32_e32 v4, 12, v4
	v_lshl_add_u64 v[36:37], v[28:29], 0, v[4:5]
	v_or_b32_e32 v4, s16, v51
	v_lshlrev_b32_e32 v4, 12, v4
	v_lshl_add_u64 v[80:81], v[28:29], 0, v[4:5]
	v_or_b32_e32 v4, s16, v53
	v_lshlrev_b32_e32 v4, 12, v4
	v_lshl_add_u64 v[82:83], v[28:29], 0, v[4:5]
	v_or_b32_e32 v4, s16, v54
	v_lshlrev_b32_e32 v4, 12, v4
	v_lshl_add_u64 v[84:85], v[28:29], 0, v[4:5]
	v_or_b32_e32 v4, s16, v55
	v_lshlrev_b32_e32 v4, 12, v4
	v_lshl_add_u64 v[86:87], v[28:29], 0, v[4:5]
	v_or_b32_e32 v4, s16, v56
	v_lshlrev_b32_e32 v4, 12, v4
	global_load_dword v94, v[30:31], off nt
	global_load_dword v95, v[32:33], off nt
	global_load_dword v96, v[34:35], off nt
	global_load_dword v97, v[36:37], off nt
	global_load_dword v98, v[80:81], off nt
	global_load_dword v99, v[82:83], off nt
	global_load_dword v100, v[84:85], off nt
	global_load_dword v101, v[86:87], off nt
	v_lshl_add_u64 v[30:31], v[28:29], 0, v[4:5]
	v_or_b32_e32 v4, s16, v57
	v_lshlrev_b32_e32 v4, 12, v4
	v_lshl_add_u64 v[32:33], v[28:29], 0, v[4:5]
	v_or_b32_e32 v4, s16, v58
	v_lshlrev_b32_e32 v4, 12, v4
	v_lshl_add_u64 v[34:35], v[28:29], 0, v[4:5]
	v_or_b32_e32 v4, s16, v60
	v_lshlrev_b32_e32 v4, 12, v4
	v_lshl_add_u64 v[36:37], v[28:29], 0, v[4:5]
	v_or_b32_e32 v4, s16, v61
	v_lshlrev_b32_e32 v4, 12, v4
	v_lshl_add_u64 v[80:81], v[28:29], 0, v[4:5]
	v_or_b32_e32 v4, s16, v62
	v_lshlrev_b32_e32 v4, 12, v4
	v_lshl_add_u64 v[82:83], v[28:29], 0, v[4:5]
	v_or_b32_e32 v4, s16, v63
	v_lshlrev_b32_e32 v4, 12, v4
	v_lshl_add_u64 v[84:85], v[28:29], 0, v[4:5]
	v_or_b32_e32 v4, s16, v64
	v_lshlrev_b32_e32 v4, 12, v4
	v_lshl_add_u64 v[86:87], v[28:29], 0, v[4:5]
	v_or_b32_e32 v4, s16, v65
	v_lshlrev_b32_e32 v4, 12, v4
	global_load_dword v102, v[30:31], off nt
	global_load_dword v103, v[32:33], off nt
	global_load_dword v104, v[34:35], off nt
	global_load_dword v105, v[36:37], off nt
	global_load_dword v106, v[80:81], off nt
	global_load_dword v107, v[82:83], off nt
	global_load_dword v108, v[84:85], off nt
	global_load_dword v109, v[86:87], off nt
	v_lshl_add_u64 v[30:31], v[28:29], 0, v[4:5]
	v_or_b32_e32 v4, s16, v67
	v_lshlrev_b32_e32 v4, 12, v4
	v_lshl_add_u64 v[32:33], v[28:29], 0, v[4:5]
	v_or_b32_e32 v4, s16, v68
	v_lshlrev_b32_e32 v4, 12, v4
	v_lshl_add_u64 v[34:35], v[28:29], 0, v[4:5]
	v_or_b32_e32 v4, s16, v71
	v_lshlrev_b32_e32 v4, 12, v4
	v_lshl_add_u64 v[36:37], v[28:29], 0, v[4:5]
	v_or_b32_e32 v4, s16, v72
	v_lshlrev_b32_e32 v4, 12, v4
	v_lshl_add_u64 v[80:81], v[28:29], 0, v[4:5]
	v_or_b32_e32 v4, s16, v73
	v_lshlrev_b32_e32 v4, 12, v4
	v_lshl_add_u64 v[82:83], v[28:29], 0, v[4:5]
	v_or_b32_e32 v4, s16, v74
	v_lshlrev_b32_e32 v4, 12, v4
	v_lshl_add_u64 v[84:85], v[28:29], 0, v[4:5]
	v_or_b32_e32 v4, s16, v75
	v_lshlrev_b32_e32 v4, 12, v4
	v_lshl_add_u64 v[28:29], v[28:29], 0, v[4:5]
	global_load_dword v4, v[30:31], off nt
	global_load_dword v86, v[32:33], off nt
	global_load_dword v87, v[34:35], off nt
	global_load_dword v110, v[36:37], off nt
	global_load_dword v111, v[80:81], off nt
	global_load_dword v112, v[82:83], off nt
	global_load_dword v113, v[84:85], off nt
	global_load_dword v114, v[28:29], off nt
	v_add_u32_e32 v28, v7, v9
	s_waitcnt vmcnt(30)
; #define LAS __attribute__((address_space(3)))
; __device__ __forceinline__ unsigned cvtpk(float lo, float hi) { typedef __bf16 bf2 __attribute__((ext_vector_type(2))); f32x2 v = {lo, hi}; bf2 b = __builtin_convertvector(v, bf2); return __builtin_bit_cast(unsigned, b); }
; __device__ __forceinline__ void transpose_item(const float* W, int K, int N, bf16_t* WT, int mode, LAS float* scr, int item, int lane) {
;     ...
;     for (int i = 0; i < 32; ++i) { const int kk = 2 * i + (lane >> 5); scr[kk * 33 + (lane & 31)] = W[(size_t)(k0 + kk) * N + n0 + (lane & 31)]; }
;     asm volatile("s_waitcnt lgkmcnt(0)" ::: "memory");
;     const int c = lane & 7;
; #pragma unroll
;     for (int j = 0; j < 4; ++j) { const int n = (lane >> 3) + 8 * j; const LAS float* s = scr + (8 * c) * 33 + n;
;         u32x4 o; o.x = cvtpk(s[0 * 33], s[1 * 33]); o.y = cvtpk(s[2 * 33], s[3 * 33]); o.z = cvtpk(s[4 * 33], s[5 * 33]); o.w = cvtpk(s[6 * 33], s[7 * 33]);
;         *(u32x4*)(WT + (size_t)wrow_map(mode, n0 + n) * K + k0 + 8 * c) = o; }
;     asm volatile("s_waitcnt lgkmcnt(0)" ::: "memory");
	ds_write2_b32 v28, v27, v79 offset1:66
	s_waitcnt vmcnt(28)
	ds_write2_b32 v28, v88, v89 offset0:132 offset1:198
	v_add_u32_e32 v27, 0x400, v28
	s_waitcnt vmcnt(26)
	ds_write2_b32 v27, v90, v91 offset0:8 offset1:74
	v_add_u32_e32 v27, v7, v45
	s_waitcnt vmcnt(24)
	ds_write2_b32 v27, v92, v93 offset1:66
	s_waitcnt vmcnt(22)
	ds_write2_b32 v27, v94, v95 offset0:132 offset1:198
	v_add_u32_e32 v27, 0x400, v27
	s_waitcnt vmcnt(20)
	ds_write2_b32 v27, v96, v97 offset0:8 offset1:74
	v_add_u32_e32 v27, v7, v52
	s_waitcnt vmcnt(18)
	ds_write2_b32 v27, v98, v99 offset1:66
	s_waitcnt vmcnt(16)
	ds_write2_b32 v27, v100, v101 offset0:132 offset1:198
	v_add_u32_e32 v27, 0x400, v27
	s_lshl_b32 s16, s16, 1
	s_add_u32 s10, s10, s16
	s_addc_u32 s11, s11, 0
	s_waitcnt vmcnt(14)
	ds_write2_b32 v27, v102, v103 offset0:8 offset1:74
	v_add_u32_e32 v27, v7, v59
	s_waitcnt vmcnt(12)
	ds_write2_b32 v27, v104, v105 offset1:66
	s_waitcnt vmcnt(10)
	ds_write2_b32 v27, v106, v107 offset0:132 offset1:198
	v_add_u32_e32 v27, 0x400, v27
	s_waitcnt vmcnt(8)
	ds_write2_b32 v27, v108, v109 offset0:8 offset1:74
	v_add_u32_e32 v27, v7, v66
	s_waitcnt vmcnt(6)
	ds_write2_b32 v27, v4, v86 offset1:66
	s_waitcnt vmcnt(4)
	ds_write2_b32 v27, v87, v110 offset0:132 offset1:198
	v_add_u32_e32 v4, 0x400, v27
	s_waitcnt vmcnt(2)
	ds_write2_b32 v4, v111, v112 offset0:8 offset1:74
	s_waitcnt vmcnt(0)
	ds_write2_b32 v4, v113, v114 offset0:140 offset1:206
	s_waitcnt lgkmcnt(0)
	ds_read2_b32 v[32:33], v70 offset0:33 offset1:41
	ds_read2_b32 v[34:35], v70 offset1:8
	ds_read2_b32 v[36:37], v70 offset0:66 offset1:74
	ds_read2_b32 v[80:81], v70 offset0:99 offset1:107
	ds_read2_b32 v[82:83], v70 offset0:132 offset1:140
	ds_read2_b32 v[84:85], v70 offset0:165 offset1:173
	ds_read2_b32 v[86:87], v70 offset0:198 offset1:206
	ds_read2_b32 v[88:89], v70 offset0:231 offset1:239
	v_mov_b32_e32 v27, v5
	v_or_b32_e32 v4, s8, v69
	v_lshl_add_u64 v[90:91], s[10:11], 0, v[26:27]
	v_lshlrev_b32_e32 v4, 10, v4
	s_waitcnt lgkmcnt(6)
	v_cvt_pk_bf16_f32 v28, v34, v32
	s_waitcnt lgkmcnt(4)
	v_cvt_pk_bf16_f32 v29, v36, v80
	s_waitcnt lgkmcnt(2)
	v_cvt_pk_bf16_f32 v30, v82, v84
	s_waitcnt lgkmcnt(0)
	v_cvt_pk_bf16_f32 v31, v86, v88
	v_lshl_add_u64 v[92:93], v[90:91], 0, v[4:5]
	global_store_dwordx4 v[92:93], v[28:31], off
	v_or_b32_e32 v4, s8, v76
	v_lshlrev_b32_e32 v4, 10, v4
	v_cvt_pk_bf16_f32 v28, v35, v33
	v_cvt_pk_bf16_f32 v29, v37, v81
	v_cvt_pk_bf16_f32 v30, v83, v85
	v_cvt_pk_bf16_f32 v31, v87, v89
	ds_read2_b32 v[34:35], v70 offset0:49 offset1:57
	ds_read2_b32 v[36:37], v70 offset0:16 offset1:24
	ds_read2_b32 v[80:81], v70 offset0:82 offset1:90
	ds_read2_b32 v[82:83], v70 offset0:115 offset1:123
	ds_read2_b32 v[84:85], v70 offset0:148 offset1:156
	ds_read2_b32 v[86:87], v70 offset0:181 offset1:189
	ds_read2_b32 v[88:89], v70 offset0:214 offset1:222
	ds_read2_b32 v[92:93], v70 offset0:247 offset1:255
	v_lshl_add_u64 v[32:33], v[90:91], 0, v[4:5]
	v_or_b32_e32 v4, s8, v77
	v_lshlrev_b32_e32 v4, 10, v4
	global_store_dwordx4 v[32:33], v[28:31], off
	v_lshl_add_u64 v[32:33], v[90:91], 0, v[4:5]
	v_or_b32_e32 v4, s8, v78
	s_waitcnt lgkmcnt(6)
	v_cvt_pk_bf16_f32 v28, v36, v34
	s_waitcnt lgkmcnt(4)
	v_cvt_pk_bf16_f32 v29, v80, v82
	s_waitcnt lgkmcnt(2)
	v_cvt_pk_bf16_f32 v30, v84, v86
	s_waitcnt lgkmcnt(0)
	v_cvt_pk_bf16_f32 v31, v88, v92
	v_lshlrev_b32_e32 v4, 10, v4
	global_store_dwordx4 v[32:33], v[28:31], off
	v_lshl_add_u64 v[32:33], v[90:91], 0, v[4:5]
	s_nop 0
	v_cvt_pk_bf16_f32 v28, v37, v35
	v_cvt_pk_bf16_f32 v29, v81, v83
	v_cvt_pk_bf16_f32 v30, v85, v87
	v_cvt_pk_bf16_f32 v31, v89, v93
	global_store_dwordx4 v[32:33], v[28:31], off
	s_waitcnt lgkmcnt(0)

; #define LAS __attribute__((address_space(3)))
; __device__ __forceinline__ void transpose_item(const float* W, int K, int N, bf16_t* WT, int mode, LAS float* scr, int item, int lane) {
;     const int nblk = N / 32, kb = item / nblk, nb = item % nblk, k0 = 64 * kb, n0 = 32 * nb;
; #pragma unroll
;     for (int i = 0; i < 32; ++i) { const int kk = 2 * i + (lane >> 5); scr[kk * 33 + (lane & 31)] = W[(size_t)(k0 + kk) * N + n0 + (lane & 31)]; }
; __device__ __forceinline__ void convert_weights(PPtr P, int li, LAS unsigned char* lds, int gw, int NGW, int wave, int lane) {
;     ...
;         if (r < I_GLU) { transpose_item(P->in[26] + (size_t)li * 512 * 1024, 512, 1024, Wb + W_GLU, 2, scr, r, lane); continue; } r -= I_GLU;
.LBB0_32:
	s_andn2_b64 vcc, exec, s[10:11]
	s_cbranch_vccnz .LBB0_34
	s_load_dwordx2 s[16:17], s[6:7], 0xd0
	s_add_i32 s11, s38, 0xfffff110
	s_and_b32 s39, s11, 31
	s_add_i32 s8, s22, 0x1e00
	s_and_b32 s8, s8, 0x1c0
	s_lshl_b32 s10, s11, 5
	s_lshl_b32 s39, s39, 7
	s_waitcnt lgkmcnt(0)
	s_add_u32 s16, s16, s39
	s_addc_u32 s17, s17, 0
	v_lshlrev_b32_e32 v4, 2, v2
	v_lshl_add_u64 v[28:29], s[16:17], 0, v[4:5]
	v_or_b32_e32 v4, s8, v3
	v_lshlrev_b32_e32 v4, 12, v4
	v_lshl_add_u64 v[30:31], v[28:29], 0, v[4:5]
	v_or_b32_e32 v4, s8, v39
	v_lshlrev_b32_e32 v4, 12, v4
	v_lshl_add_u64 v[32:33], v[28:29], 0, v[4:5]
	v_or_b32_e32 v4, s8, v40
	v_lshlrev_b32_e32 v4, 12, v4
	v_lshl_add_u64 v[34:35], v[28:29], 0, v[4:5]
	v_or_b32_e32 v4, s8, v41
	v_lshlrev_b32_e32 v4, 12, v4
	v_lshl_add_u64 v[36:37], v[28:29], 0, v[4:5]
	v_or_b32_e32 v4, s8, v42
	v_lshlrev_b32_e32 v4, 12, v4
	v_lshl_add_u64 v[80:81], v[28:29], 0, v[4:5]
	v_or_b32_e32 v4, s8, v43
	v_lshlrev_b32_e32 v4, 12, v4
	v_lshl_add_u64 v[82:83], v[28:29], 0, v[4:5]
	v_or_b32_e32 v4, s8, v44
	v_lshlrev_b32_e32 v4, 12, v4
	v_lshl_add_u64 v[84:85], v[28:29], 0, v[4:5]
	v_or_b32_e32 v4, s8, v46
	v_lshlrev_b32_e32 v4, 12, v4
	v_lshl_add_u64 v[86:87], v[28:29], 0, v[4:5]
	v_or_b32_e32 v4, s8, v47
	v_lshlrev_b32_e32 v4, 12, v4
	global_load_dword v27, v[30:31], off nt
	global_load_dword v79, v[32:33], off nt
	global_load_dword v88, v[34:35], off nt
	global_load_dword v89, v[36:37], off nt
	global_load_dword v90, v[80:81], off nt
	global_load_dword v91, v[82:83], off nt
	global_load_dword v92, v[84:85], off nt
	global_load_dword v93, v[86:87], off nt
	v_lshl_add_u64 v[30:31], v[28:29], 0, v[4:5]
	v_or_b32_e32 v4, s8, v48
	v_lshlrev_b32_e32 v4, 12, v4
	v_lshl_add_u64 v[32:33], v[28:29], 0, v[4:5]
	v_or_b32_e32 v4, s8, v49
	v_lshlrev_b32_e32 v4, 12, v4
	v_lshl_add_u64 v[34:35], v[28:29], 0, v[4:5]
	v_or_b32_e32 v4, s8, v50
	v_lshlrev_b32_e32 v4, 12, v4
	v_lshl_add_u64 v[36:37], v[28:29], 0, v[4:5]
	v_or_b32_e32 v4, s8, v51
	v_lshlrev_b32_e32 v4, 12, v4
	v_lshl_add_u64 v[80:81], v[28:29], 0, v[4:5]
	v_or_b32_e32 v4, s8, v53
	v_lshlrev_b32_e32 v4, 12, v4
	v_lshl_add_u64 v[82:83], v[28:29], 0, v[4:5]
	v_or_b32_e32 v4, s8, v54
	v_lshlrev_b32_e32 v4, 12, v4
	v_lshl_add_u64 v[84:85], v[28:29], 0, v[4:5]
	v_or_b32_e32 v4, s8, v55
	v_lshlrev_b32_e32 v4, 12, v4
	v_lshl_add_u64 v[86:87], v[28:29], 0, v[4:5]
	v_or_b32_e32 v4, s8, v56
	v_lshlrev_b32_e32 v4, 12, v4
	global_load_dword v94, v[30:31], off nt
	global_load_dword v95, v[32:33], off nt
	global_load_dword v96, v[34:35], off nt
	global_load_dword v97, v[36:37], off nt
	global_load_dword v98, v[80:81], off nt
	global_load_dword v99, v[82:83], off nt
	global_load_dword v100, v[84:85], off nt
	global_load_dword v101, v[86:87], off nt
	v_lshl_add_u64 v[30:31], v[28:29], 0, v[4:5]
	v_or_b32_e32 v4, s8, v57
	v_lshlrev_b32_e32 v4, 12, v4
	v_lshl_add_u64 v[32:33], v[28:29], 0, v[4:5]
	v_or_b32_e32 v4, s8, v58
	v_lshlrev_b32_e32 v4, 12, v4
	v_lshl_add_u64 v[34:35], v[28:29], 0, v[4:5]
	v_or_b32_e32 v4, s8, v60
	v_lshlrev_b32_e32 v4, 12, v4
	v_lshl_add_u64 v[36:37], v[28:29], 0, v[4:5]
	v_or_b32_e32 v4, s8, v61
	v_lshlrev_b32_e32 v4, 12, v4
	v_lshl_add_u64 v[80:81], v[28:29], 0, v[4:5]
	v_or_b32_e32 v4, s8, v62
	v_lshlrev_b32_e32 v4, 12, v4
	v_lshl_add_u64 v[82:83], v[28:29], 0, v[4:5]
	v_or_b32_e32 v4, s8, v63
	v_lshlrev_b32_e32 v4, 12, v4
	v_lshl_add_u64 v[84:85], v[28:29], 0, v[4:5]
	v_or_b32_e32 v4, s8, v64
	v_lshlrev_b32_e32 v4, 12, v4
	v_lshl_add_u64 v[86:87], v[28:29], 0, v[4:5]
	v_or_b32_e32 v4, s8, v65
	v_lshlrev_b32_e32 v4, 12, v4
	global_load_dword v102, v[30:31], off nt
	global_load_dword v103, v[32:33], off nt
	global_load_dword v104, v[34:35], off nt
	global_load_dword v105, v[36:37], off nt
	global_load_dword v106, v[80:81], off nt
	global_load_dword v107, v[82:83], off nt
	global_load_dword v108, v[84:85], off nt
	global_load_dword v109, v[86:87], off nt
	v_lshl_add_u64 v[30:31], v[28:29], 0, v[4:5]
	v_or_b32_e32 v4, s8, v67
	v_lshlrev_b32_e32 v4, 12, v4
	v_lshl_add_u64 v[32:33], v[28:29], 0, v[4:5]
	v_or_b32_e32 v4, s8, v68
	v_lshlrev_b32_e32 v4, 12, v4
	v_lshl_add_u64 v[34:35], v[28:29], 0, v[4:5]
	v_or_b32_e32 v4, s8, v71
	v_lshlrev_b32_e32 v4, 12, v4
	v_lshl_add_u64 v[36:37], v[28:29], 0, v[4:5]
	v_or_b32_e32 v4, s8, v72
	v_lshlrev_b32_e32 v4, 12, v4
	v_lshl_add_u64 v[80:81], v[28:29], 0, v[4:5]
	v_or_b32_e32 v4, s8, v73
	v_lshlrev_b32_e32 v4, 12, v4
	v_lshl_add_u64 v[82:83], v[28:29], 0, v[4:5]
	v_or_b32_e32 v4, s8, v74
	v_lshlrev_b32_e32 v4, 12, v4
	v_lshl_add_u64 v[84:85], v[28:29], 0, v[4:5]
	v_or_b32_e32 v4, s8, v75
	v_lshlrev_b32_e32 v4, 12, v4
	v_lshl_add_u64 v[28:29], v[28:29], 0, v[4:5]
	global_load_dword v4, v[30:31], off nt
	global_load_dword v86, v[32:33], off nt
	global_load_dword v87, v[34:35], off nt
	global_load_dword v110, v[36:37], off nt
	global_load_dword v111, v[80:81], off nt
	global_load_dword v112, v[82:83], off nt
	global_load_dword v113, v[84:85], off nt
	global_load_dword v114, v[28:29], off nt
	v_add_u32_e32 v28, v7, v9
	s_waitcnt vmcnt(30)
; #define LAS __attribute__((address_space(3)))
; __device__ __forceinline__ unsigned cvtpk(float lo, float hi) { typedef __bf16 bf2 __attribute__((ext_vector_type(2))); f32x2 v = {lo, hi}; bf2 b = __builtin_convertvector(v, bf2); return __builtin_bit_cast(unsigned, b); }
; __device__ __forceinline__ int wrow_map(int mode, int n) {
;     ...
;     if (mode == 2) { const int c = n & 511, t = c >> 7; return 256 * t + (n >> 9) * 128 + (c & 127); }
; __device__ __forceinline__ void transpose_item(const float* W, int K, int N, bf16_t* WT, int mode, LAS float* scr, int item, int lane) {
;     ...
;     for (int i = 0; i < 32; ++i) { const int kk = 2 * i + (lane >> 5); scr[kk * 33 + (lane & 31)] = W[(size_t)(k0 + kk) * N + n0 + (lane & 31)]; }
;     asm volatile("s_waitcnt lgkmcnt(0)" ::: "memory");
;     const int c = lane & 7;
; #pragma unroll
;     for (int j = 0; j < 4; ++j) { const int n = (lane >> 3) + 8 * j; const LAS float* s = scr + (8 * c) * 33 + n;
;         u32x4 o; o.x = cvtpk(s[0 * 33], s[1 * 33]); o.y = cvtpk(s[2 * 33], s[3 * 33]); o.z = cvtpk(s[4 * 33], s[5 * 33]); o.w = cvtpk(s[6 * 33], s[7 * 33]);
;         *(u32x4*)(WT + (size_t)wrow_map(mode, n0 + n) * K + k0 + 8 * c) = o; }
;     asm volatile("s_waitcnt lgkmcnt(0)" ::: "memory");
	ds_write2_b32 v28, v27, v79 offset1:66
	s_waitcnt vmcnt(28)
	ds_write2_b32 v28, v88, v89 offset0:132 offset1:198
	v_add_u32_e32 v27, 0x400, v28
	s_waitcnt vmcnt(26)
	ds_write2_b32 v27, v90, v91 offset0:8 offset1:74
	v_add_u32_e32 v27, v7, v45
	s_waitcnt vmcnt(24)
	ds_write2_b32 v27, v92, v93 offset1:66
	s_waitcnt vmcnt(22)
	ds_write2_b32 v27, v94, v95 offset0:132 offset1:198
	v_add_u32_e32 v27, 0x400, v27
	s_waitcnt vmcnt(20)
	ds_write2_b32 v27, v96, v97 offset0:8 offset1:74
	v_add_u32_e32 v27, v7, v52
	s_waitcnt vmcnt(18)
	ds_write2_b32 v27, v98, v99 offset1:66
	s_waitcnt vmcnt(16)
	ds_write2_b32 v27, v100, v101 offset0:132 offset1:198
	v_add_u32_e32 v27, 0x400, v27
	s_lshl_b32 s8, s8, 1
	v_lshl_add_u64 v[32:33], v[16:17], 0, s[8:9]
	s_lshl_b32 s8, s11, 6
	s_lshl_b32 s11, s11, 3
	s_and_b32 s8, s8, 0x300
	s_and_b32 s11, s11, 0x80
	s_and_b32 s10, s10, 0x60
	s_or_b32 s8, s8, s11
	s_waitcnt vmcnt(14)
	ds_write2_b32 v27, v102, v103 offset0:8 offset1:74
	v_add_u32_e32 v27, v7, v59
	s_waitcnt vmcnt(12)
	ds_write2_b32 v27, v104, v105 offset1:66
	s_waitcnt vmcnt(10)
	ds_write2_b32 v27, v106, v107 offset0:132 offset1:198
	v_add_u32_e32 v27, 0x400, v27
	s_waitcnt vmcnt(8)
	ds_write2_b32 v27, v108, v109 offset0:8 offset1:74
	v_add_u32_e32 v27, v7, v66
	s_waitcnt vmcnt(6)
	ds_write2_b32 v27, v4, v86 offset1:66
	s_waitcnt vmcnt(4)
	ds_write2_b32 v27, v87, v110 offset0:132 offset1:198
	v_add_u32_e32 v4, 0x400, v27
	s_waitcnt vmcnt(2)
	ds_write2_b32 v4, v111, v112 offset0:8 offset1:74
	s_waitcnt vmcnt(0)
	ds_write2_b32 v4, v113, v114 offset0:140 offset1:206
	s_waitcnt lgkmcnt(0)
	ds_read2_b32 v[34:35], v70 offset0:33 offset1:41
	ds_read2_b32 v[36:37], v70 offset1:8
	ds_read2_b32 v[80:81], v70 offset0:66 offset1:74
	ds_read2_b32 v[82:83], v70 offset0:99 offset1:107
	ds_read2_b32 v[84:85], v70 offset0:132 offset1:140
	ds_read2_b32 v[86:87], v70 offset0:165 offset1:173
	ds_read2_b32 v[88:89], v70 offset0:198 offset1:206
	ds_read2_b32 v[90:91], v70 offset0:231 offset1:239
	v_or_b32_e32 v4, s10, v69
	v_or_b32_e32 v4, s8, v4
	v_lshlrev_b32_e32 v4, 10, v4
	v_lshl_add_u64 v[92:93], v[32:33], 0, v[4:5]
	v_or_b32_e32 v4, s10, v76
	s_waitcnt lgkmcnt(6)
	v_cvt_pk_bf16_f32 v28, v36, v34
	s_waitcnt lgkmcnt(4)
	v_cvt_pk_bf16_f32 v29, v80, v82
	s_waitcnt lgkmcnt(2)
	v_cvt_pk_bf16_f32 v30, v84, v86
	s_waitcnt lgkmcnt(0)
	v_cvt_pk_bf16_f32 v31, v88, v90
	v_or_b32_e32 v4, s8, v4
	global_store_dwordx4 v[92:93], v[28:31], off
	v_lshlrev_b32_e32 v4, 10, v4
	s_nop 0
	v_cvt_pk_bf16_f32 v28, v37, v35
	v_cvt_pk_bf16_f32 v29, v81, v83
	v_cvt_pk_bf16_f32 v30, v85, v87
	v_cvt_pk_bf16_f32 v31, v89, v91
	v_lshl_add_u64 v[34:35], v[32:33], 0, v[4:5]
	ds_read2_b32 v[36:37], v70 offset0:49 offset1:57
	ds_read2_b32 v[80:81], v70 offset0:16 offset1:24
	ds_read2_b32 v[82:83], v70 offset0:82 offset1:90
	ds_read2_b32 v[84:85], v70 offset0:115 offset1:123
	ds_read2_b32 v[86:87], v70 offset0:148 offset1:156
	ds_read2_b32 v[88:89], v70 offset0:181 offset1:189
	ds_read2_b32 v[90:91], v70 offset0:214 offset1:222
	ds_read2_b32 v[92:93], v70 offset0:247 offset1:255
	v_or_b32_e32 v4, s10, v77
	v_or_b32_e32 v4, s8, v4
	v_lshlrev_b32_e32 v4, 10, v4
	global_store_dwordx4 v[34:35], v[28:31], off
	v_lshl_add_u64 v[34:35], v[32:33], 0, v[4:5]
	v_or_b32_e32 v4, s10, v78
	v_or_b32_e32 v4, s8, v4
	s_waitcnt lgkmcnt(6)
	v_cvt_pk_bf16_f32 v28, v80, v36
	s_waitcnt lgkmcnt(4)
	v_cvt_pk_bf16_f32 v29, v82, v84
	s_waitcnt lgkmcnt(2)
	v_cvt_pk_bf16_f32 v30, v86, v88
	s_waitcnt lgkmcnt(0)
	v_cvt_pk_bf16_f32 v31, v90, v92
	v_lshlrev_b32_e32 v4, 10, v4
	global_store_dwordx4 v[34:35], v[28:31], off
	v_lshl_add_u64 v[32:33], v[32:33], 0, v[4:5]
	s_nop 0
	v_cvt_pk_bf16_f32 v28, v81, v37
	v_cvt_pk_bf16_f32 v29, v83, v85
	v_cvt_pk_bf16_f32 v30, v87, v89
	v_cvt_pk_bf16_f32 v31, v91, v93
	global_store_dwordx4 v[32:33], v[28:31], off
	s_waitcnt lgkmcnt(0)

; #define LAS __attribute__((address_space(3)))
; __device__ __forceinline__ void transpose_item(const float* W, int K, int N, bf16_t* WT, int mode, LAS float* scr, int item, int lane) {
;     const int nblk = N / 32, kb = item / nblk, nb = item % nblk, k0 = 64 * kb, n0 = 32 * nb;
; #pragma unroll
;     for (int i = 0; i < 32; ++i) { const int kk = 2 * i + (lane >> 5); scr[kk * 33 + (lane & 31)] = W[(size_t)(k0 + kk) * N + n0 + (lane & 31)]; }
; __device__ __forceinline__ void convert_weights(PPtr P, int li, LAS unsigned char* lds, int gw, int NGW, int wave, int lane) {
;     ...
;         if (r < I_UKV) { transpose_item(P->in[17] + (size_t)li * 128 * 1024, 128, 1024, Wb + W_UKV, 0, scr, r, lane); continue; } r -= I_UKV;
.LBB0_35:
	s_andn2_b64 vcc, exec, s[10:11]
	s_cbranch_vccnz .LBB0_37
	s_add_i32 s8, s38, 0xfffff150
	s_add_i32 s10, s38, 0xfffff130
	s_load_dwordx2 s[16:17], s[6:7], 0x88
	s_cmp_lt_u32 s8, 32
	s_cselect_b32 s10, s8, s10
	s_cmp_gt_u32 s8, 31
	s_cselect_b32 s8, 64, 0
	s_lshl_b32 s10, s10, 5
	s_ashr_i32 s11, s10, 31
	s_lshl_b64 s[40:41], s[10:11], 2
	s_waitcnt lgkmcnt(0)
	s_add_u32 s16, s16, s40
	s_addc_u32 s17, s17, s41
	v_lshlrev_b32_e32 v4, 2, v2
	v_lshl_add_u64 v[28:29], s[16:17], 0, v[4:5]
	v_or_b32_e32 v4, s8, v3
	v_lshlrev_b32_e32 v4, 12, v4
	v_lshl_add_u64 v[30:31], v[28:29], 0, v[4:5]
	v_or_b32_e32 v4, s8, v39
	v_lshlrev_b32_e32 v4, 12, v4
	v_lshl_add_u64 v[32:33], v[28:29], 0, v[4:5]
	v_or_b32_e32 v4, s8, v40
	v_lshlrev_b32_e32 v4, 12, v4
	v_lshl_add_u64 v[34:35], v[28:29], 0, v[4:5]
	v_or_b32_e32 v4, s8, v41
	v_lshlrev_b32_e32 v4, 12, v4
	v_lshl_add_u64 v[36:37], v[28:29], 0, v[4:5]
	v_or_b32_e32 v4, s8, v42
	v_lshlrev_b32_e32 v4, 12, v4
	v_lshl_add_u64 v[80:81], v[28:29], 0, v[4:5]
	v_or_b32_e32 v4, s8, v43
	v_lshlrev_b32_e32 v4, 12, v4
	v_lshl_add_u64 v[82:83], v[28:29], 0, v[4:5]
	v_or_b32_e32 v4, s8, v44
	v_lshlrev_b32_e32 v4, 12, v4
	v_lshl_add_u64 v[84:85], v[28:29], 0, v[4:5]
	v_or_b32_e32 v4, s8, v46
	v_lshlrev_b32_e32 v4, 12, v4
	v_lshl_add_u64 v[86:87], v[28:29], 0, v[4:5]
	v_or_b32_e32 v4, s8, v47
	v_lshlrev_b32_e32 v4, 12, v4
	global_load_dword v27, v[30:31], off nt
	global_load_dword v79, v[32:33], off nt
	global_load_dword v88, v[34:35], off nt
	global_load_dword v89, v[36:37], off nt
	global_load_dword v90, v[80:81], off nt
	global_load_dword v91, v[82:83], off nt
	global_load_dword v92, v[84:85], off nt
	global_load_dword v93, v[86:87], off nt
	v_lshl_add_u64 v[30:31], v[28:29], 0, v[4:5]
	v_or_b32_e32 v4, s8, v48
	v_lshlrev_b32_e32 v4, 12, v4
	v_lshl_add_u64 v[32:33], v[28:29], 0, v[4:5]
	v_or_b32_e32 v4, s8, v49
	v_lshlrev_b32_e32 v4, 12, v4
	v_lshl_add_u64 v[34:35], v[28:29], 0, v[4:5]
	v_or_b32_e32 v4, s8, v50
	v_lshlrev_b32_e32 v4, 12, v4
	v_lshl_add_u64 v[36:37], v[28:29], 0, v[4:5]
	v_or_b32_e32 v4, s8, v51
	v_lshlrev_b32_e32 v4, 12, v4
	v_lshl_add_u64 v[80:81], v[28:29], 0, v[4:5]
	v_or_b32_e32 v4, s8, v53
	v_lshlrev_b32_e32 v4, 12, v4
	v_lshl_add_u64 v[82:83], v[28:29], 0, v[4:5]
	v_or_b32_e32 v4, s8, v54
	v_lshlrev_b32_e32 v4, 12, v4
	v_lshl_add_u64 v[84:85], v[28:29], 0, v[4:5]
	v_or_b32_e32 v4, s8, v55
	v_lshlrev_b32_e32 v4, 12, v4
	v_lshl_add_u64 v[86:87], v[28:29], 0, v[4:5]
	v_or_b32_e32 v4, s8, v56
	v_lshlrev_b32_e32 v4, 12, v4
	global_load_dword v94, v[30:31], off nt
	global_load_dword v95, v[32:33], off nt
	global_load_dword v96, v[34:35], off nt
	global_load_dword v97, v[36:37], off nt
	global_load_dword v98, v[80:81], off nt
	global_load_dword v99, v[82:83], off nt
	global_load_dword v100, v[84:85], off nt
	global_load_dword v101, v[86:87], off nt
	v_lshl_add_u64 v[30:31], v[28:29], 0, v[4:5]
	v_or_b32_e32 v4, s8, v57
	v_lshlrev_b32_e32 v4, 12, v4
	v_lshl_add_u64 v[32:33], v[28:29], 0, v[4:5]
	v_or_b32_e32 v4, s8, v58
	v_lshlrev_b32_e32 v4, 12, v4
	v_lshl_add_u64 v[34:35], v[28:29], 0, v[4:5]
	v_or_b32_e32 v4, s8, v60
	v_lshlrev_b32_e32 v4, 12, v4
	v_lshl_add_u64 v[36:37], v[28:29], 0, v[4:5]
	v_or_b32_e32 v4, s8, v61
	v_lshlrev_b32_e32 v4, 12, v4
	v_lshl_add_u64 v[80:81], v[28:29], 0, v[4:5]
	v_or_b32_e32 v4, s8, v62
	v_lshlrev_b32_e32 v4, 12, v4
	v_lshl_add_u64 v[82:83], v[28:29], 0, v[4:5]
	v_or_b32_e32 v4, s8, v63
	v_lshlrev_b32_e32 v4, 12, v4
	v_lshl_add_u64 v[84:85], v[28:29], 0, v[4:5]
	v_or_b32_e32 v4, s8, v64
	v_lshlrev_b32_e32 v4, 12, v4
	v_lshl_add_u64 v[86:87], v[28:29], 0, v[4:5]
	v_or_b32_e32 v4, s8, v65
	v_lshlrev_b32_e32 v4, 12, v4
	global_load_dword v102, v[30:31], off nt
	global_load_dword v103, v[32:33], off nt
	global_load_dword v104, v[34:35], off nt
	global_load_dword v105, v[36:37], off nt
	global_load_dword v106, v[80:81], off nt
	global_load_dword v107, v[82:83], off nt
	global_load_dword v108, v[84:85], off nt
	global_load_dword v109, v[86:87], off nt
	v_lshl_add_u64 v[30:31], v[28:29], 0, v[4:5]
	v_or_b32_e32 v4, s8, v67
	v_lshlrev_b32_e32 v4, 12, v4
	v_lshl_add_u64 v[32:33], v[28:29], 0, v[4:5]
	v_or_b32_e32 v4, s8, v68
	v_lshlrev_b32_e32 v4, 12, v4
	v_lshl_add_u64 v[34:35], v[28:29], 0, v[4:5]
	v_or_b32_e32 v4, s8, v71
	v_lshlrev_b32_e32 v4, 12, v4
	v_lshl_add_u64 v[36:37], v[28:29], 0, v[4:5]
	v_or_b32_e32 v4, s8, v72
	v_lshlrev_b32_e32 v4, 12, v4
	v_lshl_add_u64 v[80:81], v[28:29], 0, v[4:5]
	v_or_b32_e32 v4, s8, v73
	v_lshlrev_b32_e32 v4, 12, v4
	v_lshl_add_u64 v[82:83], v[28:29], 0, v[4:5]
	v_or_b32_e32 v4, s8, v74
	v_lshlrev_b32_e32 v4, 12, v4
	v_lshl_add_u64 v[84:85], v[28:29], 0, v[4:5]
	v_or_b32_e32 v4, s8, v75
	v_lshlrev_b32_e32 v4, 12, v4
	v_lshl_add_u64 v[28:29], v[28:29], 0, v[4:5]
	global_load_dword v4, v[30:31], off nt
	global_load_dword v86, v[32:33], off nt
	global_load_dword v87, v[34:35], off nt
	global_load_dword v110, v[36:37], off nt
	global_load_dword v111, v[80:81], off nt
	global_load_dword v112, v[82:83], off nt
	global_load_dword v113, v[84:85], off nt
	global_load_dword v114, v[28:29], off nt
	v_add_u32_e32 v28, v7, v9
	s_waitcnt vmcnt(30)
; #define LAS __attribute__((address_space(3)))
; __device__ __forceinline__ unsigned cvtpk(float lo, float hi) { typedef __bf16 bf2 __attribute__((ext_vector_type(2))); f32x2 v = {lo, hi}; bf2 b = __builtin_convertvector(v, bf2); return __builtin_bit_cast(unsigned, b); }
; __device__ __forceinline__ void transpose_item(const float* W, int K, int N, bf16_t* WT, int mode, LAS float* scr, int item, int lane) {
;     ...
;     for (int i = 0; i < 32; ++i) { const int kk = 2 * i + (lane >> 5); scr[kk * 33 + (lane & 31)] = W[(size_t)(k0 + kk) * N + n0 + (lane & 31)]; }
;     asm volatile("s_waitcnt lgkmcnt(0)" ::: "memory");
;     const int c = lane & 7;
; #pragma unroll
;     for (int j = 0; j < 4; ++j) { const int n = (lane >> 3) + 8 * j; const LAS float* s = scr + (8 * c) * 33 + n;
;         u32x4 o; o.x = cvtpk(s[0 * 33], s[1 * 33]); o.y = cvtpk(s[2 * 33], s[3 * 33]); o.z = cvtpk(s[4 * 33], s[5 * 33]); o.w = cvtpk(s[6 * 33], s[7 * 33]);
;         *(u32x4*)(WT + (size_t)wrow_map(mode, n0 + n) * K + k0 + 8 * c) = o; }
;     asm volatile("s_waitcnt lgkmcnt(0)" ::: "memory");
	ds_write2_b32 v28, v27, v79 offset1:66
	s_waitcnt vmcnt(28)
	ds_write2_b32 v28, v88, v89 offset0:132 offset1:198
	v_add_u32_e32 v27, 0x400, v28
	s_waitcnt vmcnt(26)
	ds_write2_b32 v27, v90, v91 offset0:8 offset1:74
	v_add_u32_e32 v27, v7, v45
	s_waitcnt vmcnt(24)
	ds_write2_b32 v27, v92, v93 offset1:66
	s_waitcnt vmcnt(22)
	ds_write2_b32 v27, v94, v95 offset0:132 offset1:198
	v_add_u32_e32 v27, 0x400, v27
	s_waitcnt vmcnt(20)
	ds_write2_b32 v27, v96, v97 offset0:8 offset1:74
	v_add_u32_e32 v27, v7, v52
	s_waitcnt vmcnt(18)
	ds_write2_b32 v27, v98, v99 offset1:66
	s_waitcnt vmcnt(16)
	ds_write2_b32 v27, v100, v101 offset0:132 offset1:198
	v_add_u32_e32 v27, 0x400, v27
	v_or_b32_e32 v92, s10, v69
	s_lshl_b32 s8, s8, 1
	v_ashrrev_i32_e32 v93, 31, v92
	v_lshl_add_u64 v[90:91], v[18:19], 0, s[8:9]
	v_lshlrev_b64 v[92:93], 8, v[92:93]
	v_lshl_add_u64 v[92:93], v[90:91], 0, v[92:93]
	s_waitcnt vmcnt(14)
	ds_write2_b32 v27, v102, v103 offset0:8 offset1:74
	v_add_u32_e32 v27, v7, v59
	s_waitcnt vmcnt(12)
	ds_write2_b32 v27, v104, v105 offset1:66
	s_waitcnt vmcnt(10)
	ds_write2_b32 v27, v106, v107 offset0:132 offset1:198
	v_add_u32_e32 v27, 0x400, v27
	s_waitcnt vmcnt(8)
	ds_write2_b32 v27, v108, v109 offset0:8 offset1:74
	v_add_u32_e32 v27, v7, v66
	s_waitcnt vmcnt(6)
	ds_write2_b32 v27, v4, v86 offset1:66
	s_waitcnt vmcnt(4)
	ds_write2_b32 v27, v87, v110 offset0:132 offset1:198
	v_add_u32_e32 v4, 0x400, v27
	s_waitcnt vmcnt(2)
	ds_write2_b32 v4, v111, v112 offset0:8 offset1:74
	s_waitcnt vmcnt(0)
	ds_write2_b32 v4, v113, v114 offset0:140 offset1:206
	s_waitcnt lgkmcnt(0)
	ds_read2_b32 v[32:33], v70 offset0:33 offset1:41
	ds_read2_b32 v[34:35], v70 offset1:8
	ds_read2_b32 v[36:37], v70 offset0:66 offset1:74
	ds_read2_b32 v[80:81], v70 offset0:99 offset1:107
	ds_read2_b32 v[82:83], v70 offset0:132 offset1:140
	ds_read2_b32 v[84:85], v70 offset0:165 offset1:173
	ds_read2_b32 v[86:87], v70 offset0:198 offset1:206
	ds_read2_b32 v[88:89], v70 offset0:231 offset1:239
	s_waitcnt lgkmcnt(6)
	v_cvt_pk_bf16_f32 v28, v34, v32
	s_waitcnt lgkmcnt(4)
	v_cvt_pk_bf16_f32 v29, v36, v80
	s_waitcnt lgkmcnt(2)
	v_cvt_pk_bf16_f32 v30, v82, v84
	v_or_b32_e32 v32, s10, v76
	s_waitcnt lgkmcnt(0)
	v_cvt_pk_bf16_f32 v31, v86, v88
	global_store_dwordx4 v[92:93], v[28:31], off
	s_nop 1
	v_cvt_pk_bf16_f32 v28, v35, v33
	v_ashrrev_i32_e32 v33, 31, v32
	v_cvt_pk_bf16_f32 v29, v37, v81
	v_cvt_pk_bf16_f32 v30, v83, v85
	v_cvt_pk_bf16_f32 v31, v87, v89
	v_lshlrev_b64 v[32:33], 8, v[32:33]
	ds_read2_b32 v[34:35], v70 offset0:49 offset1:57
	ds_read2_b32 v[36:37], v70 offset0:16 offset1:24
	ds_read2_b32 v[80:81], v70 offset0:82 offset1:90
	ds_read2_b32 v[82:83], v70 offset0:115 offset1:123
	ds_read2_b32 v[84:85], v70 offset0:148 offset1:156
	ds_read2_b32 v[86:87], v70 offset0:181 offset1:189
	ds_read2_b32 v[88:89], v70 offset0:214 offset1:222
	ds_read2_b32 v[92:93], v70 offset0:247 offset1:255
	v_lshl_add_u64 v[32:33], v[90:91], 0, v[32:33]
	global_store_dwordx4 v[32:33], v[28:31], off
	v_or_b32_e32 v32, s10, v77
	v_ashrrev_i32_e32 v33, 31, v32
	v_lshlrev_b64 v[32:33], 8, v[32:33]
	s_waitcnt lgkmcnt(6)
	v_cvt_pk_bf16_f32 v28, v36, v34
	s_waitcnt lgkmcnt(4)
	v_cvt_pk_bf16_f32 v29, v80, v82
	s_waitcnt lgkmcnt(2)
	v_cvt_pk_bf16_f32 v30, v84, v86
	s_waitcnt lgkmcnt(0)
	v_cvt_pk_bf16_f32 v31, v88, v92
	v_lshl_add_u64 v[32:33], v[90:91], 0, v[32:33]
	global_store_dwordx4 v[32:33], v[28:31], off
	v_or_b32_e32 v32, s10, v78
	v_ashrrev_i32_e32 v33, 31, v32
	v_lshlrev_b64 v[32:33], 8, v[32:33]
	v_cvt_pk_bf16_f32 v28, v37, v35
	v_cvt_pk_bf16_f32 v29, v81, v83
	v_cvt_pk_bf16_f32 v30, v85, v87
	v_cvt_pk_bf16_f32 v31, v89, v93
	v_lshl_add_u64 v[32:33], v[90:91], 0, v[32:33]
	global_store_dwordx4 v[32:33], v[28:31], off
	s_waitcnt lgkmcnt(0)

; #define LAS __attribute__((address_space(3)))
; __device__ __forceinline__ void transpose_item(const float* W, int K, int N, bf16_t* WT, int mode, LAS float* scr, int item, int lane) {
;     const int nblk = N / 32, kb = item / nblk, nb = item % nblk, k0 = 64 * kb, n0 = 32 * nb;
; #pragma unroll
;     for (int i = 0; i < 32; ++i) { const int kk = 2 * i + (lane >> 5); scr[kk * 33 + (lane & 31)] = W[(size_t)(k0 + kk) * N + n0 + (lane & 31)]; }
; __device__ __forceinline__ void convert_weights(PPtr P, int li, LAS unsigned char* lds, int gw, int NGW, int wave, int lane) {
;     ...
;         if (r < I_UQ) { transpose_item(P->in[16] + (size_t)li * 256 * 768, 256, 768, Wb + W_UQ, 1, scr, r, lane); continue; } r -= I_UQ;
.LBB0_38:
	s_andn2_b64 vcc, exec, s[10:11]
	s_cbranch_vccnz .LBB0_56
	s_add_i32 s8, s38, 0xffb0
	s_and_b32 s10, s8, 0xff
	s_mulk_i32 s10, 0xab
	s_load_dwordx2 s[40:41], s[6:7], 0x80
	s_bfe_u32 s11, s10, 0x4000c
	s_mul_i32 s10, s11, 24
	s_sub_i32 s8, s8, s10
	s_and_b32 s10, s8, 0xff
	s_lshl_b32 s8, s11, 6
	s_lshl_b32 s16, s10, 5
	s_lshl_b32 s11, s10, 7
	s_waitcnt lgkmcnt(0)
	s_add_u32 s40, s40, s11
	s_addc_u32 s41, s41, 0
	v_lshlrev_b32_e32 v4, 2, v2
	v_lshl_add_u64 v[28:29], s[40:41], 0, v[4:5]
	v_or_b32_e32 v4, s8, v3
	v_mul_u32_u24_e32 v4, 0x300, v4
	v_lshlrev_b32_e32 v4, 2, v4
	v_lshl_add_u64 v[30:31], v[28:29], 0, v[4:5]
	v_or_b32_e32 v4, s8, v39
	v_mul_u32_u24_e32 v4, 0x300, v4
	v_lshlrev_b32_e32 v4, 2, v4
	v_lshl_add_u64 v[32:33], v[28:29], 0, v[4:5]
	v_or_b32_e32 v4, s8, v40
	v_mul_u32_u24_e32 v4, 0x300, v4
	v_lshlrev_b32_e32 v4, 2, v4
	v_lshl_add_u64 v[34:35], v[28:29], 0, v[4:5]
	v_or_b32_e32 v4, s8, v41
	v_mul_u32_u24_e32 v4, 0x300, v4
	v_lshlrev_b32_e32 v4, 2, v4
	v_lshl_add_u64 v[36:37], v[28:29], 0, v[4:5]
	v_or_b32_e32 v4, s8, v42
	v_mul_u32_u24_e32 v4, 0x300, v4
	v_lshlrev_b32_e32 v4, 2, v4
	v_lshl_add_u64 v[80:81], v[28:29], 0, v[4:5]
	v_or_b32_e32 v4, s8, v43
	v_mul_u32_u24_e32 v4, 0x300, v4
	v_lshlrev_b32_e32 v4, 2, v4
	v_lshl_add_u64 v[82:83], v[28:29], 0, v[4:5]
	v_or_b32_e32 v4, s8, v44
	v_mul_u32_u24_e32 v4, 0x300, v4
	v_lshlrev_b32_e32 v4, 2, v4
	v_lshl_add_u64 v[84:85], v[28:29], 0, v[4:5]
	v_or_b32_e32 v4, s8, v46
	v_mul_u32_u24_e32 v4, 0x300, v4
	v_lshlrev_b32_e32 v4, 2, v4
	v_lshl_add_u64 v[86:87], v[28:29], 0, v[4:5]
	v_or_b32_e32 v4, s8, v47
	v_mul_u32_u24_e32 v4, 0x300, v4
	v_lshlrev_b32_e32 v4, 2, v4
	global_load_dword v27, v[30:31], off nt
	global_load_dword v79, v[32:33], off nt
	global_load_dword v88, v[34:35], off nt
	global_load_dword v89, v[36:37], off nt
	global_load_dword v90, v[80:81], off nt
	global_load_dword v91, v[82:83], off nt
	global_load_dword v92, v[84:85], off nt
	global_load_dword v93, v[86:87], off nt
	v_lshl_add_u64 v[30:31], v[28:29], 0, v[4:5]
	v_or_b32_e32 v4, s8, v48
	v_mul_u32_u24_e32 v4, 0x300, v4
	v_lshlrev_b32_e32 v4, 2, v4
	v_lshl_add_u64 v[32:33], v[28:29], 0, v[4:5]
	v_or_b32_e32 v4, s8, v49
	v_mul_u32_u24_e32 v4, 0x300, v4
	v_lshlrev_b32_e32 v4, 2, v4
	v_lshl_add_u64 v[34:35], v[28:29], 0, v[4:5]
	v_or_b32_e32 v4, s8, v50
	v_mul_u32_u24_e32 v4, 0x300, v4
	v_lshlrev_b32_e32 v4, 2, v4
	v_lshl_add_u64 v[36:37], v[28:29], 0, v[4:5]
	v_or_b32_e32 v4, s8, v51
	v_mul_u32_u24_e32 v4, 0x300, v4
	v_lshlrev_b32_e32 v4, 2, v4
	v_lshl_add_u64 v[80:81], v[28:29], 0, v[4:5]
	v_or_b32_e32 v4, s8, v53
	v_mul_u32_u24_e32 v4, 0x300, v4
	v_lshlrev_b32_e32 v4, 2, v4
	v_lshl_add_u64 v[82:83], v[28:29], 0, v[4:5]
	v_or_b32_e32 v4, s8, v54
	v_mul_u32_u24_e32 v4, 0x300, v4
	v_lshlrev_b32_e32 v4, 2, v4
	v_lshl_add_u64 v[84:85], v[28:29], 0, v[4:5]
	v_or_b32_e32 v4, s8, v55
	v_mul_u32_u24_e32 v4, 0x300, v4
	v_lshlrev_b32_e32 v4, 2, v4
	v_lshl_add_u64 v[86:87], v[28:29], 0, v[4:5]
	v_or_b32_e32 v4, s8, v56
	v_mul_u32_u24_e32 v4, 0x300, v4
	v_lshlrev_b32_e32 v4, 2, v4
	global_load_dword v94, v[30:31], off nt
	global_load_dword v95, v[32:33], off nt
	global_load_dword v96, v[34:35], off nt
	global_load_dword v97, v[36:37], off nt
	global_load_dword v98, v[80:81], off nt
	global_load_dword v99, v[82:83], off nt
	global_load_dword v100, v[84:85], off nt
	global_load_dword v101, v[86:87], off nt
	v_lshl_add_u64 v[30:31], v[28:29], 0, v[4:5]
	v_or_b32_e32 v4, s8, v57
	v_mul_u32_u24_e32 v4, 0x300, v4
	v_lshlrev_b32_e32 v4, 2, v4
	v_lshl_add_u64 v[32:33], v[28:29], 0, v[4:5]
	v_or_b32_e32 v4, s8, v58
	v_mul_u32_u24_e32 v4, 0x300, v4
	v_lshlrev_b32_e32 v4, 2, v4
	v_lshl_add_u64 v[34:35], v[28:29], 0, v[4:5]
	v_or_b32_e32 v4, s8, v60
	v_mul_u32_u24_e32 v4, 0x300, v4
	v_lshlrev_b32_e32 v4, 2, v4
	v_lshl_add_u64 v[36:37], v[28:29], 0, v[4:5]
	v_or_b32_e32 v4, s8, v61
	v_mul_u32_u24_e32 v4, 0x300, v4
	v_lshlrev_b32_e32 v4, 2, v4
	v_lshl_add_u64 v[80:81], v[28:29], 0, v[4:5]
	v_or_b32_e32 v4, s8, v62
	v_mul_u32_u24_e32 v4, 0x300, v4
	v_lshlrev_b32_e32 v4, 2, v4
	v_lshl_add_u64 v[82:83], v[28:29], 0, v[4:5]
	v_or_b32_e32 v4, s8, v63
	v_mul_u32_u24_e32 v4, 0x300, v4
	v_lshlrev_b32_e32 v4, 2, v4
	v_lshl_add_u64 v[84:85], v[28:29], 0, v[4:5]
	v_or_b32_e32 v4, s8, v64
	v_mul_u32_u24_e32 v4, 0x300, v4
	v_lshlrev_b32_e32 v4, 2, v4
	v_lshl_add_u64 v[86:87], v[28:29], 0, v[4:5]
	v_or_b32_e32 v4, s8, v65
	v_mul_u32_u24_e32 v4, 0x300, v4
	v_lshlrev_b32_e32 v4, 2, v4
	global_load_dword v102, v[30:31], off nt
	global_load_dword v103, v[32:33], off nt
	global_load_dword v104, v[34:35], off nt
	global_load_dword v105, v[36:37], off nt
	global_load_dword v106, v[80:81], off nt
	global_load_dword v107, v[82:83], off nt
	global_load_dword v108, v[84:85], off nt
	global_load_dword v109, v[86:87], off nt
	v_lshl_add_u64 v[30:31], v[28:29], 0, v[4:5]
	v_or_b32_e32 v4, s8, v67
	v_mul_u32_u24_e32 v4, 0x300, v4
	v_lshlrev_b32_e32 v4, 2, v4
	v_lshl_add_u64 v[32:33], v[28:29], 0, v[4:5]
	v_or_b32_e32 v4, s8, v68
	v_mul_u32_u24_e32 v4, 0x300, v4
	v_lshlrev_b32_e32 v4, 2, v4
	v_lshl_add_u64 v[34:35], v[28:29], 0, v[4:5]
	v_or_b32_e32 v4, s8, v71
	v_mul_u32_u24_e32 v4, 0x300, v4
	v_lshlrev_b32_e32 v4, 2, v4
	v_lshl_add_u64 v[36:37], v[28:29], 0, v[4:5]
	v_or_b32_e32 v4, s8, v72
	v_mul_u32_u24_e32 v4, 0x300, v4
	v_lshlrev_b32_e32 v4, 2, v4
	v_lshl_add_u64 v[80:81], v[28:29], 0, v[4:5]
	v_or_b32_e32 v4, s8, v73
	v_mul_u32_u24_e32 v4, 0x300, v4
	v_lshlrev_b32_e32 v4, 2, v4
	v_lshl_add_u64 v[82:83], v[28:29], 0, v[4:5]
	v_or_b32_e32 v4, s8, v74
	v_mul_u32_u24_e32 v4, 0x300, v4
	v_lshlrev_b32_e32 v4, 2, v4
	v_lshl_add_u64 v[84:85], v[28:29], 0, v[4:5]
	v_or_b32_e32 v4, s8, v75
	v_mul_u32_u24_e32 v4, 0x300, v4
	v_lshlrev_b32_e32 v4, 2, v4
	v_lshl_add_u64 v[28:29], v[28:29], 0, v[4:5]
	global_load_dword v4, v[30:31], off nt
	global_load_dword v86, v[32:33], off nt
	global_load_dword v87, v[34:35], off nt
	global_load_dword v110, v[36:37], off nt
	global_load_dword v111, v[80:81], off nt
	global_load_dword v112, v[82:83], off nt
	global_load_dword v113, v[84:85], off nt
	global_load_dword v114, v[28:29], off nt
	v_add_u32_e32 v28, v7, v9
	s_waitcnt vmcnt(30)
; #define LAS __attribute__((address_space(3)))
; __device__ __forceinline__ unsigned cvtpk(float lo, float hi) { typedef __bf16 bf2 __attribute__((ext_vector_type(2))); f32x2 v = {lo, hi}; bf2 b = __builtin_convertvector(v, bf2); return __builtin_bit_cast(unsigned, b); }
; __device__ __forceinline__ int wrow_map(int mode, int n) {
;     if (mode == 1) { const int hd = n / 96, w = n % 96; return w < 64 ? hd * 64 + w : 512 + hd * 32 + 2 * ((w - 64) & 15) + ((w - 64) >> 4); }
; __device__ __forceinline__ void transpose_item(const float* W, int K, int N, bf16_t* WT, int mode, LAS float* scr, int item, int lane) {
;     ...
;     for (int i = 0; i < 32; ++i) { const int kk = 2 * i + (lane >> 5); scr[kk * 33 + (lane & 31)] = W[(size_t)(k0 + kk) * N + n0 + (lane & 31)]; }
;     asm volatile("s_waitcnt lgkmcnt(0)" ::: "memory");
;     const int c = lane & 7;
; #pragma unroll
;     for (int j = 0; j < 4; ++j) { const int n = (lane >> 3) + 8 * j; const LAS float* s = scr + (8 * c) * 33 + n;
;         u32x4 o; o.x = cvtpk(s[0 * 33], s[1 * 33]); o.y = cvtpk(s[2 * 33], s[3 * 33]); o.z = cvtpk(s[4 * 33], s[5 * 33]); o.w = cvtpk(s[6 * 33], s[7 * 33]);
;         *(u32x4*)(WT + (size_t)wrow_map(mode, n0 + n) * K + k0 + 8 * c) = o; }
;     asm volatile("s_waitcnt lgkmcnt(0)" ::: "memory");
	ds_write2_b32 v28, v27, v79 offset1:66
	s_waitcnt vmcnt(28)
	ds_write2_b32 v28, v88, v89 offset0:132 offset1:198
	v_add_u32_e32 v27, 0x400, v28
	s_waitcnt vmcnt(26)
	ds_write2_b32 v27, v90, v91 offset0:8 offset1:74
	v_add_u32_e32 v27, v7, v45
	s_waitcnt vmcnt(24)
	ds_write2_b32 v27, v92, v93 offset1:66
	s_waitcnt vmcnt(22)
	ds_write2_b32 v27, v94, v95 offset0:132 offset1:198
	v_add_u32_e32 v27, 0x400, v27
	s_waitcnt vmcnt(20)
	ds_write2_b32 v27, v96, v97 offset0:8 offset1:74
	v_add_u32_e32 v27, v7, v52
	s_waitcnt vmcnt(18)
	ds_write2_b32 v27, v98, v99 offset1:66
	s_waitcnt vmcnt(16)
	ds_write2_b32 v27, v100, v101 offset0:132 offset1:198
	v_add_u32_e32 v27, 0x400, v27
	s_mulk_i32 s10, 0xab
	s_bfe_u32 s17, s10, 0x70009
	s_waitcnt vmcnt(14)
	ds_write2_b32 v27, v102, v103 offset0:8 offset1:74
	v_add_u32_e32 v27, v7, v59
	s_waitcnt vmcnt(12)
	ds_write2_b32 v27, v104, v105 offset1:66
	s_waitcnt vmcnt(10)
	ds_write2_b32 v27, v106, v107 offset0:132 offset1:198
	v_add_u32_e32 v27, 0x400, v27
	s_waitcnt vmcnt(8)
	ds_write2_b32 v27, v108, v109 offset0:8 offset1:74
	v_add_u32_e32 v27, v7, v66
	s_waitcnt vmcnt(6)
	ds_write2_b32 v27, v4, v86 offset1:66
	s_waitcnt vmcnt(4)
	ds_write2_b32 v27, v87, v110 offset0:132 offset1:198
	v_add_u32_e32 v4, 0x400, v27
	s_waitcnt vmcnt(2)
	ds_write2_b32 v4, v111, v112 offset0:8 offset1:74
	s_waitcnt vmcnt(0)
	ds_write2_b32 v4, v113, v114 offset0:140 offset1:206
	s_waitcnt lgkmcnt(0)
	ds_read2_b32 v[30:31], v70 offset1:33
	ds_read2_b32 v[32:33], v70 offset0:66 offset1:99
	ds_read2_b32 v[34:35], v70 offset0:132 offset1:165
	ds_read2_b32 v[36:37], v70 offset0:198 offset1:231
	v_or_b32_e32 v4, s16, v69
	v_mul_hi_u32 v27, v4, s34
	v_mul_u32_u24_e32 v27, 0x60, v27
	v_sub_u32_e32 v27, v4, v27
	v_cmp_lt_u32_e32 vcc, 63, v27
	s_and_saveexec_b64 s[10:11], vcc
	s_xor_b64 s[10:11], exec, s[10:11]
	v_subrev_u32_e32 v4, 64, v27
	v_lshlrev_b32_e32 v27, 1, v27
	v_and_b32_e32 v27, 14, v27
	v_lshrrev_b32_e32 v4, 4, v4
	v_lshl_or_b32 v27, s17, 5, v27
	v_add3_u32 v4, v4, v27, s35
	s_andn2_saveexec_b64 s[10:11], s[10:11]
	v_lshl_or_b32 v4, s17, 6, v27
	s_or_b64 exec, exec, s[10:11]
	s_lshl_b32 s8, s8, 1
	v_lshl_add_u64 v[28:29], v[20:21], 0, s[8:9]
	s_waitcnt lgkmcnt(3)
	v_cvt_pk_bf16_f32 v30, v30, v31
	s_waitcnt lgkmcnt(2)
	v_cvt_pk_bf16_f32 v31, v32, v33
	s_waitcnt lgkmcnt(1)
	v_cvt_pk_bf16_f32 v32, v34, v35
	v_lshlrev_b64 v[34:35], 9, v[4:5]
	s_waitcnt lgkmcnt(0)
	v_cvt_pk_bf16_f32 v33, v36, v37
	v_lshl_add_u64 v[34:35], v[28:29], 0, v[34:35]
	global_store_dwordx4 v[34:35], v[30:33], off
	ds_read2_b32 v[30:31], v70 offset0:8 offset1:41
	ds_read2_b32 v[32:33], v70 offset0:74 offset1:107
	ds_read2_b32 v[34:35], v70 offset0:140 offset1:173
	ds_read2_b32 v[36:37], v70 offset0:206 offset1:239
	v_or_b32_e32 v4, s16, v76
	v_mul_hi_u32 v27, v4, s34
	v_mul_u32_u24_e32 v27, 0x60, v27
	v_sub_u32_e32 v27, v4, v27
	v_cmp_lt_u32_e32 vcc, 63, v27
	s_and_saveexec_b64 s[10:11], vcc
	s_xor_b64 s[10:11], exec, s[10:11]
	v_subrev_u32_e32 v4, 64, v27
	v_lshlrev_b32_e32 v27, 1, v27
	v_and_b32_e32 v27, 30, v27
	v_lshrrev_b32_e32 v4, 4, v4
	v_lshl_or_b32 v27, s17, 5, v27
	v_add3_u32 v4, v4, v27, s35
	s_andn2_saveexec_b64 s[10:11], s[10:11]
	v_lshl_or_b32 v4, s17, 6, v27
	s_or_b64 exec, exec, s[10:11]
	s_waitcnt lgkmcnt(3)
	v_cvt_pk_bf16_f32 v30, v30, v31
	s_waitcnt lgkmcnt(2)
	v_cvt_pk_bf16_f32 v31, v32, v33
	s_waitcnt lgkmcnt(1)
	v_cvt_pk_bf16_f32 v32, v34, v35
	v_lshlrev_b64 v[34:35], 9, v[4:5]
	s_waitcnt lgkmcnt(0)
	v_cvt_pk_bf16_f32 v33, v36, v37
	v_lshl_add_u64 v[34:35], v[28:29], 0, v[34:35]
	global_store_dwordx4 v[34:35], v[30:33], off
	ds_read2_b32 v[30:31], v70 offset0:16 offset1:49
	ds_read2_b32 v[32:33], v70 offset0:82 offset1:115
	ds_read2_b32 v[34:35], v70 offset0:148 offset1:181
	ds_read2_b32 v[36:37], v70 offset0:214 offset1:247
	v_or_b32_e32 v4, s16, v77
	v_mul_hi_u32 v27, v4, s34
	v_mul_u32_u24_e32 v27, 0x60, v27
	v_sub_u32_e32 v27, v4, v27
	v_cmp_lt_u32_e32 vcc, 63, v27
	s_and_saveexec_b64 s[10:11], vcc
	s_xor_b64 s[10:11], exec, s[10:11]
	v_subrev_u32_e32 v4, 64, v27
	v_lshlrev_b32_e32 v27, 1, v27
	v_and_b32_e32 v27, 14, v27
	v_lshrrev_b32_e32 v4, 4, v4
	v_lshl_or_b32 v27, s17, 5, v27
	v_add3_u32 v4, v4, v27, s35
	s_andn2_saveexec_b64 s[10:11], s[10:11]
	v_lshl_or_b32 v4, s17, 6, v27
	s_or_b64 exec, exec, s[10:11]
	s_waitcnt lgkmcnt(3)
	v_cvt_pk_bf16_f32 v30, v30, v31
	s_waitcnt lgkmcnt(2)
	v_cvt_pk_bf16_f32 v31, v32, v33
	s_waitcnt lgkmcnt(1)
	v_cvt_pk_bf16_f32 v32, v34, v35
	v_lshlrev_b64 v[34:35], 9, v[4:5]
	s_waitcnt lgkmcnt(0)
	v_cvt_pk_bf16_f32 v33, v36, v37
	v_lshl_add_u64 v[34:35], v[28:29], 0, v[34:35]
	global_store_dwordx4 v[34:35], v[30:33], off
	ds_read2_b32 v[30:31], v70 offset0:24 offset1:57
	ds_read2_b32 v[32:33], v70 offset0:90 offset1:123
	ds_read2_b32 v[34:35], v70 offset0:156 offset1:189
	ds_read2_b32 v[36:37], v70 offset0:222 offset1:255
	v_or_b32_e32 v4, s16, v78
	v_mul_hi_u32 v27, v4, s34
	v_mul_u32_u24_e32 v27, 0x60, v27
	v_sub_u32_e32 v27, v4, v27
	v_cmp_lt_u32_e32 vcc, 63, v27
	s_and_saveexec_b64 s[10:11], vcc
	s_xor_b64 s[10:11], exec, s[10:11]
	v_subrev_u32_e32 v4, 64, v27
	v_lshlrev_b32_e32 v27, 1, v27
	v_and_b32_e32 v27, 30, v27
	v_lshrrev_b32_e32 v4, 4, v4
	v_lshl_or_b32 v27, s17, 5, v27
	v_add3_u32 v4, v4, v27, s35
	s_andn2_saveexec_b64 s[10:11], s[10:11]
	v_lshl_or_b32 v4, s17, 6, v27
	s_or_b64 exec, exec, s[10:11]
	s_waitcnt lgkmcnt(3)
	v_cvt_pk_bf16_f32 v30, v30, v31
	s_waitcnt lgkmcnt(2)
	v_cvt_pk_bf16_f32 v31, v32, v33
	s_waitcnt lgkmcnt(1)
	v_cvt_pk_bf16_f32 v32, v34, v35
	v_lshlrev_b64 v[34:35], 9, v[4:5]
	s_waitcnt lgkmcnt(0)
	v_cvt_pk_bf16_f32 v33, v36, v37
	v_lshl_add_u64 v[28:29], v[28:29], 0, v[34:35]
	global_store_dwordx4 v[28:29], v[30:33], off
	s_waitcnt lgkmcnt(0)

; #define LAS __attribute__((address_space(3)))
; __device__ __forceinline__ void transpose_item(const float* W, int K, int N, bf16_t* WT, int mode, LAS float* scr, int item, int lane) {
;     const int nblk = N / 32, kb = item / nblk, nb = item % nblk, k0 = 64 * kb, n0 = 32 * nb;
; #pragma unroll
;     for (int i = 0; i < 32; ++i) { const int kk = 2 * i + (lane >> 5); scr[kk * 33 + (lane & 31)] = W[(size_t)(k0 + kk) * N + n0 + (lane & 31)]; }
; __device__ __forceinline__ void convert_weights(PPtr P, int li, LAS unsigned char* lds, int gw, int NGW, int wave, int lane) {
;     ...
;         if (r < I_GATE) { transpose_item(P->in[6] + (size_t)li * 1024 * 4096, 1024, 4096, Wb + W_GATE, 0, scr, r, lane); continue; } r -= I_GATE;
.LBB0_57:
	s_andn2_b64 vcc, exec, s[10:11]
	s_cbranch_vccnz .LBB0_59
	s_load_dwordx2 s[16:17], s[6:7], 0x30
	s_add_i32 s8, s38, 0xfffff9b0
	s_add_i32 s10, s20, 0xffff3600
	s_lshr_b32 s8, s8, 1
	s_and_b32 s10, s10, 0xfe0
	s_and_b32 s8, s8, 0x7fc0
	s_lshl_b32 s11, s10, 2
	s_waitcnt lgkmcnt(0)
	s_add_u32 s16, s16, s11
	s_addc_u32 s17, s17, 0
	v_lshlrev_b32_e32 v4, 2, v2
	v_lshl_add_u64 v[28:29], s[16:17], 0, v[4:5]
	v_or_b32_e32 v4, s8, v3
	v_lshlrev_b32_e32 v4, 14, v4
	v_lshl_add_u64 v[30:31], v[28:29], 0, v[4:5]
	v_or_b32_e32 v4, s8, v39
	v_lshlrev_b32_e32 v4, 14, v4
	v_lshl_add_u64 v[32:33], v[28:29], 0, v[4:5]
	v_or_b32_e32 v4, s8, v40
	v_lshlrev_b32_e32 v4, 14, v4
	v_lshl_add_u64 v[34:35], v[28:29], 0, v[4:5]
	v_or_b32_e32 v4, s8, v41
	v_lshlrev_b32_e32 v4, 14, v4
	v_lshl_add_u64 v[36:37], v[28:29], 0, v[4:5]
	v_or_b32_e32 v4, s8, v42
	v_lshlrev_b32_e32 v4, 14, v4
	v_lshl_add_u64 v[80:81], v[28:29], 0, v[4:5]
	v_or_b32_e32 v4, s8, v43
	v_lshlrev_b32_e32 v4, 14, v4
	v_lshl_add_u64 v[82:83], v[28:29], 0, v[4:5]
	v_or_b32_e32 v4, s8, v44
	v_lshlrev_b32_e32 v4, 14, v4
	v_lshl_add_u64 v[84:85], v[28:29], 0, v[4:5]
	v_or_b32_e32 v4, s8, v46
	v_lshlrev_b32_e32 v4, 14, v4
	v_lshl_add_u64 v[86:87], v[28:29], 0, v[4:5]
	v_or_b32_e32 v4, s8, v47
	v_lshlrev_b32_e32 v4, 14, v4
	global_load_dword v27, v[30:31], off nt
	global_load_dword v79, v[32:33], off nt
	global_load_dword v88, v[34:35], off nt
	global_load_dword v89, v[36:37], off nt
	global_load_dword v90, v[80:81], off nt
	global_load_dword v91, v[82:83], off nt
	global_load_dword v92, v[84:85], off nt
	global_load_dword v93, v[86:87], off nt
	v_lshl_add_u64 v[30:31], v[28:29], 0, v[4:5]
	v_or_b32_e32 v4, s8, v48
	v_lshlrev_b32_e32 v4, 14, v4
	v_lshl_add_u64 v[32:33], v[28:29], 0, v[4:5]
	v_or_b32_e32 v4, s8, v49
	v_lshlrev_b32_e32 v4, 14, v4
	v_lshl_add_u64 v[34:35], v[28:29], 0, v[4:5]
	v_or_b32_e32 v4, s8, v50
	v_lshlrev_b32_e32 v4, 14, v4
	v_lshl_add_u64 v[36:37], v[28:29], 0, v[4:5]
	v_or_b32_e32 v4, s8, v51
	v_lshlrev_b32_e32 v4, 14, v4
	v_lshl_add_u64 v[80:81], v[28:29], 0, v[4:5]
	v_or_b32_e32 v4, s8, v53
	v_lshlrev_b32_e32 v4, 14, v4
	v_lshl_add_u64 v[82:83], v[28:29], 0, v[4:5]
	v_or_b32_e32 v4, s8, v54
	v_lshlrev_b32_e32 v4, 14, v4
	v_lshl_add_u64 v[84:85], v[28:29], 0, v[4:5]
	v_or_b32_e32 v4, s8, v55
	v_lshlrev_b32_e32 v4, 14, v4
	v_lshl_add_u64 v[86:87], v[28:29], 0, v[4:5]
	v_or_b32_e32 v4, s8, v56
	v_lshlrev_b32_e32 v4, 14, v4
	global_load_dword v94, v[30:31], off nt
	global_load_dword v95, v[32:33], off nt
	global_load_dword v96, v[34:35], off nt
	global_load_dword v97, v[36:37], off nt
	global_load_dword v98, v[80:81], off nt
	global_load_dword v99, v[82:83], off nt
	global_load_dword v100, v[84:85], off nt
	global_load_dword v101, v[86:87], off nt
	v_lshl_add_u64 v[30:31], v[28:29], 0, v[4:5]
	v_or_b32_e32 v4, s8, v57
	v_lshlrev_b32_e32 v4, 14, v4
	v_lshl_add_u64 v[32:33], v[28:29], 0, v[4:5]
	v_or_b32_e32 v4, s8, v58
	v_lshlrev_b32_e32 v4, 14, v4
	v_lshl_add_u64 v[34:35], v[28:29], 0, v[4:5]
	v_or_b32_e32 v4, s8, v60
	v_lshlrev_b32_e32 v4, 14, v4
	v_lshl_add_u64 v[36:37], v[28:29], 0, v[4:5]
	v_or_b32_e32 v4, s8, v61
	v_lshlrev_b32_e32 v4, 14, v4
	v_lshl_add_u64 v[80:81], v[28:29], 0, v[4:5]
	v_or_b32_e32 v4, s8, v62
	v_lshlrev_b32_e32 v4, 14, v4
	v_lshl_add_u64 v[82:83], v[28:29], 0, v[4:5]
	v_or_b32_e32 v4, s8, v63
	v_lshlrev_b32_e32 v4, 14, v4
	v_lshl_add_u64 v[84:85], v[28:29], 0, v[4:5]
	v_or_b32_e32 v4, s8, v64
	v_lshlrev_b32_e32 v4, 14, v4
	v_lshl_add_u64 v[86:87], v[28:29], 0, v[4:5]
	v_or_b32_e32 v4, s8, v65
	v_lshlrev_b32_e32 v4, 14, v4
	global_load_dword v102, v[30:31], off nt
	global_load_dword v103, v[32:33], off nt
	global_load_dword v104, v[34:35], off nt
	global_load_dword v105, v[36:37], off nt
	global_load_dword v106, v[80:81], off nt
	global_load_dword v107, v[82:83], off nt
	global_load_dword v108, v[84:85], off nt
	global_load_dword v109, v[86:87], off nt
	v_lshl_add_u64 v[30:31], v[28:29], 0, v[4:5]
	v_or_b32_e32 v4, s8, v67
	v_lshlrev_b32_e32 v4, 14, v4
	v_lshl_add_u64 v[32:33], v[28:29], 0, v[4:5]
	v_or_b32_e32 v4, s8, v68
	v_lshlrev_b32_e32 v4, 14, v4
	v_lshl_add_u64 v[34:35], v[28:29], 0, v[4:5]
	v_or_b32_e32 v4, s8, v71
	v_lshlrev_b32_e32 v4, 14, v4
	v_lshl_add_u64 v[36:37], v[28:29], 0, v[4:5]
	v_or_b32_e32 v4, s8, v72
	v_lshlrev_b32_e32 v4, 14, v4
	v_lshl_add_u64 v[80:81], v[28:29], 0, v[4:5]
	v_or_b32_e32 v4, s8, v73
	v_lshlrev_b32_e32 v4, 14, v4
	v_lshl_add_u64 v[82:83], v[28:29], 0, v[4:5]
	v_or_b32_e32 v4, s8, v74
	v_lshlrev_b32_e32 v4, 14, v4
	v_lshl_add_u64 v[84:85], v[28:29], 0, v[4:5]
	v_or_b32_e32 v4, s8, v75
	v_lshlrev_b32_e32 v4, 14, v4
	v_lshl_add_u64 v[28:29], v[28:29], 0, v[4:5]
	global_load_dword v4, v[30:31], off nt
	global_load_dword v86, v[32:33], off nt
	global_load_dword v87, v[34:35], off nt
	global_load_dword v110, v[36:37], off nt
	global_load_dword v111, v[80:81], off nt
	global_load_dword v112, v[82:83], off nt
	global_load_dword v113, v[84:85], off nt
	global_load_dword v114, v[28:29], off nt
	v_add_u32_e32 v28, v7, v9
	s_waitcnt vmcnt(30)
; #define LAS __attribute__((address_space(3)))
; __device__ __forceinline__ unsigned cvtpk(float lo, float hi) { typedef __bf16 bf2 __attribute__((ext_vector_type(2))); f32x2 v = {lo, hi}; bf2 b = __builtin_convertvector(v, bf2); return __builtin_bit_cast(unsigned, b); }
; __device__ __forceinline__ void transpose_item(const float* W, int K, int N, bf16_t* WT, int mode, LAS float* scr, int item, int lane) {
;     ...
;     for (int i = 0; i < 32; ++i) { const int kk = 2 * i + (lane >> 5); scr[kk * 33 + (lane & 31)] = W[(size_t)(k0 + kk) * N + n0 + (lane & 31)]; }
;     asm volatile("s_waitcnt lgkmcnt(0)" ::: "memory");
;     const int c = lane & 7;
; #pragma unroll
;     for (int j = 0; j < 4; ++j) { const int n = (lane >> 3) + 8 * j; const LAS float* s = scr + (8 * c) * 33 + n;
;         u32x4 o; o.x = cvtpk(s[0 * 33], s[1 * 33]); o.y = cvtpk(s[2 * 33], s[3 * 33]); o.z = cvtpk(s[4 * 33], s[5 * 33]); o.w = cvtpk(s[6 * 33], s[7 * 33]);
;         *(u32x4*)(WT + (size_t)wrow_map(mode, n0 + n) * K + k0 + 8 * c) = o; }
;     asm volatile("s_waitcnt lgkmcnt(0)" ::: "memory");
	ds_write2_b32 v28, v27, v79 offset1:66
	s_waitcnt vmcnt(28)
	ds_write2_b32 v28, v88, v89 offset0:132 offset1:198
	v_add_u32_e32 v27, 0x400, v28
	s_waitcnt vmcnt(26)
	ds_write2_b32 v27, v90, v91 offset0:8 offset1:74
	v_add_u32_e32 v27, v7, v45
	s_waitcnt vmcnt(24)
	ds_write2_b32 v27, v92, v93 offset1:66
	s_waitcnt vmcnt(22)
	ds_write2_b32 v27, v94, v95 offset0:132 offset1:198
	v_add_u32_e32 v27, 0x400, v27
	s_waitcnt vmcnt(20)
	ds_write2_b32 v27, v96, v97 offset0:8 offset1:74
	v_add_u32_e32 v27, v7, v52
	s_waitcnt vmcnt(18)
	ds_write2_b32 v27, v98, v99 offset1:66
	s_waitcnt vmcnt(16)
	ds_write2_b32 v27, v100, v101 offset0:132 offset1:198
	v_add_u32_e32 v27, 0x400, v27
	s_lshl_b32 s8, s8, 1
	v_lshl_add_u64 v[90:91], v[22:23], 0, s[8:9]
	s_waitcnt vmcnt(14)
	ds_write2_b32 v27, v102, v103 offset0:8 offset1:74
	v_add_u32_e32 v27, v7, v59
	s_waitcnt vmcnt(12)
	ds_write2_b32 v27, v104, v105 offset1:66
	s_waitcnt vmcnt(10)
	ds_write2_b32 v27, v106, v107 offset0:132 offset1:198
	v_add_u32_e32 v27, 0x400, v27
	s_waitcnt vmcnt(8)
	ds_write2_b32 v27, v108, v109 offset0:8 offset1:74
	v_add_u32_e32 v27, v7, v66
	s_waitcnt vmcnt(6)
	ds_write2_b32 v27, v4, v86 offset1:66
	s_waitcnt vmcnt(4)
	ds_write2_b32 v27, v87, v110 offset0:132 offset1:198
	v_add_u32_e32 v4, 0x400, v27
	s_waitcnt vmcnt(2)
	ds_write2_b32 v4, v111, v112 offset0:8 offset1:74
	s_waitcnt vmcnt(0)
	ds_write2_b32 v4, v113, v114 offset0:140 offset1:206
	s_waitcnt lgkmcnt(0)
	ds_read2_b32 v[32:33], v70 offset0:33 offset1:41
	ds_read2_b32 v[34:35], v70 offset1:8
	ds_read2_b32 v[36:37], v70 offset0:66 offset1:74
	ds_read2_b32 v[80:81], v70 offset0:99 offset1:107
	ds_read2_b32 v[82:83], v70 offset0:132 offset1:140
	ds_read2_b32 v[84:85], v70 offset0:165 offset1:173
	ds_read2_b32 v[86:87], v70 offset0:198 offset1:206
	ds_read2_b32 v[88:89], v70 offset0:231 offset1:239
	v_or_b32_e32 v4, s10, v69
	v_lshlrev_b32_e32 v4, 11, v4
	s_waitcnt lgkmcnt(6)
	v_cvt_pk_bf16_f32 v28, v34, v32
	s_waitcnt lgkmcnt(4)
	v_cvt_pk_bf16_f32 v29, v36, v80
	s_waitcnt lgkmcnt(2)
	v_cvt_pk_bf16_f32 v30, v82, v84
	s_waitcnt lgkmcnt(0)
	v_cvt_pk_bf16_f32 v31, v86, v88
	v_lshl_add_u64 v[92:93], v[90:91], 0, v[4:5]
	global_store_dwordx4 v[92:93], v[28:31], off
	v_or_b32_e32 v4, s10, v76
	v_lshlrev_b32_e32 v4, 11, v4
	v_cvt_pk_bf16_f32 v28, v35, v33
	v_cvt_pk_bf16_f32 v29, v37, v81
	v_cvt_pk_bf16_f32 v30, v83, v85
	v_cvt_pk_bf16_f32 v31, v87, v89
	ds_read2_b32 v[34:35], v70 offset0:49 offset1:57
	ds_read2_b32 v[36:37], v70 offset0:16 offset1:24
	ds_read2_b32 v[80:81], v70 offset0:82 offset1:90
	ds_read2_b32 v[82:83], v70 offset0:115 offset1:123
	ds_read2_b32 v[84:85], v70 offset0:148 offset1:156
	ds_read2_b32 v[86:87], v70 offset0:181 offset1:189
	ds_read2_b32 v[88:89], v70 offset0:214 offset1:222
	ds_read2_b32 v[92:93], v70 offset0:247 offset1:255
	v_lshl_add_u64 v[32:33], v[90:91], 0, v[4:5]
	v_or_b32_e32 v4, s10, v77
	v_lshlrev_b32_e32 v4, 11, v4
	global_store_dwordx4 v[32:33], v[28:31], off
	v_lshl_add_u64 v[32:33], v[90:91], 0, v[4:5]
	v_or_b32_e32 v4, s10, v78
	s_waitcnt lgkmcnt(6)
	v_cvt_pk_bf16_f32 v28, v36, v34
	s_waitcnt lgkmcnt(4)
	v_cvt_pk_bf16_f32 v29, v80, v82
	s_waitcnt lgkmcnt(2)
	v_cvt_pk_bf16_f32 v30, v84, v86
	s_waitcnt lgkmcnt(0)
	v_cvt_pk_bf16_f32 v31, v88, v92
	v_lshlrev_b32_e32 v4, 11, v4
	global_store_dwordx4 v[32:33], v[28:31], off
	v_lshl_add_u64 v[32:33], v[90:91], 0, v[4:5]
	s_nop 0
	v_cvt_pk_bf16_f32 v28, v37, v35
	v_cvt_pk_bf16_f32 v29, v81, v83
	v_cvt_pk_bf16_f32 v30, v85, v87
	v_cvt_pk_bf16_f32 v31, v89, v93
	global_store_dwordx4 v[32:33], v[28:31], off
	s_waitcnt lgkmcnt(0)

; #define LAS __attribute__((address_space(3)))
; __device__ __forceinline__ void transpose_item(const float* W, int K, int N, bf16_t* WT, int mode, LAS float* scr, int item, int lane) {
;     const int nblk = N / 32, kb = item / nblk, nb = item % nblk, k0 = 64 * kb, n0 = 32 * nb;
; #pragma unroll
;     for (int i = 0; i < 32; ++i) { const int kk = 2 * i + (lane >> 5); scr[kk * 33 + (lane & 31)] = W[(size_t)(k0 + kk) * N + n0 + (lane & 31)]; }
; __device__ __forceinline__ void convert_weights(PPtr P, int li, LAS unsigned char* lds, int gw, int NGW, int wave, int lane) {
;     ...
;         if (r < I_IN) { transpose_item(P->in[5] + (size_t)li * 1024 * 3232, 1024, 3232, Wb + W_IN, 0, scr, r, lane); continue; } r -= I_IN;
.LBB0_60:
	s_andn2_b64 vcc, exec, s[10:11]
	s_cbranch_vccnz .LBB0_13
	s_mul_hi_i32 s8, s38, 0x288df0cb
	s_lshr_b32 s10, s8, 31
	s_ashr_i32 s8, s8, 4
	s_load_dwordx2 s[40:41], s[6:7], 0x28
	s_add_i32 s8, s8, s10
	s_lshl_b32 s10, s8, 6
	s_mulk_i32 s8, 0xf360
	s_add_i32 s16, s20, s8
	s_ashr_i32 s17, s16, 31
	s_lshl_b64 s[42:43], s[16:17], 2
	s_waitcnt lgkmcnt(0)
	s_add_u32 s40, s40, s42
	s_addc_u32 s41, s41, s43
	v_lshlrev_b32_e32 v4, 2, v2
	v_lshl_add_u64 v[28:29], s[40:41], 0, v[4:5]
	v_or_b32_e32 v4, s10, v3
	v_mad_i64_i32 v[30:31], s[40:41], v4, s37, v[28:29]
	v_or_b32_e32 v4, s10, v39
	v_mad_i64_i32 v[32:33], s[40:41], v4, s37, v[28:29]
	v_or_b32_e32 v4, s10, v40
	v_mad_i64_i32 v[34:35], s[40:41], v4, s37, v[28:29]
	v_or_b32_e32 v4, s10, v41
	v_mad_i64_i32 v[36:37], s[40:41], v4, s37, v[28:29]
	v_or_b32_e32 v4, s10, v42
	v_mad_i64_i32 v[80:81], s[40:41], v4, s37, v[28:29]
	v_or_b32_e32 v4, s10, v43
	v_mad_i64_i32 v[82:83], s[40:41], v4, s37, v[28:29]
	v_or_b32_e32 v4, s10, v44
	v_mad_i64_i32 v[84:85], s[40:41], v4, s37, v[28:29]
	v_or_b32_e32 v4, s10, v46
	v_mad_i64_i32 v[86:87], s[40:41], v4, s37, v[28:29]
	global_load_dword v4, v[30:31], off nt
	global_load_dword v27, v[32:33], off nt
	global_load_dword v79, v[34:35], off nt
	global_load_dword v90, v[36:37], off nt
	global_load_dword v91, v[80:81], off nt
	global_load_dword v92, v[82:83], off nt
	global_load_dword v93, v[84:85], off nt
	global_load_dword v94, v[86:87], off nt
	v_or_b32_e32 v30, s10, v47
	v_mad_i64_i32 v[30:31], s[40:41], v30, s37, v[28:29]
	v_or_b32_e32 v32, s10, v48
	v_or_b32_e32 v34, s10, v49
	v_or_b32_e32 v36, s10, v50
	v_or_b32_e32 v80, s10, v51
	v_or_b32_e32 v82, s10, v53
	v_or_b32_e32 v84, s10, v54
	v_or_b32_e32 v86, s10, v55
	v_mad_i64_i32 v[32:33], s[40:41], v32, s37, v[28:29]
	v_mad_i64_i32 v[34:35], s[40:41], v34, s37, v[28:29]
	v_mad_i64_i32 v[36:37], s[40:41], v36, s37, v[28:29]
	v_mad_i64_i32 v[80:81], s[40:41], v80, s37, v[28:29]
	v_mad_i64_i32 v[82:83], s[40:41], v82, s37, v[28:29]
	v_mad_i64_i32 v[84:85], s[40:41], v84, s37, v[28:29]
	v_mad_i64_i32 v[86:87], s[40:41], v86, s37, v[28:29]
	global_load_dword v96, v[30:31], off nt
	global_load_dword v97, v[32:33], off nt
	global_load_dword v98, v[34:35], off nt
	global_load_dword v99, v[36:37], off nt
	global_load_dword v100, v[80:81], off nt
	global_load_dword v101, v[82:83], off nt
	global_load_dword v102, v[84:85], off nt
	global_load_dword v103, v[86:87], off nt
	v_or_b32_e32 v88, s10, v56
	v_or_b32_e32 v95, s10, v57
	v_mad_i64_i32 v[88:89], s[40:41], v88, s37, v[28:29]
	v_mad_i64_i32 v[30:31], s[40:41], v95, s37, v[28:29]
	v_or_b32_e32 v32, s10, v58
	v_or_b32_e32 v34, s10, v60
	v_or_b32_e32 v36, s10, v61
	v_or_b32_e32 v80, s10, v62
	v_or_b32_e32 v82, s10, v63
	v_or_b32_e32 v84, s10, v64
	v_mad_i64_i32 v[32:33], s[40:41], v32, s37, v[28:29]
	v_mad_i64_i32 v[34:35], s[40:41], v34, s37, v[28:29]
	v_mad_i64_i32 v[36:37], s[40:41], v36, s37, v[28:29]
	v_mad_i64_i32 v[80:81], s[40:41], v80, s37, v[28:29]
	v_mad_i64_i32 v[82:83], s[40:41], v82, s37, v[28:29]
	v_mad_i64_i32 v[84:85], s[40:41], v84, s37, v[28:29]
	global_load_dword v86, v[88:89], off nt
	global_load_dword v87, v[30:31], off nt
	global_load_dword v95, v[32:33], off nt
	global_load_dword v104, v[34:35], off nt
	global_load_dword v105, v[36:37], off nt
	global_load_dword v106, v[80:81], off nt
	global_load_dword v107, v[82:83], off nt
	global_load_dword v108, v[84:85], off nt
	v_or_b32_e32 v30, s10, v65
	v_mad_i64_i32 v[30:31], s[40:41], v30, s37, v[28:29]
	v_or_b32_e32 v32, s10, v67
	v_or_b32_e32 v34, s10, v68
	v_or_b32_e32 v36, s10, v71
	v_or_b32_e32 v80, s10, v72
	v_or_b32_e32 v82, s10, v73
	v_or_b32_e32 v84, s10, v74
	v_or_b32_e32 v88, s10, v75
	v_mad_i64_i32 v[32:33], s[40:41], v32, s37, v[28:29]
	v_mad_i64_i32 v[34:35], s[40:41], v34, s37, v[28:29]
	v_mad_i64_i32 v[36:37], s[40:41], v36, s37, v[28:29]
	v_mad_i64_i32 v[80:81], s[40:41], v80, s37, v[28:29]
	v_mad_i64_i32 v[82:83], s[40:41], v82, s37, v[28:29]
	v_mad_i64_i32 v[84:85], s[40:41], v84, s37, v[28:29]
	v_mad_i64_i32 v[28:29], s[40:41], v88, s37, v[28:29]
	global_load_dword v88, v[30:31], off nt
	global_load_dword v89, v[32:33], off nt
	global_load_dword v109, v[34:35], off nt
	global_load_dword v110, v[36:37], off nt
	global_load_dword v111, v[80:81], off nt
	global_load_dword v112, v[82:83], off nt
	global_load_dword v113, v[84:85], off nt
	global_load_dword v114, v[28:29], off nt
	v_add_u32_e32 v28, v7, v9
	v_add_u32_e32 v29, v7, v45
	v_add_u32_e32 v30, 0x400, v28
	v_add_u32_e32 v31, 0x400, v29
	s_waitcnt vmcnt(30)
; #define LAS __attribute__((address_space(3)))
; __device__ __forceinline__ unsigned cvtpk(float lo, float hi) { typedef __bf16 bf2 __attribute__((ext_vector_type(2))); f32x2 v = {lo, hi}; bf2 b = __builtin_convertvector(v, bf2); return __builtin_bit_cast(unsigned, b); }
; __device__ __forceinline__ void transpose_item(const float* W, int K, int N, bf16_t* WT, int mode, LAS float* scr, int item, int lane) {
;     ...
;     for (int i = 0; i < 32; ++i) { const int kk = 2 * i + (lane >> 5); scr[kk * 33 + (lane & 31)] = W[(size_t)(k0 + kk) * N + n0 + (lane & 31)]; }
;     asm volatile("s_waitcnt lgkmcnt(0)" ::: "memory");
;     const int c = lane & 7;
; #pragma unroll
;     for (int j = 0; j < 4; ++j) { const int n = (lane >> 3) + 8 * j; const LAS float* s = scr + (8 * c) * 33 + n;
;         u32x4 o; o.x = cvtpk(s[0 * 33], s[1 * 33]); o.y = cvtpk(s[2 * 33], s[3 * 33]); o.z = cvtpk(s[4 * 33], s[5 * 33]); o.w = cvtpk(s[6 * 33], s[7 * 33]);
;         *(u32x4*)(WT + (size_t)wrow_map(mode, n0 + n) * K + k0 + 8 * c) = o; }
;     asm volatile("s_waitcnt lgkmcnt(0)" ::: "memory");
	ds_write2_b32 v28, v4, v27 offset1:66
	s_waitcnt vmcnt(28)
	ds_write2_b32 v28, v79, v90 offset0:132 offset1:198
	s_waitcnt vmcnt(26)
	ds_write2_b32 v30, v91, v92 offset0:8 offset1:74
	s_waitcnt vmcnt(24)
	ds_write2_b32 v29, v93, v94 offset1:66
	s_waitcnt vmcnt(22)
	ds_write2_b32 v29, v96, v97 offset0:132 offset1:198
	s_waitcnt vmcnt(20)
	ds_write2_b32 v31, v98, v99 offset0:8 offset1:74
	v_add_u32_e32 v4, v7, v52
	s_waitcnt vmcnt(18)
	ds_write2_b32 v4, v100, v101 offset1:66
	s_waitcnt vmcnt(16)
	ds_write2_b32 v4, v102, v103 offset0:132 offset1:198
	v_add_u32_e32 v4, 0x400, v4
	v_add_u32_e32 v90, s16, v69
	s_ashr_i32 s11, s10, 31
	v_ashrrev_i32_e32 v91, 31, v90
	v_lshl_add_u64 v[92:93], s[10:11], 1, v[24:25]
	s_waitcnt vmcnt(14)
	ds_write2_b32 v4, v86, v87 offset0:8 offset1:74
	v_add_u32_e32 v4, v7, v59
	s_waitcnt vmcnt(12)
	ds_write2_b32 v4, v95, v104 offset1:66
	s_waitcnt vmcnt(10)
	ds_write2_b32 v4, v105, v106 offset0:132 offset1:198
	v_add_u32_e32 v4, 0x400, v4
	s_waitcnt vmcnt(8)
	ds_write2_b32 v4, v107, v108 offset0:8 offset1:74
	v_add_u32_e32 v4, v7, v66
	s_waitcnt vmcnt(6)
	ds_write2_b32 v4, v88, v89 offset1:66
	s_waitcnt vmcnt(4)
	ds_write2_b32 v4, v109, v110 offset0:132 offset1:198
	v_add_u32_e32 v4, 0x400, v4
	s_waitcnt vmcnt(2)
	ds_write2_b32 v4, v111, v112 offset0:8 offset1:74
	s_waitcnt vmcnt(0)
	ds_write2_b32 v4, v113, v114 offset0:140 offset1:206
	s_waitcnt lgkmcnt(0)
	ds_read2_b32 v[32:33], v70 offset0:33 offset1:41
	ds_read2_b32 v[34:35], v70 offset1:8
	ds_read2_b32 v[36:37], v70 offset0:66 offset1:74
	ds_read2_b32 v[80:81], v70 offset0:99 offset1:107
	ds_read2_b32 v[82:83], v70 offset0:132 offset1:140
	ds_read2_b32 v[84:85], v70 offset0:165 offset1:173
	ds_read2_b32 v[86:87], v70 offset0:198 offset1:206
	ds_read2_b32 v[88:89], v70 offset0:231 offset1:239
	v_lshlrev_b64 v[94:95], 11, v[90:91]
	s_waitcnt lgkmcnt(6)
	v_cvt_pk_bf16_f32 v28, v34, v32
	s_waitcnt lgkmcnt(4)
	v_cvt_pk_bf16_f32 v29, v36, v80
	s_waitcnt lgkmcnt(2)
	v_cvt_pk_bf16_f32 v30, v82, v84
	s_waitcnt lgkmcnt(0)
	v_cvt_pk_bf16_f32 v31, v86, v88
	v_lshl_add_u64 v[94:95], v[92:93], 0, v[94:95]
	v_add_u32_e32 v32, 8, v90
	global_store_dwordx4 v[94:95], v[28:31], off
	s_nop 1
	v_cvt_pk_bf16_f32 v28, v35, v33
	v_ashrrev_i32_e32 v33, 31, v32
	v_cvt_pk_bf16_f32 v29, v37, v81
	v_cvt_pk_bf16_f32 v30, v83, v85
	v_cvt_pk_bf16_f32 v31, v87, v89
	v_lshlrev_b64 v[32:33], 11, v[32:33]
	ds_read2_b32 v[34:35], v70 offset0:49 offset1:57
	ds_read2_b32 v[36:37], v70 offset0:16 offset1:24
	ds_read2_b32 v[80:81], v70 offset0:82 offset1:90
	ds_read2_b32 v[82:83], v70 offset0:115 offset1:123
	ds_read2_b32 v[84:85], v70 offset0:148 offset1:156
	ds_read2_b32 v[86:87], v70 offset0:181 offset1:189
	ds_read2_b32 v[88:89], v70 offset0:214 offset1:222
	ds_read2_b32 v[94:95], v70 offset0:247 offset1:255
	v_lshl_add_u64 v[32:33], v[92:93], 0, v[32:33]
	global_store_dwordx4 v[32:33], v[28:31], off
	v_add_u32_e32 v32, 16, v90
	v_ashrrev_i32_e32 v33, 31, v32
	v_lshlrev_b64 v[32:33], 11, v[32:33]
	s_waitcnt lgkmcnt(6)
	v_cvt_pk_bf16_f32 v28, v36, v34
	s_waitcnt lgkmcnt(4)
	v_cvt_pk_bf16_f32 v29, v80, v82
	s_waitcnt lgkmcnt(2)
	v_cvt_pk_bf16_f32 v30, v84, v86
	s_waitcnt lgkmcnt(0)
	v_cvt_pk_bf16_f32 v31, v88, v94
	v_lshl_add_u64 v[32:33], v[92:93], 0, v[32:33]
	global_store_dwordx4 v[32:33], v[28:31], off
	v_add_u32_e32 v32, 24, v90
	v_ashrrev_i32_e32 v33, 31, v32
	v_lshlrev_b64 v[32:33], 11, v[32:33]
	v_cvt_pk_bf16_f32 v28, v37, v35
	v_cvt_pk_bf16_f32 v29, v81, v83
	v_cvt_pk_bf16_f32 v30, v85, v87
	v_cvt_pk_bf16_f32 v31, v89, v95
	v_lshl_add_u64 v[32:33], v[92:93], 0, v[32:33]
	global_store_dwordx4 v[32:33], v[28:31], off
	s_waitcnt lgkmcnt(0)
	s_branch .LBB0_13

; #define LAS __attribute__((address_space(3)))
; __device__ __forceinline__ void transpose_item(const float* W, int K, int N, bf16_t* WT, int mode, LAS float* scr, int item, int lane) {
;     const int nblk = N / 32, kb = item / nblk, nb = item % nblk, k0 = 64 * kb, n0 = 32 * nb;
; #pragma unroll
;     for (int i = 0; i < 32; ++i) { const int kk = 2 * i + (lane >> 5); scr[kk * 33 + (lane & 31)] = W[(size_t)(k0 + kk) * N + n0 + (lane & 31)]; }
; __device__ __forceinline__ void convert_weights(PPtr P, int li, LAS unsigned char* lds, int gw, int NGW, int wave, int lane) {
;     ...
;         transpose_item(P->in[33] + (size_t)li * 4096 * 1024, 4096, 1024, Wb + W_F2, 0, scr, r, lane);
.LBB0_1445:
	s_cmpk_gt_i32 s48, 0x64f
	s_mov_b64 s[36:37], -1
	s_cbranch_scc0 .LBB0_1491
	s_cmpk_gt_u32 s48, 0xe4f
	s_cbranch_scc0 .LBB0_1488
	s_cmpk_gt_u32 s48, 0xeaf
	s_cbranch_scc0 .LBB0_1469
	s_cmpk_gt_u32 s48, 0xeef
	s_cbranch_scc0 .LBB0_1466
	s_cmpk_gt_u32 s48, 0xfef
	s_cbranch_scc0 .LBB0_1463
	s_cmpk_gt_u32 s48, 0x13ef
	s_cbranch_scc0 .LBB0_1460
	s_cmpk_gt_u32 s48, 0x15ef
	s_cbranch_scc0 .LBB0_1457
	s_cmpk_gt_u32 s48, 0x1def
	s_cbranch_scc0 .LBB0_1454
	s_load_dwordx2 s[38:39], s[6:7], 0x108
	s_add_i32 s36, s41, 0xfffc4200
	s_and_b32 s36, s36, 0x3e0
	s_and_b32 s8, s43, 0x1ffc0
	s_lshl_b32 s37, s36, 2
	s_waitcnt lgkmcnt(0)
	s_add_u32 s38, s38, s37
	s_addc_u32 s39, s39, 0
	v_lshlrev_b32_e32 v4, 2, v2
	v_lshl_add_u64 v[24:25], s[38:39], 0, v[4:5]
	v_or_b32_e32 v4, s8, v3
	v_lshl_add_u64 v[24:25], v[24:25], 0, s[10:11]
	v_lshlrev_b32_e32 v4, 12, v4
	v_lshl_add_u64 v[26:27], v[24:25], 0, v[4:5]
	v_or_b32_e32 v4, s8, v37
	v_lshlrev_b32_e32 v4, 12, v4
	v_lshl_add_u64 v[28:29], v[24:25], 0, v[4:5]
	v_or_b32_e32 v4, s8, v38
	v_lshlrev_b32_e32 v4, 12, v4
	v_lshl_add_u64 v[30:31], v[24:25], 0, v[4:5]
	v_or_b32_e32 v4, s8, v39
	v_lshlrev_b32_e32 v4, 12, v4
	v_lshl_add_u64 v[32:33], v[24:25], 0, v[4:5]
	v_or_b32_e32 v4, s8, v40
	v_lshlrev_b32_e32 v4, 12, v4
	v_lshl_add_u64 v[78:79], v[24:25], 0, v[4:5]
	v_or_b32_e32 v4, s8, v41
	v_lshlrev_b32_e32 v4, 12, v4
	v_lshl_add_u64 v[80:81], v[24:25], 0, v[4:5]
	v_or_b32_e32 v4, s8, v42
	v_lshlrev_b32_e32 v4, 12, v4
	v_lshl_add_u64 v[82:83], v[24:25], 0, v[4:5]
	v_or_b32_e32 v4, s8, v44
	v_lshlrev_b32_e32 v4, 12, v4
	v_lshl_add_u64 v[84:85], v[24:25], 0, v[4:5]
	v_or_b32_e32 v4, s8, v45
	v_lshlrev_b32_e32 v4, 12, v4
	global_load_dword v23, v[26:27], off nt
	global_load_dword v77, v[28:29], off nt
	global_load_dword v86, v[30:31], off nt
	global_load_dword v87, v[32:33], off nt
	global_load_dword v88, v[78:79], off nt
	global_load_dword v89, v[80:81], off nt
	global_load_dword v90, v[82:83], off nt
	global_load_dword v91, v[84:85], off nt
	v_lshl_add_u64 v[26:27], v[24:25], 0, v[4:5]
	v_or_b32_e32 v4, s8, v46
	v_lshlrev_b32_e32 v4, 12, v4
	v_lshl_add_u64 v[28:29], v[24:25], 0, v[4:5]
	v_or_b32_e32 v4, s8, v47
	v_lshlrev_b32_e32 v4, 12, v4
	v_lshl_add_u64 v[30:31], v[24:25], 0, v[4:5]
	v_or_b32_e32 v4, s8, v48
	v_lshlrev_b32_e32 v4, 12, v4
	v_lshl_add_u64 v[32:33], v[24:25], 0, v[4:5]
	v_or_b32_e32 v4, s8, v49
	v_lshlrev_b32_e32 v4, 12, v4
	v_lshl_add_u64 v[78:79], v[24:25], 0, v[4:5]
	v_or_b32_e32 v4, s8, v51
	v_lshlrev_b32_e32 v4, 12, v4
	v_lshl_add_u64 v[80:81], v[24:25], 0, v[4:5]
	v_or_b32_e32 v4, s8, v52
	v_lshlrev_b32_e32 v4, 12, v4
	v_lshl_add_u64 v[82:83], v[24:25], 0, v[4:5]
	v_or_b32_e32 v4, s8, v53
	v_lshlrev_b32_e32 v4, 12, v4
	v_lshl_add_u64 v[84:85], v[24:25], 0, v[4:5]
	v_or_b32_e32 v4, s8, v54
	v_lshlrev_b32_e32 v4, 12, v4
	global_load_dword v92, v[26:27], off nt
	global_load_dword v93, v[28:29], off nt
	global_load_dword v94, v[30:31], off nt
	global_load_dword v95, v[32:33], off nt
	global_load_dword v96, v[78:79], off nt
	global_load_dword v97, v[80:81], off nt
	global_load_dword v98, v[82:83], off nt
	global_load_dword v99, v[84:85], off nt
	v_lshl_add_u64 v[26:27], v[24:25], 0, v[4:5]
	v_or_b32_e32 v4, s8, v55
	v_lshlrev_b32_e32 v4, 12, v4
	v_lshl_add_u64 v[28:29], v[24:25], 0, v[4:5]
	v_or_b32_e32 v4, s8, v56
	v_lshlrev_b32_e32 v4, 12, v4
	v_lshl_add_u64 v[30:31], v[24:25], 0, v[4:5]
	v_or_b32_e32 v4, s8, v58
	v_lshlrev_b32_e32 v4, 12, v4
	v_lshl_add_u64 v[32:33], v[24:25], 0, v[4:5]
	v_or_b32_e32 v4, s8, v59
	v_lshlrev_b32_e32 v4, 12, v4
	v_lshl_add_u64 v[78:79], v[24:25], 0, v[4:5]
	v_or_b32_e32 v4, s8, v60
	v_lshlrev_b32_e32 v4, 12, v4
	v_lshl_add_u64 v[80:81], v[24:25], 0, v[4:5]
	v_or_b32_e32 v4, s8, v61
	v_lshlrev_b32_e32 v4, 12, v4
	v_lshl_add_u64 v[82:83], v[24:25], 0, v[4:5]
	v_or_b32_e32 v4, s8, v62
	v_lshlrev_b32_e32 v4, 12, v4
	v_lshl_add_u64 v[84:85], v[24:25], 0, v[4:5]
	v_or_b32_e32 v4, s8, v63
	v_lshlrev_b32_e32 v4, 12, v4
	global_load_dword v100, v[26:27], off nt
	global_load_dword v101, v[28:29], off nt
	global_load_dword v102, v[30:31], off nt
	global_load_dword v103, v[32:33], off nt
	global_load_dword v104, v[78:79], off nt
	global_load_dword v105, v[80:81], off nt
	global_load_dword v106, v[82:83], off nt
	global_load_dword v107, v[84:85], off nt
	v_lshl_add_u64 v[26:27], v[24:25], 0, v[4:5]
	v_or_b32_e32 v4, s8, v65
	v_lshlrev_b32_e32 v4, 12, v4
	v_lshl_add_u64 v[28:29], v[24:25], 0, v[4:5]
	v_or_b32_e32 v4, s8, v66
	v_lshlrev_b32_e32 v4, 12, v4
	v_lshl_add_u64 v[30:31], v[24:25], 0, v[4:5]
	v_or_b32_e32 v4, s8, v67
	v_lshlrev_b32_e32 v4, 12, v4
	v_lshl_add_u64 v[32:33], v[24:25], 0, v[4:5]
	v_or_b32_e32 v4, s8, v68
	v_lshlrev_b32_e32 v4, 12, v4
	v_lshl_add_u64 v[78:79], v[24:25], 0, v[4:5]
	v_or_b32_e32 v4, s8, v69
	v_lshlrev_b32_e32 v4, 12, v4
	v_lshl_add_u64 v[80:81], v[24:25], 0, v[4:5]
	v_or_b32_e32 v4, s8, v70
	v_lshlrev_b32_e32 v4, 12, v4
	v_lshl_add_u64 v[82:83], v[24:25], 0, v[4:5]
	v_or_b32_e32 v4, s8, v71
	v_lshlrev_b32_e32 v4, 12, v4
	v_lshl_add_u64 v[24:25], v[24:25], 0, v[4:5]
	global_load_dword v4, v[26:27], off nt
	global_load_dword v84, v[28:29], off nt
	global_load_dword v85, v[30:31], off nt
	global_load_dword v108, v[32:33], off nt
	global_load_dword v109, v[78:79], off nt
	global_load_dword v110, v[80:81], off nt
	global_load_dword v111, v[82:83], off nt
	global_load_dword v112, v[24:25], off nt
	v_add_u32_e32 v24, v35, v36
	s_waitcnt vmcnt(0)
; #define LAS __attribute__((address_space(3)))
; __device__ __forceinline__ unsigned cvtpk(float lo, float hi) { typedef __bf16 bf2 __attribute__((ext_vector_type(2))); f32x2 v = {lo, hi}; bf2 b = __builtin_convertvector(v, bf2); return __builtin_bit_cast(unsigned, b); }
; __device__ __forceinline__ void transpose_item(const float* W, int K, int N, bf16_t* WT, int mode, LAS float* scr, int item, int lane) {
;     const int nblk = N / 32, kb = item / nblk, nb = item % nblk, k0 = 64 * kb, n0 = 32 * nb;
; #pragma unroll
;     for (int i = 0; i < 32; ++i) { const int kk = 2 * i + (lane >> 5); scr[kk * 33 + (lane & 31)] = W[(size_t)(k0 + kk) * N + n0 + (lane & 31)]; }
;     asm volatile("s_waitcnt lgkmcnt(0)" ::: "memory");
;     const int c = lane & 7;
; #pragma unroll
;     for (int j = 0; j < 4; ++j) { const int n = (lane >> 3) + 8 * j; const LAS float* s = scr + (8 * c) * 33 + n;
;         u32x4 o; o.x = cvtpk(s[0 * 33], s[1 * 33]); o.y = cvtpk(s[2 * 33], s[3 * 33]); o.z = cvtpk(s[4 * 33], s[5 * 33]); o.w = cvtpk(s[6 * 33], s[7 * 33]);
;         *(u32x4*)(WT + (size_t)wrow_map(mode, n0 + n) * K + k0 + 8 * c) = o; }
;     asm volatile("s_waitcnt lgkmcnt(0)" ::: "memory");
; __device__ __forceinline__ void convert_weights(PPtr P, int li, LAS unsigned char* lds, int gw, int NGW, int wave, int lane) {
;     ...
;         if (r < I_F1) { transpose_item(P->in[32] + (size_t)li * 1024 * 4096, 1024, 4096, Wb + W_F1, 0, scr, r, lane); continue; } r -= I_F1;
	ds_write2_b32 v24, v23, v77 offset1:66
	ds_write2_b32 v24, v86, v87 offset0:132 offset1:198
	v_add_u32_e32 v23, 0x400, v24
	ds_write2_b32 v23, v88, v89 offset0:8 offset1:74
	v_add_u32_e32 v23, v35, v43
	ds_write2_b32 v23, v90, v91 offset1:66
	ds_write2_b32 v23, v92, v93 offset0:132 offset1:198
	v_add_u32_e32 v23, 0x400, v23
	ds_write2_b32 v23, v94, v95 offset0:8 offset1:74
	v_add_u32_e32 v23, v35, v50
	ds_write2_b32 v23, v96, v97 offset1:66
	ds_write2_b32 v23, v98, v99 offset0:132 offset1:198
	v_add_u32_e32 v23, 0x400, v23
	s_lshl_b32 s8, s8, 1
	v_lshl_add_u64 v[88:89], v[6:7], 0, s[8:9]
	ds_write2_b32 v23, v100, v101 offset0:8 offset1:74
	v_add_u32_e32 v23, v35, v57
	ds_write2_b32 v23, v102, v103 offset1:66
	ds_write2_b32 v23, v104, v105 offset0:132 offset1:198
	v_add_u32_e32 v23, 0x400, v23
	ds_write2_b32 v23, v106, v107 offset0:8 offset1:74
	v_add_u32_e32 v23, v35, v64
	ds_write2_b32 v23, v4, v84 offset1:66
	ds_write2_b32 v23, v85, v108 offset0:132 offset1:198
	v_add_u32_e32 v4, 0x400, v23
	ds_write2_b32 v4, v109, v110 offset0:8 offset1:74
	ds_write2_b32 v4, v111, v112 offset0:140 offset1:206
	s_waitcnt lgkmcnt(0)
	ds_read2_b32 v[28:29], v73 offset0:33 offset1:41
	ds_read2_b32 v[30:31], v73 offset1:8
	ds_read2_b32 v[32:33], v73 offset0:66 offset1:74
	ds_read2_b32 v[78:79], v73 offset0:99 offset1:107
	ds_read2_b32 v[80:81], v73 offset0:132 offset1:140
	ds_read2_b32 v[82:83], v73 offset0:165 offset1:173
	ds_read2_b32 v[84:85], v73 offset0:198 offset1:206
	ds_read2_b32 v[86:87], v73 offset0:231 offset1:239
	v_or_b32_e32 v4, s36, v72
	v_lshlrev_b32_e32 v4, 13, v4
	s_waitcnt lgkmcnt(6)
	v_cvt_pk_bf16_f32 v24, v30, v28
	s_waitcnt lgkmcnt(4)
	v_cvt_pk_bf16_f32 v25, v32, v78
	s_waitcnt lgkmcnt(2)
	v_cvt_pk_bf16_f32 v26, v80, v82
	s_waitcnt lgkmcnt(0)
	v_cvt_pk_bf16_f32 v27, v84, v86
	v_lshl_add_u64 v[90:91], v[88:89], 0, v[4:5]
	global_store_dwordx4 v[90:91], v[24:27], off
	v_or_b32_e32 v4, s36, v74
	v_lshlrev_b32_e32 v4, 13, v4
	v_cvt_pk_bf16_f32 v24, v31, v29
	v_cvt_pk_bf16_f32 v25, v33, v79
	v_cvt_pk_bf16_f32 v26, v81, v83
	v_cvt_pk_bf16_f32 v27, v85, v87
	ds_read2_b32 v[30:31], v73 offset0:49 offset1:57
	ds_read2_b32 v[32:33], v73 offset0:16 offset1:24
	ds_read2_b32 v[78:79], v73 offset0:82 offset1:90
	ds_read2_b32 v[80:81], v73 offset0:115 offset1:123
	ds_read2_b32 v[82:83], v73 offset0:148 offset1:156
	ds_read2_b32 v[84:85], v73 offset0:181 offset1:189
	ds_read2_b32 v[86:87], v73 offset0:214 offset1:222
	ds_read2_b32 v[90:91], v73 offset0:247 offset1:255
	v_lshl_add_u64 v[28:29], v[88:89], 0, v[4:5]
	v_or_b32_e32 v4, s36, v75
	v_lshlrev_b32_e32 v4, 13, v4
	global_store_dwordx4 v[28:29], v[24:27], off
	v_lshl_add_u64 v[28:29], v[88:89], 0, v[4:5]
	v_or_b32_e32 v4, s36, v76
	s_waitcnt lgkmcnt(6)
	v_cvt_pk_bf16_f32 v24, v32, v30
	s_waitcnt lgkmcnt(4)
	v_cvt_pk_bf16_f32 v25, v78, v80
	s_waitcnt lgkmcnt(2)
	v_cvt_pk_bf16_f32 v26, v82, v84
	s_waitcnt lgkmcnt(0)
	v_cvt_pk_bf16_f32 v27, v86, v90
	v_lshlrev_b32_e32 v4, 13, v4
	global_store_dwordx4 v[28:29], v[24:27], off
	v_lshl_add_u64 v[28:29], v[88:89], 0, v[4:5]
	s_mov_b64 s[36:37], 0
	v_cvt_pk_bf16_f32 v24, v33, v31
	v_cvt_pk_bf16_f32 v25, v79, v81
	v_cvt_pk_bf16_f32 v26, v83, v85
	v_cvt_pk_bf16_f32 v27, v87, v91
	global_store_dwordx4 v[28:29], v[24:27], off
	s_waitcnt lgkmcnt(0)
.LBB0_1454:
	s_andn2_b64 vcc, exec, s[36:37]
	s_cbranch_vccnz .LBB0_1456
	s_load_dwordx2 s[38:39], s[6:7], 0x100
	s_add_i32 s8, s48, 0xffffea10
	s_add_i32 s36, s41, 0xfffd4200
	s_lshr_b32 s8, s8, 1
	s_and_b32 s36, s36, 0xfe0
	s_and_b32 s8, s8, 0x7fc0
	s_lshl_b32 s37, s36, 2
	s_waitcnt lgkmcnt(0)
	s_add_u32 s38, s38, s37
	s_addc_u32 s39, s39, 0
	v_lshlrev_b32_e32 v4, 2, v2
	v_lshl_add_u64 v[24:25], s[38:39], 0, v[4:5]
	v_or_b32_e32 v4, s8, v3
	v_lshl_add_u64 v[24:25], v[24:25], 0, s[10:11]
	v_lshlrev_b32_e32 v4, 14, v4
	v_lshl_add_u64 v[26:27], v[24:25], 0, v[4:5]
	v_or_b32_e32 v4, s8, v37
	v_lshlrev_b32_e32 v4, 14, v4
	v_lshl_add_u64 v[28:29], v[24:25], 0, v[4:5]
	v_or_b32_e32 v4, s8, v38
	v_lshlrev_b32_e32 v4, 14, v4
	v_lshl_add_u64 v[30:31], v[24:25], 0, v[4:5]
	v_or_b32_e32 v4, s8, v39
	v_lshlrev_b32_e32 v4, 14, v4
	v_lshl_add_u64 v[32:33], v[24:25], 0, v[4:5]
	v_or_b32_e32 v4, s8, v40
	v_lshlrev_b32_e32 v4, 14, v4
	v_lshl_add_u64 v[78:79], v[24:25], 0, v[4:5]
	v_or_b32_e32 v4, s8, v41
	v_lshlrev_b32_e32 v4, 14, v4
	v_lshl_add_u64 v[80:81], v[24:25], 0, v[4:5]
	v_or_b32_e32 v4, s8, v42
	v_lshlrev_b32_e32 v4, 14, v4
	v_lshl_add_u64 v[82:83], v[24:25], 0, v[4:5]
	v_or_b32_e32 v4, s8, v44
	v_lshlrev_b32_e32 v4, 14, v4
	v_lshl_add_u64 v[84:85], v[24:25], 0, v[4:5]
	v_or_b32_e32 v4, s8, v45
	v_lshlrev_b32_e32 v4, 14, v4
	global_load_dword v23, v[26:27], off nt
	global_load_dword v77, v[28:29], off nt
	global_load_dword v86, v[30:31], off nt
	global_load_dword v87, v[32:33], off nt
	global_load_dword v88, v[78:79], off nt
	global_load_dword v89, v[80:81], off nt
	global_load_dword v90, v[82:83], off nt
	global_load_dword v91, v[84:85], off nt
	v_lshl_add_u64 v[26:27], v[24:25], 0, v[4:5]
	v_or_b32_e32 v4, s8, v46
	v_lshlrev_b32_e32 v4, 14, v4
	v_lshl_add_u64 v[28:29], v[24:25], 0, v[4:5]
	v_or_b32_e32 v4, s8, v47
	v_lshlrev_b32_e32 v4, 14, v4
	v_lshl_add_u64 v[30:31], v[24:25], 0, v[4:5]
	v_or_b32_e32 v4, s8, v48
	v_lshlrev_b32_e32 v4, 14, v4
	v_lshl_add_u64 v[32:33], v[24:25], 0, v[4:5]
	v_or_b32_e32 v4, s8, v49
	v_lshlrev_b32_e32 v4, 14, v4
	v_lshl_add_u64 v[78:79], v[24:25], 0, v[4:5]
	v_or_b32_e32 v4, s8, v51
	v_lshlrev_b32_e32 v4, 14, v4
	v_lshl_add_u64 v[80:81], v[24:25], 0, v[4:5]
	v_or_b32_e32 v4, s8, v52
	v_lshlrev_b32_e32 v4, 14, v4
	v_lshl_add_u64 v[82:83], v[24:25], 0, v[4:5]
	v_or_b32_e32 v4, s8, v53
; #define LAS __attribute__((address_space(3)))
; __device__ __forceinline__ unsigned cvtpk(float lo, float hi) { typedef __bf16 bf2 __attribute__((ext_vector_type(2))); f32x2 v = {lo, hi}; bf2 b = __builtin_convertvector(v, bf2); return __builtin_bit_cast(unsigned, b); }
; __device__ __forceinline__ void transpose_item(const float* W, int K, int N, bf16_t* WT, int mode, LAS float* scr, int item, int lane) {
;     const int nblk = N / 32, kb = item / nblk, nb = item % nblk, k0 = 64 * kb, n0 = 32 * nb;
; #pragma unroll
;     for (int i = 0; i < 32; ++i) { const int kk = 2 * i + (lane >> 5); scr[kk * 33 + (lane & 31)] = W[(size_t)(k0 + kk) * N + n0 + (lane & 31)]; }
;     asm volatile("s_waitcnt lgkmcnt(0)" ::: "memory");
;     const int c = lane & 7;
; #pragma unroll
;     for (int j = 0; j < 4; ++j) { const int n = (lane >> 3) + 8 * j; const LAS float* s = scr + (8 * c) * 33 + n;
;         u32x4 o; o.x = cvtpk(s[0 * 33], s[1 * 33]); o.y = cvtpk(s[2 * 33], s[3 * 33]); o.z = cvtpk(s[4 * 33], s[5 * 33]); o.w = cvtpk(s[6 * 33], s[7 * 33]);
;         *(u32x4*)(WT + (size_t)wrow_map(mode, n0 + n) * K + k0 + 8 * c) = o; }
;     asm volatile("s_waitcnt lgkmcnt(0)" ::: "memory");
; __device__ __forceinline__ void convert_weights(PPtr P, int li, LAS unsigned char* lds, int gw, int NGW, int wave, int lane) {
;     ...
;         if (r < I_F1) { transpose_item(P->in[32] + (size_t)li * 1024 * 4096, 1024, 4096, Wb + W_F1, 0, scr, r, lane); continue; } r -= I_F1;
	v_lshlrev_b32_e32 v4, 14, v4
	v_lshl_add_u64 v[84:85], v[24:25], 0, v[4:5]
	v_or_b32_e32 v4, s8, v54
	v_lshlrev_b32_e32 v4, 14, v4
	global_load_dword v92, v[26:27], off nt
	global_load_dword v93, v[28:29], off nt
	global_load_dword v94, v[30:31], off nt
	global_load_dword v95, v[32:33], off nt
	global_load_dword v96, v[78:79], off nt
	global_load_dword v97, v[80:81], off nt
	global_load_dword v98, v[82:83], off nt
	global_load_dword v99, v[84:85], off nt
	v_lshl_add_u64 v[26:27], v[24:25], 0, v[4:5]
	v_or_b32_e32 v4, s8, v55
	v_lshlrev_b32_e32 v4, 14, v4
	v_lshl_add_u64 v[28:29], v[24:25], 0, v[4:5]
	v_or_b32_e32 v4, s8, v56
	v_lshlrev_b32_e32 v4, 14, v4
	v_lshl_add_u64 v[30:31], v[24:25], 0, v[4:5]
	v_or_b32_e32 v4, s8, v58
	v_lshlrev_b32_e32 v4, 14, v4
	v_lshl_add_u64 v[32:33], v[24:25], 0, v[4:5]
	v_or_b32_e32 v4, s8, v59
	v_lshlrev_b32_e32 v4, 14, v4
	v_lshl_add_u64 v[78:79], v[24:25], 0, v[4:5]
	v_or_b32_e32 v4, s8, v60
	v_lshlrev_b32_e32 v4, 14, v4
	v_lshl_add_u64 v[80:81], v[24:25], 0, v[4:5]
	v_or_b32_e32 v4, s8, v61
	v_lshlrev_b32_e32 v4, 14, v4
	v_lshl_add_u64 v[82:83], v[24:25], 0, v[4:5]
	v_or_b32_e32 v4, s8, v62
	v_lshlrev_b32_e32 v4, 14, v4
	v_lshl_add_u64 v[84:85], v[24:25], 0, v[4:5]
	v_or_b32_e32 v4, s8, v63
	v_lshlrev_b32_e32 v4, 14, v4
	global_load_dword v100, v[26:27], off nt
	global_load_dword v101, v[28:29], off nt
	global_load_dword v102, v[30:31], off nt
	global_load_dword v103, v[32:33], off nt
	global_load_dword v104, v[78:79], off nt
	global_load_dword v105, v[80:81], off nt
	global_load_dword v106, v[82:83], off nt
	global_load_dword v107, v[84:85], off nt
	v_lshl_add_u64 v[26:27], v[24:25], 0, v[4:5]
	v_or_b32_e32 v4, s8, v65
	v_lshlrev_b32_e32 v4, 14, v4
	v_lshl_add_u64 v[28:29], v[24:25], 0, v[4:5]
	v_or_b32_e32 v4, s8, v66
	v_lshlrev_b32_e32 v4, 14, v4
	v_lshl_add_u64 v[30:31], v[24:25], 0, v[4:5]
	v_or_b32_e32 v4, s8, v67
	v_lshlrev_b32_e32 v4, 14, v4
	v_lshl_add_u64 v[32:33], v[24:25], 0, v[4:5]
	v_or_b32_e32 v4, s8, v68
	v_lshlrev_b32_e32 v4, 14, v4
	v_lshl_add_u64 v[78:79], v[24:25], 0, v[4:5]
	v_or_b32_e32 v4, s8, v69
	v_lshlrev_b32_e32 v4, 14, v4
	v_lshl_add_u64 v[80:81], v[24:25], 0, v[4:5]
	v_or_b32_e32 v4, s8, v70
	v_lshlrev_b32_e32 v4, 14, v4
	v_lshl_add_u64 v[82:83], v[24:25], 0, v[4:5]
	v_or_b32_e32 v4, s8, v71
	v_lshlrev_b32_e32 v4, 14, v4
	v_lshl_add_u64 v[24:25], v[24:25], 0, v[4:5]
	global_load_dword v4, v[26:27], off nt
	global_load_dword v84, v[28:29], off nt
	global_load_dword v85, v[30:31], off nt
	global_load_dword v108, v[32:33], off nt
	global_load_dword v109, v[78:79], off nt
	global_load_dword v110, v[80:81], off nt
	global_load_dword v111, v[82:83], off nt
	global_load_dword v112, v[24:25], off nt
	v_add_u32_e32 v24, v35, v36
	s_waitcnt vmcnt(0)
	ds_write2_b32 v24, v23, v77 offset1:66
	ds_write2_b32 v24, v86, v87 offset0:132 offset1:198
	v_add_u32_e32 v23, 0x400, v24
	ds_write2_b32 v23, v88, v89 offset0:8 offset1:74
	v_add_u32_e32 v23, v35, v43
	ds_write2_b32 v23, v90, v91 offset1:66
	ds_write2_b32 v23, v92, v93 offset0:132 offset1:198
	v_add_u32_e32 v23, 0x400, v23
	ds_write2_b32 v23, v94, v95 offset0:8 offset1:74
	v_add_u32_e32 v23, v35, v50
	ds_write2_b32 v23, v96, v97 offset1:66
	ds_write2_b32 v23, v98, v99 offset0:132 offset1:198
	v_add_u32_e32 v23, 0x400, v23
	s_lshl_b32 s8, s8, 1
	v_lshl_add_u64 v[88:89], v[8:9], 0, s[8:9]
	ds_write2_b32 v23, v100, v101 offset0:8 offset1:74
	v_add_u32_e32 v23, v35, v57
	ds_write2_b32 v23, v102, v103 offset1:66
	ds_write2_b32 v23, v104, v105 offset0:132 offset1:198
	v_add_u32_e32 v23, 0x400, v23
	ds_write2_b32 v23, v106, v107 offset0:8 offset1:74
	v_add_u32_e32 v23, v35, v64
	ds_write2_b32 v23, v4, v84 offset1:66
	ds_write2_b32 v23, v85, v108 offset0:132 offset1:198
	v_add_u32_e32 v4, 0x400, v23
	ds_write2_b32 v4, v109, v110 offset0:8 offset1:74
	ds_write2_b32 v4, v111, v112 offset0:140 offset1:206
	s_waitcnt lgkmcnt(0)
	ds_read2_b32 v[28:29], v73 offset0:33 offset1:41
	ds_read2_b32 v[30:31], v73 offset1:8
	ds_read2_b32 v[32:33], v73 offset0:66 offset1:74
	ds_read2_b32 v[78:79], v73 offset0:99 offset1:107
	ds_read2_b32 v[80:81], v73 offset0:132 offset1:140
	ds_read2_b32 v[82:83], v73 offset0:165 offset1:173
	ds_read2_b32 v[84:85], v73 offset0:198 offset1:206
	ds_read2_b32 v[86:87], v73 offset0:231 offset1:239
	v_or_b32_e32 v4, s36, v72
	v_lshlrev_b32_e32 v4, 11, v4
	s_waitcnt lgkmcnt(6)
	v_cvt_pk_bf16_f32 v24, v30, v28
	s_waitcnt lgkmcnt(4)
	v_cvt_pk_bf16_f32 v25, v32, v78
	s_waitcnt lgkmcnt(2)
	v_cvt_pk_bf16_f32 v26, v80, v82
	s_waitcnt lgkmcnt(0)
	v_cvt_pk_bf16_f32 v27, v84, v86
	v_lshl_add_u64 v[90:91], v[88:89], 0, v[4:5]
	global_store_dwordx4 v[90:91], v[24:27], off
	v_or_b32_e32 v4, s36, v74
	v_lshlrev_b32_e32 v4, 11, v4
	v_cvt_pk_bf16_f32 v24, v31, v29
	v_cvt_pk_bf16_f32 v25, v33, v79
	v_cvt_pk_bf16_f32 v26, v81, v83
	v_cvt_pk_bf16_f32 v27, v85, v87
	ds_read2_b32 v[30:31], v73 offset0:49 offset1:57
	ds_read2_b32 v[32:33], v73 offset0:16 offset1:24
	ds_read2_b32 v[78:79], v73 offset0:82 offset1:90
	ds_read2_b32 v[80:81], v73 offset0:115 offset1:123
	ds_read2_b32 v[82:83], v73 offset0:148 offset1:156
	ds_read2_b32 v[84:85], v73 offset0:181 offset1:189
	ds_read2_b32 v[86:87], v73 offset0:214 offset1:222
	ds_read2_b32 v[90:91], v73 offset0:247 offset1:255
	v_lshl_add_u64 v[28:29], v[88:89], 0, v[4:5]
	v_or_b32_e32 v4, s36, v75
	v_lshlrev_b32_e32 v4, 11, v4
	global_store_dwordx4 v[28:29], v[24:27], off
	v_lshl_add_u64 v[28:29], v[88:89], 0, v[4:5]
	v_or_b32_e32 v4, s36, v76
	s_waitcnt lgkmcnt(6)
	v_cvt_pk_bf16_f32 v24, v32, v30
	s_waitcnt lgkmcnt(4)
	v_cvt_pk_bf16_f32 v25, v78, v80
	s_waitcnt lgkmcnt(2)
	v_cvt_pk_bf16_f32 v26, v82, v84
	s_waitcnt lgkmcnt(0)
	v_cvt_pk_bf16_f32 v27, v86, v90
	v_lshlrev_b32_e32 v4, 11, v4
	global_store_dwordx4 v[28:29], v[24:27], off
	v_lshl_add_u64 v[28:29], v[88:89], 0, v[4:5]
	s_nop 0
	v_cvt_pk_bf16_f32 v24, v33, v31
	v_cvt_pk_bf16_f32 v25, v79, v81
	v_cvt_pk_bf16_f32 v26, v83, v85
	v_cvt_pk_bf16_f32 v27, v87, v91
	global_store_dwordx4 v[28:29], v[24:27], off
	s_waitcnt lgkmcnt(0)

; #define LAS __attribute__((address_space(3)))
; __device__ __forceinline__ void transpose_item(const float* W, int K, int N, bf16_t* WT, int mode, LAS float* scr, int item, int lane) {
;     const int nblk = N / 32, kb = item / nblk, nb = item % nblk, k0 = 64 * kb, n0 = 32 * nb;
; #pragma unroll
;     for (int i = 0; i < 32; ++i) { const int kk = 2 * i + (lane >> 5); scr[kk * 33 + (lane & 31)] = W[(size_t)(k0 + kk) * N + n0 + (lane & 31)]; }
; __device__ __forceinline__ void convert_weights(PPtr P, int li, LAS unsigned char* lds, int gw, int NGW, int wave, int lane) {
;     ...
;         if (r < I_OUT) { transpose_item(P->in[31] + (size_t)li * 1024 * 1024, 1024, 1024, Wb + W_OUT, 0, scr, r, lane); continue; } r -= I_OUT;
.LBB0_1457:
	s_andn2_b64 vcc, exec, s[36:37]
	s_cbranch_vccnz .LBB0_1459
	s_load_dwordx2 s[38:39], s[6:7], 0xf8
	s_add_i32 s36, s41, 0xfffd8200
	s_add_i32 s8, s43, 0x1400
	s_and_b32 s36, s36, 0x3e0
	s_and_b32 s8, s8, 0x1ffc0
	s_lshl_b32 s37, s36, 2
	s_waitcnt lgkmcnt(0)
	s_add_u32 s38, s38, s37
	s_addc_u32 s39, s39, 0
	v_lshlrev_b32_e32 v4, 2, v2
	v_lshl_add_u64 v[24:25], s[38:39], 0, v[4:5]
	v_or_b32_e32 v4, s8, v3
	v_lshl_add_u64 v[24:25], v[24:25], 0, s[16:17]
	v_lshlrev_b32_e32 v4, 12, v4
	v_lshl_add_u64 v[26:27], v[24:25], 0, v[4:5]
	v_or_b32_e32 v4, s8, v37
	v_lshlrev_b32_e32 v4, 12, v4
	v_lshl_add_u64 v[28:29], v[24:25], 0, v[4:5]
	v_or_b32_e32 v4, s8, v38
	v_lshlrev_b32_e32 v4, 12, v4
	v_lshl_add_u64 v[30:31], v[24:25], 0, v[4:5]
	v_or_b32_e32 v4, s8, v39
	v_lshlrev_b32_e32 v4, 12, v4
	v_lshl_add_u64 v[32:33], v[24:25], 0, v[4:5]
	v_or_b32_e32 v4, s8, v40
	v_lshlrev_b32_e32 v4, 12, v4
	v_lshl_add_u64 v[78:79], v[24:25], 0, v[4:5]
	v_or_b32_e32 v4, s8, v41
	v_lshlrev_b32_e32 v4, 12, v4
	v_lshl_add_u64 v[80:81], v[24:25], 0, v[4:5]
	v_or_b32_e32 v4, s8, v42
	v_lshlrev_b32_e32 v4, 12, v4
	v_lshl_add_u64 v[82:83], v[24:25], 0, v[4:5]
	v_or_b32_e32 v4, s8, v44
	v_lshlrev_b32_e32 v4, 12, v4
	v_lshl_add_u64 v[84:85], v[24:25], 0, v[4:5]
	v_or_b32_e32 v4, s8, v45
	v_lshlrev_b32_e32 v4, 12, v4
	global_load_dword v23, v[26:27], off nt
	global_load_dword v77, v[28:29], off nt
	global_load_dword v86, v[30:31], off nt
	global_load_dword v87, v[32:33], off nt
	global_load_dword v88, v[78:79], off nt
	global_load_dword v89, v[80:81], off nt
	global_load_dword v90, v[82:83], off nt
	global_load_dword v91, v[84:85], off nt
	v_lshl_add_u64 v[26:27], v[24:25], 0, v[4:5]
	v_or_b32_e32 v4, s8, v46
	v_lshlrev_b32_e32 v4, 12, v4
	v_lshl_add_u64 v[28:29], v[24:25], 0, v[4:5]
	v_or_b32_e32 v4, s8, v47
	v_lshlrev_b32_e32 v4, 12, v4
	v_lshl_add_u64 v[30:31], v[24:25], 0, v[4:5]
	v_or_b32_e32 v4, s8, v48
	v_lshlrev_b32_e32 v4, 12, v4
	v_lshl_add_u64 v[32:33], v[24:25], 0, v[4:5]
	v_or_b32_e32 v4, s8, v49
	v_lshlrev_b32_e32 v4, 12, v4
	v_lshl_add_u64 v[78:79], v[24:25], 0, v[4:5]
	v_or_b32_e32 v4, s8, v51
	v_lshlrev_b32_e32 v4, 12, v4
	v_lshl_add_u64 v[80:81], v[24:25], 0, v[4:5]
	v_or_b32_e32 v4, s8, v52
	v_lshlrev_b32_e32 v4, 12, v4
	v_lshl_add_u64 v[82:83], v[24:25], 0, v[4:5]
	v_or_b32_e32 v4, s8, v53
	v_lshlrev_b32_e32 v4, 12, v4
	v_lshl_add_u64 v[84:85], v[24:25], 0, v[4:5]
	v_or_b32_e32 v4, s8, v54
	v_lshlrev_b32_e32 v4, 12, v4
	global_load_dword v92, v[26:27], off nt
	global_load_dword v93, v[28:29], off nt
	global_load_dword v94, v[30:31], off nt
	global_load_dword v95, v[32:33], off nt
	global_load_dword v96, v[78:79], off nt
	global_load_dword v97, v[80:81], off nt
	global_load_dword v98, v[82:83], off nt
	global_load_dword v99, v[84:85], off nt
	v_lshl_add_u64 v[26:27], v[24:25], 0, v[4:5]
	v_or_b32_e32 v4, s8, v55
	v_lshlrev_b32_e32 v4, 12, v4
	v_lshl_add_u64 v[28:29], v[24:25], 0, v[4:5]
	v_or_b32_e32 v4, s8, v56
	v_lshlrev_b32_e32 v4, 12, v4
	v_lshl_add_u64 v[30:31], v[24:25], 0, v[4:5]
	v_or_b32_e32 v4, s8, v58
	v_lshlrev_b32_e32 v4, 12, v4
	v_lshl_add_u64 v[32:33], v[24:25], 0, v[4:5]
	v_or_b32_e32 v4, s8, v59
	v_lshlrev_b32_e32 v4, 12, v4
	v_lshl_add_u64 v[78:79], v[24:25], 0, v[4:5]
	v_or_b32_e32 v4, s8, v60
	v_lshlrev_b32_e32 v4, 12, v4
	v_lshl_add_u64 v[80:81], v[24:25], 0, v[4:5]
	v_or_b32_e32 v4, s8, v61
	v_lshlrev_b32_e32 v4, 12, v4
	v_lshl_add_u64 v[82:83], v[24:25], 0, v[4:5]
	v_or_b32_e32 v4, s8, v62
	v_lshlrev_b32_e32 v4, 12, v4
	v_lshl_add_u64 v[84:85], v[24:25], 0, v[4:5]
	v_or_b32_e32 v4, s8, v63
	v_lshlrev_b32_e32 v4, 12, v4
	global_load_dword v100, v[26:27], off nt
	global_load_dword v101, v[28:29], off nt
	global_load_dword v102, v[30:31], off nt
	global_load_dword v103, v[32:33], off nt
	global_load_dword v104, v[78:79], off nt
	global_load_dword v105, v[80:81], off nt
	global_load_dword v106, v[82:83], off nt
	global_load_dword v107, v[84:85], off nt
	v_lshl_add_u64 v[26:27], v[24:25], 0, v[4:5]
	v_or_b32_e32 v4, s8, v65
	v_lshlrev_b32_e32 v4, 12, v4
	v_lshl_add_u64 v[28:29], v[24:25], 0, v[4:5]
	v_or_b32_e32 v4, s8, v66
	v_lshlrev_b32_e32 v4, 12, v4
	v_lshl_add_u64 v[30:31], v[24:25], 0, v[4:5]
	v_or_b32_e32 v4, s8, v67
	v_lshlrev_b32_e32 v4, 12, v4
	v_lshl_add_u64 v[32:33], v[24:25], 0, v[4:5]
	v_or_b32_e32 v4, s8, v68
	v_lshlrev_b32_e32 v4, 12, v4
	v_lshl_add_u64 v[78:79], v[24:25], 0, v[4:5]
	v_or_b32_e32 v4, s8, v69
	v_lshlrev_b32_e32 v4, 12, v4
	v_lshl_add_u64 v[80:81], v[24:25], 0, v[4:5]
	v_or_b32_e32 v4, s8, v70
	v_lshlrev_b32_e32 v4, 12, v4
	v_lshl_add_u64 v[82:83], v[24:25], 0, v[4:5]
	v_or_b32_e32 v4, s8, v71
	v_lshlrev_b32_e32 v4, 12, v4
	v_lshl_add_u64 v[24:25], v[24:25], 0, v[4:5]
	global_load_dword v4, v[26:27], off nt
	global_load_dword v84, v[28:29], off nt
	global_load_dword v85, v[30:31], off nt
	global_load_dword v108, v[32:33], off nt
	global_load_dword v109, v[78:79], off nt
	global_load_dword v110, v[80:81], off nt
	global_load_dword v111, v[82:83], off nt
	global_load_dword v112, v[24:25], off nt
	v_add_u32_e32 v24, v35, v36
	s_waitcnt vmcnt(0)
; #define LAS __attribute__((address_space(3)))
; __device__ __forceinline__ unsigned cvtpk(float lo, float hi) { typedef __bf16 bf2 __attribute__((ext_vector_type(2))); f32x2 v = {lo, hi}; bf2 b = __builtin_convertvector(v, bf2); return __builtin_bit_cast(unsigned, b); }
; __device__ __forceinline__ void transpose_item(const float* W, int K, int N, bf16_t* WT, int mode, LAS float* scr, int item, int lane) {
;     ...
;     for (int i = 0; i < 32; ++i) { const int kk = 2 * i + (lane >> 5); scr[kk * 33 + (lane & 31)] = W[(size_t)(k0 + kk) * N + n0 + (lane & 31)]; }
;     asm volatile("s_waitcnt lgkmcnt(0)" ::: "memory");
;     const int c = lane & 7;
; #pragma unroll
;     for (int j = 0; j < 4; ++j) { const int n = (lane >> 3) + 8 * j; const LAS float* s = scr + (8 * c) * 33 + n;
;         u32x4 o; o.x = cvtpk(s[0 * 33], s[1 * 33]); o.y = cvtpk(s[2 * 33], s[3 * 33]); o.z = cvtpk(s[4 * 33], s[5 * 33]); o.w = cvtpk(s[6 * 33], s[7 * 33]);
;         *(u32x4*)(WT + (size_t)wrow_map(mode, n0 + n) * K + k0 + 8 * c) = o; }
;     asm volatile("s_waitcnt lgkmcnt(0)" ::: "memory");
	ds_write2_b32 v24, v23, v77 offset1:66
	ds_write2_b32 v24, v86, v87 offset0:132 offset1:198
	v_add_u32_e32 v23, 0x400, v24
	ds_write2_b32 v23, v88, v89 offset0:8 offset1:74
	v_add_u32_e32 v23, v35, v43
	ds_write2_b32 v23, v90, v91 offset1:66
	ds_write2_b32 v23, v92, v93 offset0:132 offset1:198
	v_add_u32_e32 v23, 0x400, v23
	ds_write2_b32 v23, v94, v95 offset0:8 offset1:74
	v_add_u32_e32 v23, v35, v50
	ds_write2_b32 v23, v96, v97 offset1:66
	ds_write2_b32 v23, v98, v99 offset0:132 offset1:198
	v_add_u32_e32 v23, 0x400, v23
	s_lshl_b32 s8, s8, 1
	v_lshl_add_u64 v[88:89], v[10:11], 0, s[8:9]
	ds_write2_b32 v23, v100, v101 offset0:8 offset1:74
	v_add_u32_e32 v23, v35, v57
	ds_write2_b32 v23, v102, v103 offset1:66
	ds_write2_b32 v23, v104, v105 offset0:132 offset1:198
	v_add_u32_e32 v23, 0x400, v23
	ds_write2_b32 v23, v106, v107 offset0:8 offset1:74
	v_add_u32_e32 v23, v35, v64
	ds_write2_b32 v23, v4, v84 offset1:66
	ds_write2_b32 v23, v85, v108 offset0:132 offset1:198
	v_add_u32_e32 v4, 0x400, v23
	ds_write2_b32 v4, v109, v110 offset0:8 offset1:74
	ds_write2_b32 v4, v111, v112 offset0:140 offset1:206
	s_waitcnt lgkmcnt(0)
	ds_read2_b32 v[28:29], v73 offset0:33 offset1:41
	ds_read2_b32 v[30:31], v73 offset1:8
	ds_read2_b32 v[32:33], v73 offset0:66 offset1:74
	ds_read2_b32 v[78:79], v73 offset0:99 offset1:107
	ds_read2_b32 v[80:81], v73 offset0:132 offset1:140
	ds_read2_b32 v[82:83], v73 offset0:165 offset1:173
	ds_read2_b32 v[84:85], v73 offset0:198 offset1:206
	ds_read2_b32 v[86:87], v73 offset0:231 offset1:239
	v_or_b32_e32 v4, s36, v72
	v_lshlrev_b32_e32 v4, 11, v4
	s_waitcnt lgkmcnt(6)
	v_cvt_pk_bf16_f32 v24, v30, v28
	s_waitcnt lgkmcnt(4)
	v_cvt_pk_bf16_f32 v25, v32, v78
	s_waitcnt lgkmcnt(2)
	v_cvt_pk_bf16_f32 v26, v80, v82
	s_waitcnt lgkmcnt(0)
	v_cvt_pk_bf16_f32 v27, v84, v86
	v_lshl_add_u64 v[90:91], v[88:89], 0, v[4:5]
	global_store_dwordx4 v[90:91], v[24:27], off
	v_or_b32_e32 v4, s36, v74
	v_lshlrev_b32_e32 v4, 11, v4
	v_cvt_pk_bf16_f32 v24, v31, v29
	v_cvt_pk_bf16_f32 v25, v33, v79
	v_cvt_pk_bf16_f32 v26, v81, v83
	v_cvt_pk_bf16_f32 v27, v85, v87
	ds_read2_b32 v[30:31], v73 offset0:49 offset1:57
	ds_read2_b32 v[32:33], v73 offset0:16 offset1:24
	ds_read2_b32 v[78:79], v73 offset0:82 offset1:90
	ds_read2_b32 v[80:81], v73 offset0:115 offset1:123
	ds_read2_b32 v[82:83], v73 offset0:148 offset1:156
	ds_read2_b32 v[84:85], v73 offset0:181 offset1:189
	ds_read2_b32 v[86:87], v73 offset0:214 offset1:222
	ds_read2_b32 v[90:91], v73 offset0:247 offset1:255
	v_lshl_add_u64 v[28:29], v[88:89], 0, v[4:5]
	v_or_b32_e32 v4, s36, v75
	v_lshlrev_b32_e32 v4, 11, v4
	global_store_dwordx4 v[28:29], v[24:27], off
	v_lshl_add_u64 v[28:29], v[88:89], 0, v[4:5]
	v_or_b32_e32 v4, s36, v76
	s_waitcnt lgkmcnt(6)
	v_cvt_pk_bf16_f32 v24, v32, v30
	s_waitcnt lgkmcnt(4)
	v_cvt_pk_bf16_f32 v25, v78, v80
	s_waitcnt lgkmcnt(2)
	v_cvt_pk_bf16_f32 v26, v82, v84
	s_waitcnt lgkmcnt(0)
	v_cvt_pk_bf16_f32 v27, v86, v90
	v_lshlrev_b32_e32 v4, 11, v4
	global_store_dwordx4 v[28:29], v[24:27], off
	v_lshl_add_u64 v[28:29], v[88:89], 0, v[4:5]
	s_nop 0
	v_cvt_pk_bf16_f32 v24, v33, v31
	v_cvt_pk_bf16_f32 v25, v79, v81
	v_cvt_pk_bf16_f32 v26, v83, v85
	v_cvt_pk_bf16_f32 v27, v87, v91
	global_store_dwordx4 v[28:29], v[24:27], off
	s_waitcnt lgkmcnt(0)

; #define LAS __attribute__((address_space(3)))
; __device__ __forceinline__ void transpose_item(const float* W, int K, int N, bf16_t* WT, int mode, LAS float* scr, int item, int lane) {
;     const int nblk = N / 32, kb = item / nblk, nb = item % nblk, k0 = 64 * kb, n0 = 32 * nb;
; #pragma unroll
;     for (int i = 0; i < 32; ++i) { const int kk = 2 * i + (lane >> 5); scr[kk * 33 + (lane & 31)] = W[(size_t)(k0 + kk) * N + n0 + (lane & 31)]; }
; __device__ __forceinline__ void convert_weights(PPtr P, int li, LAS unsigned char* lds, int gw, int NGW, int wave, int lane) {
;     ...
;         if (r < 4 * I_BR) { const int b = r / I_BR; transpose_item(P->in[27 + b] + (size_t)li * 512 * 1024, 512, 1024, Wb + W_BR + (size_t)b * 524288, 0, scr, r % I_BR, lane); continue; } r -= 4 * I_BR;
.LBB0_1460:
	s_andn2_b64 vcc, exec, s[36:37]
	s_cbranch_vccnz .LBB0_1462
	s_add_i32 s8, s48, 0xfffff010
	s_lshr_b32 s8, s8, 8
	s_lshl_b32 s36, s8, 3
	s_load_dwordx2 s[50:51], s[6:7], s36 offset:0xd8
	s_lshl_b64 s[36:37], s[8:9], 20
	s_add_u32 s36, s27, s36
	s_addc_u32 s37, s40, s37
	s_add_i32 s8, s43, 0x1c00
	s_and_b32 s38, s8, 0x1c0
	s_add_i32 s8, s41, 0xfffe0200
	s_and_b32 s8, s8, 0x3e0
	s_lshl_b32 s39, s8, 2
	s_waitcnt lgkmcnt(0)
	s_add_u32 s50, s50, s39
	s_addc_u32 s51, s51, 0
	v_lshlrev_b32_e32 v4, 2, v2
	v_lshl_add_u64 v[24:25], s[50:51], 0, v[4:5]
	v_or_b32_e32 v4, s38, v3
	v_lshl_add_u64 v[24:25], v[24:25], 0, s[18:19]
	v_lshlrev_b32_e32 v4, 12, v4
	v_lshl_add_u64 v[26:27], v[24:25], 0, v[4:5]
	v_or_b32_e32 v4, s38, v37
	v_lshlrev_b32_e32 v4, 12, v4
	v_lshl_add_u64 v[28:29], v[24:25], 0, v[4:5]
	v_or_b32_e32 v4, s38, v38
	v_lshlrev_b32_e32 v4, 12, v4
	v_lshl_add_u64 v[30:31], v[24:25], 0, v[4:5]
	v_or_b32_e32 v4, s38, v39
	v_lshlrev_b32_e32 v4, 12, v4
	v_lshl_add_u64 v[32:33], v[24:25], 0, v[4:5]
	v_or_b32_e32 v4, s38, v40
	v_lshlrev_b32_e32 v4, 12, v4
	v_lshl_add_u64 v[78:79], v[24:25], 0, v[4:5]
	v_or_b32_e32 v4, s38, v41
	v_lshlrev_b32_e32 v4, 12, v4
	v_lshl_add_u64 v[80:81], v[24:25], 0, v[4:5]
	v_or_b32_e32 v4, s38, v42
	v_lshlrev_b32_e32 v4, 12, v4
	v_lshl_add_u64 v[82:83], v[24:25], 0, v[4:5]
	v_or_b32_e32 v4, s38, v44
	v_lshlrev_b32_e32 v4, 12, v4
	v_lshl_add_u64 v[84:85], v[24:25], 0, v[4:5]
	v_or_b32_e32 v4, s38, v45
	v_lshlrev_b32_e32 v4, 12, v4
	global_load_dword v23, v[26:27], off nt
	global_load_dword v77, v[28:29], off nt
	global_load_dword v86, v[30:31], off nt
	global_load_dword v87, v[32:33], off nt
	global_load_dword v88, v[78:79], off nt
	global_load_dword v89, v[80:81], off nt
	global_load_dword v90, v[82:83], off nt
	global_load_dword v91, v[84:85], off nt
	v_lshl_add_u64 v[26:27], v[24:25], 0, v[4:5]
	v_or_b32_e32 v4, s38, v46
	v_lshlrev_b32_e32 v4, 12, v4
	v_lshl_add_u64 v[28:29], v[24:25], 0, v[4:5]
	v_or_b32_e32 v4, s38, v47
	v_lshlrev_b32_e32 v4, 12, v4
	v_lshl_add_u64 v[30:31], v[24:25], 0, v[4:5]
	v_or_b32_e32 v4, s38, v48
	v_lshlrev_b32_e32 v4, 12, v4
	v_lshl_add_u64 v[32:33], v[24:25], 0, v[4:5]
	v_or_b32_e32 v4, s38, v49
	v_lshlrev_b32_e32 v4, 12, v4
	v_lshl_add_u64 v[78:79], v[24:25], 0, v[4:5]
	v_or_b32_e32 v4, s38, v51
	v_lshlrev_b32_e32 v4, 12, v4
	v_lshl_add_u64 v[80:81], v[24:25], 0, v[4:5]
	v_or_b32_e32 v4, s38, v52
	v_lshlrev_b32_e32 v4, 12, v4
	v_lshl_add_u64 v[82:83], v[24:25], 0, v[4:5]
	v_or_b32_e32 v4, s38, v53
	v_lshlrev_b32_e32 v4, 12, v4
	v_lshl_add_u64 v[84:85], v[24:25], 0, v[4:5]
	v_or_b32_e32 v4, s38, v54
	v_lshlrev_b32_e32 v4, 12, v4
	global_load_dword v92, v[26:27], off nt
	global_load_dword v93, v[28:29], off nt
	global_load_dword v94, v[30:31], off nt
	global_load_dword v95, v[32:33], off nt
	global_load_dword v96, v[78:79], off nt
	global_load_dword v97, v[80:81], off nt
	global_load_dword v98, v[82:83], off nt
	global_load_dword v99, v[84:85], off nt
	v_lshl_add_u64 v[26:27], v[24:25], 0, v[4:5]
	v_or_b32_e32 v4, s38, v55
	v_lshlrev_b32_e32 v4, 12, v4
	v_lshl_add_u64 v[28:29], v[24:25], 0, v[4:5]
	v_or_b32_e32 v4, s38, v56
	v_lshlrev_b32_e32 v4, 12, v4
	v_lshl_add_u64 v[30:31], v[24:25], 0, v[4:5]
	v_or_b32_e32 v4, s38, v58
	v_lshlrev_b32_e32 v4, 12, v4
	v_lshl_add_u64 v[32:33], v[24:25], 0, v[4:5]
	v_or_b32_e32 v4, s38, v59
	v_lshlrev_b32_e32 v4, 12, v4
	v_lshl_add_u64 v[78:79], v[24:25], 0, v[4:5]
	v_or_b32_e32 v4, s38, v60
	v_lshlrev_b32_e32 v4, 12, v4
	v_lshl_add_u64 v[80:81], v[24:25], 0, v[4:5]
	v_or_b32_e32 v4, s38, v61
	v_lshlrev_b32_e32 v4, 12, v4
	v_lshl_add_u64 v[82:83], v[24:25], 0, v[4:5]
	v_or_b32_e32 v4, s38, v62
	v_lshlrev_b32_e32 v4, 12, v4
	v_lshl_add_u64 v[84:85], v[24:25], 0, v[4:5]
	v_or_b32_e32 v4, s38, v63
	v_lshlrev_b32_e32 v4, 12, v4
	global_load_dword v100, v[26:27], off nt
	global_load_dword v101, v[28:29], off nt
	global_load_dword v102, v[30:31], off nt
	global_load_dword v103, v[32:33], off nt
	global_load_dword v104, v[78:79], off nt
	global_load_dword v105, v[80:81], off nt
	global_load_dword v106, v[82:83], off nt
	global_load_dword v107, v[84:85], off nt
	v_lshl_add_u64 v[26:27], v[24:25], 0, v[4:5]
	v_or_b32_e32 v4, s38, v65
	v_lshlrev_b32_e32 v4, 12, v4
	v_lshl_add_u64 v[28:29], v[24:25], 0, v[4:5]
	v_or_b32_e32 v4, s38, v66
	v_lshlrev_b32_e32 v4, 12, v4
	v_lshl_add_u64 v[30:31], v[24:25], 0, v[4:5]
	v_or_b32_e32 v4, s38, v67
	v_lshlrev_b32_e32 v4, 12, v4
	v_lshl_add_u64 v[32:33], v[24:25], 0, v[4:5]
	v_or_b32_e32 v4, s38, v68
	v_lshlrev_b32_e32 v4, 12, v4
	v_lshl_add_u64 v[78:79], v[24:25], 0, v[4:5]
	v_or_b32_e32 v4, s38, v69
	v_lshlrev_b32_e32 v4, 12, v4
	v_lshl_add_u64 v[80:81], v[24:25], 0, v[4:5]
	v_or_b32_e32 v4, s38, v70
	v_lshlrev_b32_e32 v4, 12, v4
	v_lshl_add_u64 v[82:83], v[24:25], 0, v[4:5]
	v_or_b32_e32 v4, s38, v71
	v_lshlrev_b32_e32 v4, 12, v4
	v_lshl_add_u64 v[24:25], v[24:25], 0, v[4:5]
	global_load_dword v4, v[26:27], off nt
	global_load_dword v84, v[28:29], off nt
	global_load_dword v85, v[30:31], off nt
	global_load_dword v108, v[32:33], off nt
	global_load_dword v109, v[78:79], off nt
	global_load_dword v110, v[80:81], off nt
	global_load_dword v111, v[82:83], off nt
	global_load_dword v112, v[24:25], off nt
	v_add_u32_e32 v24, v35, v36
	s_waitcnt vmcnt(0)
; #define LAS __attribute__((address_space(3)))
; __device__ __forceinline__ unsigned cvtpk(float lo, float hi) { typedef __bf16 bf2 __attribute__((ext_vector_type(2))); f32x2 v = {lo, hi}; bf2 b = __builtin_convertvector(v, bf2); return __builtin_bit_cast(unsigned, b); }
; __device__ __forceinline__ void transpose_item(const float* W, int K, int N, bf16_t* WT, int mode, LAS float* scr, int item, int lane) {
;     ...
;     for (int i = 0; i < 32; ++i) { const int kk = 2 * i + (lane >> 5); scr[kk * 33 + (lane & 31)] = W[(size_t)(k0 + kk) * N + n0 + (lane & 31)]; }
;     asm volatile("s_waitcnt lgkmcnt(0)" ::: "memory");
;     const int c = lane & 7;
; #pragma unroll
;     for (int j = 0; j < 4; ++j) { const int n = (lane >> 3) + 8 * j; const LAS float* s = scr + (8 * c) * 33 + n;
;         u32x4 o; o.x = cvtpk(s[0 * 33], s[1 * 33]); o.y = cvtpk(s[2 * 33], s[3 * 33]); o.z = cvtpk(s[4 * 33], s[5 * 33]); o.w = cvtpk(s[6 * 33], s[7 * 33]);
;         *(u32x4*)(WT + (size_t)wrow_map(mode, n0 + n) * K + k0 + 8 * c) = o; }
;     asm volatile("s_waitcnt lgkmcnt(0)" ::: "memory");
	ds_write2_b32 v24, v23, v77 offset1:66
	ds_write2_b32 v24, v86, v87 offset0:132 offset1:198
	v_add_u32_e32 v23, 0x400, v24
	ds_write2_b32 v23, v88, v89 offset0:8 offset1:74
	v_add_u32_e32 v23, v35, v43
	ds_write2_b32 v23, v90, v91 offset1:66
	ds_write2_b32 v23, v92, v93 offset0:132 offset1:198
	v_add_u32_e32 v23, 0x400, v23
	ds_write2_b32 v23, v94, v95 offset0:8 offset1:74
	v_add_u32_e32 v23, v35, v50
	ds_write2_b32 v23, v96, v97 offset1:66
	ds_write2_b32 v23, v98, v99 offset0:132 offset1:198
	v_add_u32_e32 v23, 0x400, v23
	s_lshl_b32 s38, s38, 1
	s_add_u32 s36, s36, s38
	s_addc_u32 s37, s37, 0
	ds_write2_b32 v23, v100, v101 offset0:8 offset1:74
	v_add_u32_e32 v23, v35, v57
	ds_write2_b32 v23, v102, v103 offset1:66
	ds_write2_b32 v23, v104, v105 offset0:132 offset1:198
	v_add_u32_e32 v23, 0x400, v23
	ds_write2_b32 v23, v106, v107 offset0:8 offset1:74
	v_add_u32_e32 v23, v35, v64
	ds_write2_b32 v23, v4, v84 offset1:66
	ds_write2_b32 v23, v85, v108 offset0:132 offset1:198
	v_add_u32_e32 v4, 0x400, v23
	ds_write2_b32 v4, v109, v110 offset0:8 offset1:74
	ds_write2_b32 v4, v111, v112 offset0:140 offset1:206
	s_waitcnt lgkmcnt(0)
	ds_read2_b32 v[28:29], v73 offset0:33 offset1:41
	ds_read2_b32 v[30:31], v73 offset1:8
	ds_read2_b32 v[32:33], v73 offset0:66 offset1:74
	ds_read2_b32 v[78:79], v73 offset0:99 offset1:107
	ds_read2_b32 v[80:81], v73 offset0:132 offset1:140
	ds_read2_b32 v[82:83], v73 offset0:165 offset1:173
	ds_read2_b32 v[84:85], v73 offset0:198 offset1:206
	ds_read2_b32 v[86:87], v73 offset0:231 offset1:239
	v_mov_b32_e32 v23, v5
	v_or_b32_e32 v4, s8, v72
	v_lshl_add_u64 v[88:89], s[36:37], 0, v[22:23]
	v_lshlrev_b32_e32 v4, 10, v4
	s_waitcnt lgkmcnt(6)
	v_cvt_pk_bf16_f32 v24, v30, v28
	s_waitcnt lgkmcnt(4)
	v_cvt_pk_bf16_f32 v25, v32, v78
	s_waitcnt lgkmcnt(2)
	v_cvt_pk_bf16_f32 v26, v80, v82
	s_waitcnt lgkmcnt(0)
	v_cvt_pk_bf16_f32 v27, v84, v86
	v_lshl_add_u64 v[90:91], v[88:89], 0, v[4:5]
	global_store_dwordx4 v[90:91], v[24:27], off
	v_or_b32_e32 v4, s8, v74
	v_lshlrev_b32_e32 v4, 10, v4
	v_cvt_pk_bf16_f32 v24, v31, v29
	v_cvt_pk_bf16_f32 v25, v33, v79
	v_cvt_pk_bf16_f32 v26, v81, v83
	v_cvt_pk_bf16_f32 v27, v85, v87
	ds_read2_b32 v[30:31], v73 offset0:49 offset1:57
	ds_read2_b32 v[32:33], v73 offset0:16 offset1:24
	ds_read2_b32 v[78:79], v73 offset0:82 offset1:90
	ds_read2_b32 v[80:81], v73 offset0:115 offset1:123
	ds_read2_b32 v[82:83], v73 offset0:148 offset1:156
	ds_read2_b32 v[84:85], v73 offset0:181 offset1:189
	ds_read2_b32 v[86:87], v73 offset0:214 offset1:222
	ds_read2_b32 v[90:91], v73 offset0:247 offset1:255
	v_lshl_add_u64 v[28:29], v[88:89], 0, v[4:5]
	v_or_b32_e32 v4, s8, v75
	v_lshlrev_b32_e32 v4, 10, v4
	global_store_dwordx4 v[28:29], v[24:27], off
	v_lshl_add_u64 v[28:29], v[88:89], 0, v[4:5]
	v_or_b32_e32 v4, s8, v76
	s_waitcnt lgkmcnt(6)
	v_cvt_pk_bf16_f32 v24, v32, v30
	s_waitcnt lgkmcnt(4)
	v_cvt_pk_bf16_f32 v25, v78, v80
	s_waitcnt lgkmcnt(2)
	v_cvt_pk_bf16_f32 v26, v82, v84
	s_waitcnt lgkmcnt(0)
	v_cvt_pk_bf16_f32 v27, v86, v90
	v_lshlrev_b32_e32 v4, 10, v4
	global_store_dwordx4 v[28:29], v[24:27], off
	v_lshl_add_u64 v[28:29], v[88:89], 0, v[4:5]
	s_nop 0
	v_cvt_pk_bf16_f32 v24, v33, v31
	v_cvt_pk_bf16_f32 v25, v79, v81
	v_cvt_pk_bf16_f32 v26, v83, v85
	v_cvt_pk_bf16_f32 v27, v87, v91
	global_store_dwordx4 v[28:29], v[24:27], off
	s_waitcnt lgkmcnt(0)

; #define LAS __attribute__((address_space(3)))
; __device__ __forceinline__ void transpose_item(const float* W, int K, int N, bf16_t* WT, int mode, LAS float* scr, int item, int lane) {
;     const int nblk = N / 32, kb = item / nblk, nb = item % nblk, k0 = 64 * kb, n0 = 32 * nb;
; #pragma unroll
;     for (int i = 0; i < 32; ++i) { const int kk = 2 * i + (lane >> 5); scr[kk * 33 + (lane & 31)] = W[(size_t)(k0 + kk) * N + n0 + (lane & 31)]; }
; __device__ __forceinline__ void convert_weights(PPtr P, int li, LAS unsigned char* lds, int gw, int NGW, int wave, int lane) {
;     ...
;         if (r < I_GLU) { transpose_item(P->in[26] + (size_t)li * 512 * 1024, 512, 1024, Wb + W_GLU, 2, scr, r, lane); continue; } r -= I_GLU;
.LBB0_1463:
	s_andn2_b64 vcc, exec, s[36:37]
	s_cbranch_vccnz .LBB0_1465
	s_load_dwordx2 s[38:39], s[6:7], 0xd0
	s_add_i32 s37, s48, 0xfffff110
	s_and_b32 s49, s37, 31
	s_add_i32 s8, s43, 0x1e00
	s_and_b32 s8, s8, 0x1c0
	s_lshl_b32 s36, s37, 5
	s_lshl_b32 s49, s49, 7
	s_waitcnt lgkmcnt(0)
	s_add_u32 s38, s38, s49
	s_addc_u32 s39, s39, 0
	v_lshlrev_b32_e32 v4, 2, v2
	v_lshl_add_u64 v[24:25], s[38:39], 0, v[4:5]
	v_or_b32_e32 v4, s8, v3
	v_lshl_add_u64 v[24:25], v[24:25], 0, s[18:19]
	v_lshlrev_b32_e32 v4, 12, v4
	v_lshl_add_u64 v[26:27], v[24:25], 0, v[4:5]
	v_or_b32_e32 v4, s8, v37
	v_lshlrev_b32_e32 v4, 12, v4
	v_lshl_add_u64 v[28:29], v[24:25], 0, v[4:5]
	v_or_b32_e32 v4, s8, v38
	v_lshlrev_b32_e32 v4, 12, v4
	v_lshl_add_u64 v[30:31], v[24:25], 0, v[4:5]
	v_or_b32_e32 v4, s8, v39
	v_lshlrev_b32_e32 v4, 12, v4
	v_lshl_add_u64 v[32:33], v[24:25], 0, v[4:5]
	v_or_b32_e32 v4, s8, v40
	v_lshlrev_b32_e32 v4, 12, v4
	v_lshl_add_u64 v[78:79], v[24:25], 0, v[4:5]
	v_or_b32_e32 v4, s8, v41
	v_lshlrev_b32_e32 v4, 12, v4
	v_lshl_add_u64 v[80:81], v[24:25], 0, v[4:5]
	v_or_b32_e32 v4, s8, v42
	v_lshlrev_b32_e32 v4, 12, v4
	v_lshl_add_u64 v[82:83], v[24:25], 0, v[4:5]
	v_or_b32_e32 v4, s8, v44
	v_lshlrev_b32_e32 v4, 12, v4
	v_lshl_add_u64 v[84:85], v[24:25], 0, v[4:5]
	v_or_b32_e32 v4, s8, v45
	v_lshlrev_b32_e32 v4, 12, v4
	global_load_dword v23, v[26:27], off nt
	global_load_dword v77, v[28:29], off nt
	global_load_dword v86, v[30:31], off nt
	global_load_dword v87, v[32:33], off nt
	global_load_dword v88, v[78:79], off nt
	global_load_dword v89, v[80:81], off nt
	global_load_dword v90, v[82:83], off nt
	global_load_dword v91, v[84:85], off nt
	v_lshl_add_u64 v[26:27], v[24:25], 0, v[4:5]
	v_or_b32_e32 v4, s8, v46
	v_lshlrev_b32_e32 v4, 12, v4
	v_lshl_add_u64 v[28:29], v[24:25], 0, v[4:5]
	v_or_b32_e32 v4, s8, v47
	v_lshlrev_b32_e32 v4, 12, v4
	v_lshl_add_u64 v[30:31], v[24:25], 0, v[4:5]
	v_or_b32_e32 v4, s8, v48
	v_lshlrev_b32_e32 v4, 12, v4
	v_lshl_add_u64 v[32:33], v[24:25], 0, v[4:5]
	v_or_b32_e32 v4, s8, v49
	v_lshlrev_b32_e32 v4, 12, v4
	v_lshl_add_u64 v[78:79], v[24:25], 0, v[4:5]
	v_or_b32_e32 v4, s8, v51
	v_lshlrev_b32_e32 v4, 12, v4
	v_lshl_add_u64 v[80:81], v[24:25], 0, v[4:5]
	v_or_b32_e32 v4, s8, v52
	v_lshlrev_b32_e32 v4, 12, v4
	v_lshl_add_u64 v[82:83], v[24:25], 0, v[4:5]
	v_or_b32_e32 v4, s8, v53
	v_lshlrev_b32_e32 v4, 12, v4
	v_lshl_add_u64 v[84:85], v[24:25], 0, v[4:5]
	v_or_b32_e32 v4, s8, v54
	v_lshlrev_b32_e32 v4, 12, v4
	global_load_dword v92, v[26:27], off nt
	global_load_dword v93, v[28:29], off nt
	global_load_dword v94, v[30:31], off nt
	global_load_dword v95, v[32:33], off nt
	global_load_dword v96, v[78:79], off nt
	global_load_dword v97, v[80:81], off nt
	global_load_dword v98, v[82:83], off nt
	global_load_dword v99, v[84:85], off nt
	v_lshl_add_u64 v[26:27], v[24:25], 0, v[4:5]
	v_or_b32_e32 v4, s8, v55
	v_lshlrev_b32_e32 v4, 12, v4
	v_lshl_add_u64 v[28:29], v[24:25], 0, v[4:5]
	v_or_b32_e32 v4, s8, v56
	v_lshlrev_b32_e32 v4, 12, v4
	v_lshl_add_u64 v[30:31], v[24:25], 0, v[4:5]
	v_or_b32_e32 v4, s8, v58
	v_lshlrev_b32_e32 v4, 12, v4
	v_lshl_add_u64 v[32:33], v[24:25], 0, v[4:5]
	v_or_b32_e32 v4, s8, v59
	v_lshlrev_b32_e32 v4, 12, v4
	v_lshl_add_u64 v[78:79], v[24:25], 0, v[4:5]
	v_or_b32_e32 v4, s8, v60
	v_lshlrev_b32_e32 v4, 12, v4
	v_lshl_add_u64 v[80:81], v[24:25], 0, v[4:5]
	v_or_b32_e32 v4, s8, v61
	v_lshlrev_b32_e32 v4, 12, v4
	v_lshl_add_u64 v[82:83], v[24:25], 0, v[4:5]
	v_or_b32_e32 v4, s8, v62
	v_lshlrev_b32_e32 v4, 12, v4
	v_lshl_add_u64 v[84:85], v[24:25], 0, v[4:5]
	v_or_b32_e32 v4, s8, v63
	v_lshlrev_b32_e32 v4, 12, v4
	global_load_dword v100, v[26:27], off nt
	global_load_dword v101, v[28:29], off nt
	global_load_dword v102, v[30:31], off nt
	global_load_dword v103, v[32:33], off nt
	global_load_dword v104, v[78:79], off nt
	global_load_dword v105, v[80:81], off nt
	global_load_dword v106, v[82:83], off nt
	global_load_dword v107, v[84:85], off nt
	v_lshl_add_u64 v[26:27], v[24:25], 0, v[4:5]
	v_or_b32_e32 v4, s8, v65
	v_lshlrev_b32_e32 v4, 12, v4
	v_lshl_add_u64 v[28:29], v[24:25], 0, v[4:5]
	v_or_b32_e32 v4, s8, v66
	v_lshlrev_b32_e32 v4, 12, v4
	v_lshl_add_u64 v[30:31], v[24:25], 0, v[4:5]
	v_or_b32_e32 v4, s8, v67
	v_lshlrev_b32_e32 v4, 12, v4
	v_lshl_add_u64 v[32:33], v[24:25], 0, v[4:5]
	v_or_b32_e32 v4, s8, v68
	v_lshlrev_b32_e32 v4, 12, v4
	v_lshl_add_u64 v[78:79], v[24:25], 0, v[4:5]
	v_or_b32_e32 v4, s8, v69
	v_lshlrev_b32_e32 v4, 12, v4
	v_lshl_add_u64 v[80:81], v[24:25], 0, v[4:5]
	v_or_b32_e32 v4, s8, v70
	v_lshlrev_b32_e32 v4, 12, v4
	v_lshl_add_u64 v[82:83], v[24:25], 0, v[4:5]
	v_or_b32_e32 v4, s8, v71
	v_lshlrev_b32_e32 v4, 12, v4
	v_lshl_add_u64 v[24:25], v[24:25], 0, v[4:5]
	global_load_dword v4, v[26:27], off nt
	global_load_dword v84, v[28:29], off nt
	global_load_dword v85, v[30:31], off nt
	global_load_dword v108, v[32:33], off nt
	global_load_dword v109, v[78:79], off nt
	global_load_dword v110, v[80:81], off nt
	global_load_dword v111, v[82:83], off nt
	global_load_dword v112, v[24:25], off nt
	v_add_u32_e32 v24, v35, v36
	s_waitcnt vmcnt(0)
; #define LAS __attribute__((address_space(3)))
; __device__ __forceinline__ unsigned cvtpk(float lo, float hi) { typedef __bf16 bf2 __attribute__((ext_vector_type(2))); f32x2 v = {lo, hi}; bf2 b = __builtin_convertvector(v, bf2); return __builtin_bit_cast(unsigned, b); }
; __device__ __forceinline__ int wrow_map(int mode, int n) {
;     ...
;     if (mode == 2) { const int c = n & 511, t = c >> 7; return 256 * t + (n >> 9) * 128 + (c & 127); }
; __device__ __forceinline__ void transpose_item(const float* W, int K, int N, bf16_t* WT, int mode, LAS float* scr, int item, int lane) {
;     ...
;     for (int i = 0; i < 32; ++i) { const int kk = 2 * i + (lane >> 5); scr[kk * 33 + (lane & 31)] = W[(size_t)(k0 + kk) * N + n0 + (lane & 31)]; }
;     asm volatile("s_waitcnt lgkmcnt(0)" ::: "memory");
;     const int c = lane & 7;
; #pragma unroll
;     for (int j = 0; j < 4; ++j) { const int n = (lane >> 3) + 8 * j; const LAS float* s = scr + (8 * c) * 33 + n;
;         u32x4 o; o.x = cvtpk(s[0 * 33], s[1 * 33]); o.y = cvtpk(s[2 * 33], s[3 * 33]); o.z = cvtpk(s[4 * 33], s[5 * 33]); o.w = cvtpk(s[6 * 33], s[7 * 33]);
;         *(u32x4*)(WT + (size_t)wrow_map(mode, n0 + n) * K + k0 + 8 * c) = o; }
;     asm volatile("s_waitcnt lgkmcnt(0)" ::: "memory");
	ds_write2_b32 v24, v23, v77 offset1:66
	ds_write2_b32 v24, v86, v87 offset0:132 offset1:198
	v_add_u32_e32 v23, 0x400, v24
	ds_write2_b32 v23, v88, v89 offset0:8 offset1:74
	v_add_u32_e32 v23, v35, v43
	ds_write2_b32 v23, v90, v91 offset1:66
	ds_write2_b32 v23, v92, v93 offset0:132 offset1:198
	v_add_u32_e32 v23, 0x400, v23
	ds_write2_b32 v23, v94, v95 offset0:8 offset1:74
	v_add_u32_e32 v23, v35, v50
	ds_write2_b32 v23, v96, v97 offset1:66
	ds_write2_b32 v23, v98, v99 offset0:132 offset1:198
	v_add_u32_e32 v23, 0x400, v23
	s_lshl_b32 s8, s8, 1
	v_lshl_add_u64 v[28:29], v[12:13], 0, s[8:9]
	s_lshl_b32 s8, s37, 6
	s_lshl_b32 s37, s37, 3
	s_and_b32 s8, s8, 0x300
	s_and_b32 s37, s37, 0x80
	s_and_b32 s36, s36, 0x60
	s_or_b32 s8, s8, s37
	ds_write2_b32 v23, v100, v101 offset0:8 offset1:74
	v_add_u32_e32 v23, v35, v57
	ds_write2_b32 v23, v102, v103 offset1:66
	ds_write2_b32 v23, v104, v105 offset0:132 offset1:198
	v_add_u32_e32 v23, 0x400, v23
	ds_write2_b32 v23, v106, v107 offset0:8 offset1:74
	v_add_u32_e32 v23, v35, v64
	ds_write2_b32 v23, v4, v84 offset1:66
	ds_write2_b32 v23, v85, v108 offset0:132 offset1:198
	v_add_u32_e32 v4, 0x400, v23
	ds_write2_b32 v4, v109, v110 offset0:8 offset1:74
	ds_write2_b32 v4, v111, v112 offset0:140 offset1:206
	s_waitcnt lgkmcnt(0)
	ds_read2_b32 v[30:31], v73 offset0:33 offset1:41
	ds_read2_b32 v[32:33], v73 offset1:8
	ds_read2_b32 v[78:79], v73 offset0:66 offset1:74
	ds_read2_b32 v[80:81], v73 offset0:99 offset1:107
	ds_read2_b32 v[82:83], v73 offset0:132 offset1:140
	ds_read2_b32 v[84:85], v73 offset0:165 offset1:173
	ds_read2_b32 v[86:87], v73 offset0:198 offset1:206
	ds_read2_b32 v[88:89], v73 offset0:231 offset1:239
	v_or_b32_e32 v4, s36, v72
	v_or_b32_e32 v4, s8, v4
	v_lshlrev_b32_e32 v4, 10, v4
	v_lshl_add_u64 v[90:91], v[28:29], 0, v[4:5]
	v_or_b32_e32 v4, s36, v74
	s_waitcnt lgkmcnt(6)
	v_cvt_pk_bf16_f32 v24, v32, v30
	s_waitcnt lgkmcnt(4)
	v_cvt_pk_bf16_f32 v25, v78, v80
	s_waitcnt lgkmcnt(2)
	v_cvt_pk_bf16_f32 v26, v82, v84
	s_waitcnt lgkmcnt(0)
	v_cvt_pk_bf16_f32 v27, v86, v88
	v_or_b32_e32 v4, s8, v4
	global_store_dwordx4 v[90:91], v[24:27], off
	v_lshlrev_b32_e32 v4, 10, v4
	s_nop 0
	v_cvt_pk_bf16_f32 v24, v33, v31
	v_cvt_pk_bf16_f32 v25, v79, v81
	v_cvt_pk_bf16_f32 v26, v83, v85
	v_cvt_pk_bf16_f32 v27, v87, v89
	v_lshl_add_u64 v[30:31], v[28:29], 0, v[4:5]
	ds_read2_b32 v[32:33], v73 offset0:49 offset1:57
	ds_read2_b32 v[78:79], v73 offset0:16 offset1:24
	ds_read2_b32 v[80:81], v73 offset0:82 offset1:90
	ds_read2_b32 v[82:83], v73 offset0:115 offset1:123
	ds_read2_b32 v[84:85], v73 offset0:148 offset1:156
	ds_read2_b32 v[86:87], v73 offset0:181 offset1:189
	ds_read2_b32 v[88:89], v73 offset0:214 offset1:222
	ds_read2_b32 v[90:91], v73 offset0:247 offset1:255
	v_or_b32_e32 v4, s36, v75
	v_or_b32_e32 v4, s8, v4
	v_lshlrev_b32_e32 v4, 10, v4
	global_store_dwordx4 v[30:31], v[24:27], off
	v_lshl_add_u64 v[30:31], v[28:29], 0, v[4:5]
	v_or_b32_e32 v4, s36, v76
	v_or_b32_e32 v4, s8, v4
	s_waitcnt lgkmcnt(6)
	v_cvt_pk_bf16_f32 v24, v78, v32
	s_waitcnt lgkmcnt(4)
	v_cvt_pk_bf16_f32 v25, v80, v82
	s_waitcnt lgkmcnt(2)
	v_cvt_pk_bf16_f32 v26, v84, v86
	s_waitcnt lgkmcnt(0)
	v_cvt_pk_bf16_f32 v27, v88, v90
	v_lshlrev_b32_e32 v4, 10, v4
	global_store_dwordx4 v[30:31], v[24:27], off
	v_lshl_add_u64 v[28:29], v[28:29], 0, v[4:5]
	s_nop 0
	v_cvt_pk_bf16_f32 v24, v79, v33
	v_cvt_pk_bf16_f32 v25, v81, v83
	v_cvt_pk_bf16_f32 v26, v85, v87
	v_cvt_pk_bf16_f32 v27, v89, v91
	global_store_dwordx4 v[28:29], v[24:27], off
	s_waitcnt lgkmcnt(0)

; #define LAS __attribute__((address_space(3)))
; __device__ __forceinline__ void transpose_item(const float* W, int K, int N, bf16_t* WT, int mode, LAS float* scr, int item, int lane) {
;     const int nblk = N / 32, kb = item / nblk, nb = item % nblk, k0 = 64 * kb, n0 = 32 * nb;
; #pragma unroll
;     for (int i = 0; i < 32; ++i) { const int kk = 2 * i + (lane >> 5); scr[kk * 33 + (lane & 31)] = W[(size_t)(k0 + kk) * N + n0 + (lane & 31)]; }
; __device__ __forceinline__ void convert_weights(PPtr P, int li, LAS unsigned char* lds, int gw, int NGW, int wave, int lane) {
;     ...
;         if (r < I_UKV) { transpose_item(P->in[17] + (size_t)li * 128 * 1024, 128, 1024, Wb + W_UKV, 0, scr, r, lane); continue; } r -= I_UKV;
.LBB0_1466:
	s_andn2_b64 vcc, exec, s[36:37]
	s_cbranch_vccnz .LBB0_1468
	s_add_i32 s8, s48, 0xfffff150
	s_add_i32 s36, s48, 0xfffff130
	s_load_dwordx2 s[38:39], s[6:7], 0x88
	s_cmp_lt_u32 s8, 32
	s_cselect_b32 s36, s8, s36
	s_cmp_gt_u32 s8, 31
	s_cselect_b32 s8, 64, 0
	s_lshl_b32 s36, s36, 5
	s_ashr_i32 s37, s36, 31
	s_lshl_b64 s[50:51], s[36:37], 2
	s_waitcnt lgkmcnt(0)
	s_add_u32 s38, s38, s50
	s_addc_u32 s39, s39, s51
	v_lshlrev_b32_e32 v4, 2, v2
	v_lshl_add_u64 v[24:25], s[38:39], 0, v[4:5]
	v_or_b32_e32 v4, s8, v3
	v_lshl_add_u64 v[24:25], v[24:25], 0, s[20:21]
	v_lshlrev_b32_e32 v4, 12, v4
	v_lshl_add_u64 v[26:27], v[24:25], 0, v[4:5]
	v_or_b32_e32 v4, s8, v37
	v_lshlrev_b32_e32 v4, 12, v4
	v_lshl_add_u64 v[28:29], v[24:25], 0, v[4:5]
	v_or_b32_e32 v4, s8, v38
	v_lshlrev_b32_e32 v4, 12, v4
	v_lshl_add_u64 v[30:31], v[24:25], 0, v[4:5]
	v_or_b32_e32 v4, s8, v39
	v_lshlrev_b32_e32 v4, 12, v4
	v_lshl_add_u64 v[32:33], v[24:25], 0, v[4:5]
	v_or_b32_e32 v4, s8, v40
	v_lshlrev_b32_e32 v4, 12, v4
	v_lshl_add_u64 v[78:79], v[24:25], 0, v[4:5]
	v_or_b32_e32 v4, s8, v41
	v_lshlrev_b32_e32 v4, 12, v4
	v_lshl_add_u64 v[80:81], v[24:25], 0, v[4:5]
	v_or_b32_e32 v4, s8, v42
	v_lshlrev_b32_e32 v4, 12, v4
	v_lshl_add_u64 v[82:83], v[24:25], 0, v[4:5]
	v_or_b32_e32 v4, s8, v44
	v_lshlrev_b32_e32 v4, 12, v4
	v_lshl_add_u64 v[84:85], v[24:25], 0, v[4:5]
	v_or_b32_e32 v4, s8, v45
	v_lshlrev_b32_e32 v4, 12, v4
	global_load_dword v23, v[26:27], off nt
	global_load_dword v77, v[28:29], off nt
	global_load_dword v86, v[30:31], off nt
	global_load_dword v87, v[32:33], off nt
	global_load_dword v88, v[78:79], off nt
	global_load_dword v89, v[80:81], off nt
	global_load_dword v90, v[82:83], off nt
	global_load_dword v91, v[84:85], off nt
	v_lshl_add_u64 v[26:27], v[24:25], 0, v[4:5]
	v_or_b32_e32 v4, s8, v46
	v_lshlrev_b32_e32 v4, 12, v4
	v_lshl_add_u64 v[28:29], v[24:25], 0, v[4:5]
	v_or_b32_e32 v4, s8, v47
	v_lshlrev_b32_e32 v4, 12, v4
	v_lshl_add_u64 v[30:31], v[24:25], 0, v[4:5]
	v_or_b32_e32 v4, s8, v48
	v_lshlrev_b32_e32 v4, 12, v4
	v_lshl_add_u64 v[32:33], v[24:25], 0, v[4:5]
	v_or_b32_e32 v4, s8, v49
	v_lshlrev_b32_e32 v4, 12, v4
	v_lshl_add_u64 v[78:79], v[24:25], 0, v[4:5]
	v_or_b32_e32 v4, s8, v51
	v_lshlrev_b32_e32 v4, 12, v4
	v_lshl_add_u64 v[80:81], v[24:25], 0, v[4:5]
	v_or_b32_e32 v4, s8, v52
	v_lshlrev_b32_e32 v4, 12, v4
	v_lshl_add_u64 v[82:83], v[24:25], 0, v[4:5]
	v_or_b32_e32 v4, s8, v53
	v_lshlrev_b32_e32 v4, 12, v4
	v_lshl_add_u64 v[84:85], v[24:25], 0, v[4:5]
	v_or_b32_e32 v4, s8, v54
	v_lshlrev_b32_e32 v4, 12, v4
	global_load_dword v92, v[26:27], off nt
	global_load_dword v93, v[28:29], off nt
	global_load_dword v94, v[30:31], off nt
	global_load_dword v95, v[32:33], off nt
	global_load_dword v96, v[78:79], off nt
	global_load_dword v97, v[80:81], off nt
	global_load_dword v98, v[82:83], off nt
	global_load_dword v99, v[84:85], off nt
	v_lshl_add_u64 v[26:27], v[24:25], 0, v[4:5]
	v_or_b32_e32 v4, s8, v55
	v_lshlrev_b32_e32 v4, 12, v4
	v_lshl_add_u64 v[28:29], v[24:25], 0, v[4:5]
	v_or_b32_e32 v4, s8, v56
	v_lshlrev_b32_e32 v4, 12, v4
	v_lshl_add_u64 v[30:31], v[24:25], 0, v[4:5]
	v_or_b32_e32 v4, s8, v58
	v_lshlrev_b32_e32 v4, 12, v4
	v_lshl_add_u64 v[32:33], v[24:25], 0, v[4:5]
	v_or_b32_e32 v4, s8, v59
	v_lshlrev_b32_e32 v4, 12, v4
	v_lshl_add_u64 v[78:79], v[24:25], 0, v[4:5]
	v_or_b32_e32 v4, s8, v60
	v_lshlrev_b32_e32 v4, 12, v4
	v_lshl_add_u64 v[80:81], v[24:25], 0, v[4:5]
	v_or_b32_e32 v4, s8, v61
	v_lshlrev_b32_e32 v4, 12, v4
	v_lshl_add_u64 v[82:83], v[24:25], 0, v[4:5]
	v_or_b32_e32 v4, s8, v62
	v_lshlrev_b32_e32 v4, 12, v4
	v_lshl_add_u64 v[84:85], v[24:25], 0, v[4:5]
	v_or_b32_e32 v4, s8, v63
	v_lshlrev_b32_e32 v4, 12, v4
	global_load_dword v100, v[26:27], off nt
	global_load_dword v101, v[28:29], off nt
	global_load_dword v102, v[30:31], off nt
	global_load_dword v103, v[32:33], off nt
	global_load_dword v104, v[78:79], off nt
	global_load_dword v105, v[80:81], off nt
	global_load_dword v106, v[82:83], off nt
	global_load_dword v107, v[84:85], off nt
	v_lshl_add_u64 v[26:27], v[24:25], 0, v[4:5]
	v_or_b32_e32 v4, s8, v65
	v_lshlrev_b32_e32 v4, 12, v4
	v_lshl_add_u64 v[28:29], v[24:25], 0, v[4:5]
	v_or_b32_e32 v4, s8, v66
	v_lshlrev_b32_e32 v4, 12, v4
	v_lshl_add_u64 v[30:31], v[24:25], 0, v[4:5]
	v_or_b32_e32 v4, s8, v67
	v_lshlrev_b32_e32 v4, 12, v4
	v_lshl_add_u64 v[32:33], v[24:25], 0, v[4:5]
	v_or_b32_e32 v4, s8, v68
	v_lshlrev_b32_e32 v4, 12, v4
	v_lshl_add_u64 v[78:79], v[24:25], 0, v[4:5]
	v_or_b32_e32 v4, s8, v69
	v_lshlrev_b32_e32 v4, 12, v4
	v_lshl_add_u64 v[80:81], v[24:25], 0, v[4:5]
	v_or_b32_e32 v4, s8, v70
	v_lshlrev_b32_e32 v4, 12, v4
	v_lshl_add_u64 v[82:83], v[24:25], 0, v[4:5]
	v_or_b32_e32 v4, s8, v71
	v_lshlrev_b32_e32 v4, 12, v4
	v_lshl_add_u64 v[24:25], v[24:25], 0, v[4:5]
	global_load_dword v4, v[26:27], off nt
	global_load_dword v84, v[28:29], off nt
	global_load_dword v85, v[30:31], off nt
	global_load_dword v108, v[32:33], off nt
	global_load_dword v109, v[78:79], off nt
	global_load_dword v110, v[80:81], off nt
	global_load_dword v111, v[82:83], off nt
	global_load_dword v112, v[24:25], off nt
	v_add_u32_e32 v24, v35, v36
	s_waitcnt vmcnt(0)
; #define LAS __attribute__((address_space(3)))
; __device__ __forceinline__ unsigned cvtpk(float lo, float hi) { typedef __bf16 bf2 __attribute__((ext_vector_type(2))); f32x2 v = {lo, hi}; bf2 b = __builtin_convertvector(v, bf2); return __builtin_bit_cast(unsigned, b); }
; __device__ __forceinline__ void transpose_item(const float* W, int K, int N, bf16_t* WT, int mode, LAS float* scr, int item, int lane) {
;     ...
;     for (int i = 0; i < 32; ++i) { const int kk = 2 * i + (lane >> 5); scr[kk * 33 + (lane & 31)] = W[(size_t)(k0 + kk) * N + n0 + (lane & 31)]; }
;     asm volatile("s_waitcnt lgkmcnt(0)" ::: "memory");
;     const int c = lane & 7;
; #pragma unroll
;     for (int j = 0; j < 4; ++j) { const int n = (lane >> 3) + 8 * j; const LAS float* s = scr + (8 * c) * 33 + n;
;         u32x4 o; o.x = cvtpk(s[0 * 33], s[1 * 33]); o.y = cvtpk(s[2 * 33], s[3 * 33]); o.z = cvtpk(s[4 * 33], s[5 * 33]); o.w = cvtpk(s[6 * 33], s[7 * 33]);
;         *(u32x4*)(WT + (size_t)wrow_map(mode, n0 + n) * K + k0 + 8 * c) = o; }
;     asm volatile("s_waitcnt lgkmcnt(0)" ::: "memory");
	ds_write2_b32 v24, v23, v77 offset1:66
	ds_write2_b32 v24, v86, v87 offset0:132 offset1:198
	v_add_u32_e32 v23, 0x400, v24
	ds_write2_b32 v23, v88, v89 offset0:8 offset1:74
	v_add_u32_e32 v23, v35, v43
	ds_write2_b32 v23, v90, v91 offset1:66
	ds_write2_b32 v23, v92, v93 offset0:132 offset1:198
	v_add_u32_e32 v23, 0x400, v23
	ds_write2_b32 v23, v94, v95 offset0:8 offset1:74
	v_add_u32_e32 v23, v35, v50
	ds_write2_b32 v23, v96, v97 offset1:66
	ds_write2_b32 v23, v98, v99 offset0:132 offset1:198
	v_add_u32_e32 v23, 0x400, v23
	v_or_b32_e32 v90, s36, v72
	s_lshl_b32 s8, s8, 1
	v_ashrrev_i32_e32 v91, 31, v90
	v_lshl_add_u64 v[88:89], v[14:15], 0, s[8:9]
	v_lshlrev_b64 v[90:91], 8, v[90:91]
	v_lshl_add_u64 v[90:91], v[88:89], 0, v[90:91]
	ds_write2_b32 v23, v100, v101 offset0:8 offset1:74
	v_add_u32_e32 v23, v35, v57
	ds_write2_b32 v23, v102, v103 offset1:66
	ds_write2_b32 v23, v104, v105 offset0:132 offset1:198
	v_add_u32_e32 v23, 0x400, v23
	ds_write2_b32 v23, v106, v107 offset0:8 offset1:74
	v_add_u32_e32 v23, v35, v64
	ds_write2_b32 v23, v4, v84 offset1:66
	ds_write2_b32 v23, v85, v108 offset0:132 offset1:198
	v_add_u32_e32 v4, 0x400, v23
	ds_write2_b32 v4, v109, v110 offset0:8 offset1:74
	ds_write2_b32 v4, v111, v112 offset0:140 offset1:206
	s_waitcnt lgkmcnt(0)
	ds_read2_b32 v[28:29], v73 offset0:33 offset1:41
	ds_read2_b32 v[30:31], v73 offset1:8
	ds_read2_b32 v[32:33], v73 offset0:66 offset1:74
	ds_read2_b32 v[78:79], v73 offset0:99 offset1:107
	ds_read2_b32 v[80:81], v73 offset0:132 offset1:140
	ds_read2_b32 v[82:83], v73 offset0:165 offset1:173
	ds_read2_b32 v[84:85], v73 offset0:198 offset1:206
	ds_read2_b32 v[86:87], v73 offset0:231 offset1:239
	s_waitcnt lgkmcnt(6)
	v_cvt_pk_bf16_f32 v24, v30, v28
	s_waitcnt lgkmcnt(4)
	v_cvt_pk_bf16_f32 v25, v32, v78
	s_waitcnt lgkmcnt(2)
	v_cvt_pk_bf16_f32 v26, v80, v82
	v_or_b32_e32 v28, s36, v74
	s_waitcnt lgkmcnt(0)
	v_cvt_pk_bf16_f32 v27, v84, v86
	global_store_dwordx4 v[90:91], v[24:27], off
	s_nop 1
	v_cvt_pk_bf16_f32 v24, v31, v29
	v_ashrrev_i32_e32 v29, 31, v28
	v_cvt_pk_bf16_f32 v25, v33, v79
	v_cvt_pk_bf16_f32 v26, v81, v83
	v_cvt_pk_bf16_f32 v27, v85, v87
	v_lshlrev_b64 v[28:29], 8, v[28:29]
	ds_read2_b32 v[30:31], v73 offset0:49 offset1:57
	ds_read2_b32 v[32:33], v73 offset0:16 offset1:24
	ds_read2_b32 v[78:79], v73 offset0:82 offset1:90
	ds_read2_b32 v[80:81], v73 offset0:115 offset1:123
	ds_read2_b32 v[82:83], v73 offset0:148 offset1:156
	ds_read2_b32 v[84:85], v73 offset0:181 offset1:189
	ds_read2_b32 v[86:87], v73 offset0:214 offset1:222
	ds_read2_b32 v[90:91], v73 offset0:247 offset1:255
	v_lshl_add_u64 v[28:29], v[88:89], 0, v[28:29]
	global_store_dwordx4 v[28:29], v[24:27], off
	v_or_b32_e32 v28, s36, v75
	v_ashrrev_i32_e32 v29, 31, v28
	v_lshlrev_b64 v[28:29], 8, v[28:29]
	s_waitcnt lgkmcnt(6)
	v_cvt_pk_bf16_f32 v24, v32, v30
	s_waitcnt lgkmcnt(4)
	v_cvt_pk_bf16_f32 v25, v78, v80
	s_waitcnt lgkmcnt(2)
	v_cvt_pk_bf16_f32 v26, v82, v84
	s_waitcnt lgkmcnt(0)
	v_cvt_pk_bf16_f32 v27, v86, v90
	v_lshl_add_u64 v[28:29], v[88:89], 0, v[28:29]
	global_store_dwordx4 v[28:29], v[24:27], off
	v_or_b32_e32 v28, s36, v76
	v_ashrrev_i32_e32 v29, 31, v28
	v_lshlrev_b64 v[28:29], 8, v[28:29]
	v_cvt_pk_bf16_f32 v24, v33, v31
	v_cvt_pk_bf16_f32 v25, v79, v81
	v_cvt_pk_bf16_f32 v26, v83, v85
	v_cvt_pk_bf16_f32 v27, v87, v91
	v_lshl_add_u64 v[28:29], v[88:89], 0, v[28:29]
	global_store_dwordx4 v[28:29], v[24:27], off
	s_waitcnt lgkmcnt(0)

; #define LAS __attribute__((address_space(3)))
; __device__ __forceinline__ void transpose_item(const float* W, int K, int N, bf16_t* WT, int mode, LAS float* scr, int item, int lane) {
;     const int nblk = N / 32, kb = item / nblk, nb = item % nblk, k0 = 64 * kb, n0 = 32 * nb;
; #pragma unroll
;     for (int i = 0; i < 32; ++i) { const int kk = 2 * i + (lane >> 5); scr[kk * 33 + (lane & 31)] = W[(size_t)(k0 + kk) * N + n0 + (lane & 31)]; }
; __device__ __forceinline__ void convert_weights(PPtr P, int li, LAS unsigned char* lds, int gw, int NGW, int wave, int lane) {
;     ...
;         if (r < I_UQ) { transpose_item(P->in[16] + (size_t)li * 256 * 768, 256, 768, Wb + W_UQ, 1, scr, r, lane); continue; } r -= I_UQ;
.LBB0_1469:
	s_andn2_b64 vcc, exec, s[36:37]
	s_cbranch_vccnz .LBB0_1487
	s_add_i32 s8, s48, 0xffb0
	s_and_b32 s36, s8, 0xff
	s_mulk_i32 s36, 0xab
	s_load_dwordx2 s[50:51], s[6:7], 0x80
	s_bfe_u32 s37, s36, 0x4000c
	s_mul_i32 s36, s37, 24
	s_sub_i32 s8, s8, s36
	s_and_b32 s36, s8, 0xff
	s_lshl_b32 s8, s37, 6
	s_lshl_b32 s38, s36, 5
	s_lshl_b32 s37, s36, 7
	s_waitcnt lgkmcnt(0)
	s_add_u32 s50, s50, s37
	s_addc_u32 s51, s51, 0
	v_lshlrev_b32_e32 v4, 2, v2
	v_lshl_add_u64 v[24:25], s[50:51], 0, v[4:5]
	v_or_b32_e32 v4, s8, v3
	v_mul_u32_u24_e32 v4, 0x300, v4
	v_lshl_add_u64 v[24:25], v[24:25], 0, s[22:23]
	v_lshlrev_b32_e32 v4, 2, v4
	v_lshl_add_u64 v[26:27], v[24:25], 0, v[4:5]
	v_or_b32_e32 v4, s8, v37
	v_mul_u32_u24_e32 v4, 0x300, v4
	v_lshlrev_b32_e32 v4, 2, v4
	v_lshl_add_u64 v[28:29], v[24:25], 0, v[4:5]
	v_or_b32_e32 v4, s8, v38
	v_mul_u32_u24_e32 v4, 0x300, v4
	v_lshlrev_b32_e32 v4, 2, v4
	v_lshl_add_u64 v[30:31], v[24:25], 0, v[4:5]
	v_or_b32_e32 v4, s8, v39
	v_mul_u32_u24_e32 v4, 0x300, v4
	v_lshlrev_b32_e32 v4, 2, v4
	v_lshl_add_u64 v[32:33], v[24:25], 0, v[4:5]
	v_or_b32_e32 v4, s8, v40
	v_mul_u32_u24_e32 v4, 0x300, v4
	v_lshlrev_b32_e32 v4, 2, v4
	v_lshl_add_u64 v[78:79], v[24:25], 0, v[4:5]
	v_or_b32_e32 v4, s8, v41
	v_mul_u32_u24_e32 v4, 0x300, v4
	v_lshlrev_b32_e32 v4, 2, v4
	v_lshl_add_u64 v[80:81], v[24:25], 0, v[4:5]
	v_or_b32_e32 v4, s8, v42
	v_mul_u32_u24_e32 v4, 0x300, v4
	v_lshlrev_b32_e32 v4, 2, v4
	v_lshl_add_u64 v[82:83], v[24:25], 0, v[4:5]
	v_or_b32_e32 v4, s8, v44
	v_mul_u32_u24_e32 v4, 0x300, v4
	v_lshlrev_b32_e32 v4, 2, v4
	v_lshl_add_u64 v[84:85], v[24:25], 0, v[4:5]
	v_or_b32_e32 v4, s8, v45
	v_mul_u32_u24_e32 v4, 0x300, v4
	v_lshlrev_b32_e32 v4, 2, v4
	global_load_dword v23, v[26:27], off nt
	global_load_dword v77, v[28:29], off nt
	global_load_dword v86, v[30:31], off nt
	global_load_dword v87, v[32:33], off nt
	global_load_dword v88, v[78:79], off nt
	global_load_dword v89, v[80:81], off nt
	global_load_dword v90, v[82:83], off nt
	global_load_dword v91, v[84:85], off nt
	v_lshl_add_u64 v[26:27], v[24:25], 0, v[4:5]
	v_or_b32_e32 v4, s8, v46
	v_mul_u32_u24_e32 v4, 0x300, v4
	v_lshlrev_b32_e32 v4, 2, v4
	v_lshl_add_u64 v[28:29], v[24:25], 0, v[4:5]
	v_or_b32_e32 v4, s8, v47
	v_mul_u32_u24_e32 v4, 0x300, v4
	v_lshlrev_b32_e32 v4, 2, v4
	v_lshl_add_u64 v[30:31], v[24:25], 0, v[4:5]
	v_or_b32_e32 v4, s8, v48
	v_mul_u32_u24_e32 v4, 0x300, v4
	v_lshlrev_b32_e32 v4, 2, v4
	v_lshl_add_u64 v[32:33], v[24:25], 0, v[4:5]
	v_or_b32_e32 v4, s8, v49
	v_mul_u32_u24_e32 v4, 0x300, v4
	v_lshlrev_b32_e32 v4, 2, v4
	v_lshl_add_u64 v[78:79], v[24:25], 0, v[4:5]
	v_or_b32_e32 v4, s8, v51
	v_mul_u32_u24_e32 v4, 0x300, v4
	v_lshlrev_b32_e32 v4, 2, v4
	v_lshl_add_u64 v[80:81], v[24:25], 0, v[4:5]
	v_or_b32_e32 v4, s8, v52
	v_mul_u32_u24_e32 v4, 0x300, v4
	v_lshlrev_b32_e32 v4, 2, v4
	v_lshl_add_u64 v[82:83], v[24:25], 0, v[4:5]
	v_or_b32_e32 v4, s8, v53
	v_mul_u32_u24_e32 v4, 0x300, v4
	v_lshlrev_b32_e32 v4, 2, v4
	v_lshl_add_u64 v[84:85], v[24:25], 0, v[4:5]
	v_or_b32_e32 v4, s8, v54
	v_mul_u32_u24_e32 v4, 0x300, v4
	v_lshlrev_b32_e32 v4, 2, v4
	global_load_dword v92, v[26:27], off nt
	global_load_dword v93, v[28:29], off nt
	global_load_dword v94, v[30:31], off nt
	global_load_dword v95, v[32:33], off nt
	global_load_dword v96, v[78:79], off nt
	global_load_dword v97, v[80:81], off nt
	global_load_dword v98, v[82:83], off nt
	global_load_dword v99, v[84:85], off nt
	v_lshl_add_u64 v[26:27], v[24:25], 0, v[4:5]
	v_or_b32_e32 v4, s8, v55
	v_mul_u32_u24_e32 v4, 0x300, v4
	v_lshlrev_b32_e32 v4, 2, v4
	v_lshl_add_u64 v[28:29], v[24:25], 0, v[4:5]
	v_or_b32_e32 v4, s8, v56
	v_mul_u32_u24_e32 v4, 0x300, v4
	v_lshlrev_b32_e32 v4, 2, v4
	v_lshl_add_u64 v[30:31], v[24:25], 0, v[4:5]
	v_or_b32_e32 v4, s8, v58
	v_mul_u32_u24_e32 v4, 0x300, v4
	v_lshlrev_b32_e32 v4, 2, v4
	v_lshl_add_u64 v[32:33], v[24:25], 0, v[4:5]
	v_or_b32_e32 v4, s8, v59
	v_mul_u32_u24_e32 v4, 0x300, v4
	v_lshlrev_b32_e32 v4, 2, v4
	v_lshl_add_u64 v[78:79], v[24:25], 0, v[4:5]
	v_or_b32_e32 v4, s8, v60
	v_mul_u32_u24_e32 v4, 0x300, v4
	v_lshlrev_b32_e32 v4, 2, v4
	v_lshl_add_u64 v[80:81], v[24:25], 0, v[4:5]
	v_or_b32_e32 v4, s8, v61
	v_mul_u32_u24_e32 v4, 0x300, v4
	v_lshlrev_b32_e32 v4, 2, v4
	v_lshl_add_u64 v[82:83], v[24:25], 0, v[4:5]
	v_or_b32_e32 v4, s8, v62
	v_mul_u32_u24_e32 v4, 0x300, v4
	v_lshlrev_b32_e32 v4, 2, v4
	v_lshl_add_u64 v[84:85], v[24:25], 0, v[4:5]
	v_or_b32_e32 v4, s8, v63
	v_mul_u32_u24_e32 v4, 0x300, v4
	v_lshlrev_b32_e32 v4, 2, v4
	global_load_dword v100, v[26:27], off nt
	global_load_dword v101, v[28:29], off nt
	global_load_dword v102, v[30:31], off nt
	global_load_dword v103, v[32:33], off nt
	global_load_dword v104, v[78:79], off nt
	global_load_dword v105, v[80:81], off nt
	global_load_dword v106, v[82:83], off nt
	global_load_dword v107, v[84:85], off nt
	v_lshl_add_u64 v[26:27], v[24:25], 0, v[4:5]
	v_or_b32_e32 v4, s8, v65
	v_mul_u32_u24_e32 v4, 0x300, v4
	v_lshlrev_b32_e32 v4, 2, v4
	v_lshl_add_u64 v[28:29], v[24:25], 0, v[4:5]
	v_or_b32_e32 v4, s8, v66
	v_mul_u32_u24_e32 v4, 0x300, v4
	v_lshlrev_b32_e32 v4, 2, v4
	v_lshl_add_u64 v[30:31], v[24:25], 0, v[4:5]
	v_or_b32_e32 v4, s8, v67
	v_mul_u32_u24_e32 v4, 0x300, v4
	v_lshlrev_b32_e32 v4, 2, v4
	v_lshl_add_u64 v[32:33], v[24:25], 0, v[4:5]
	v_or_b32_e32 v4, s8, v68
	v_mul_u32_u24_e32 v4, 0x300, v4
	v_lshlrev_b32_e32 v4, 2, v4
	v_lshl_add_u64 v[78:79], v[24:25], 0, v[4:5]
	v_or_b32_e32 v4, s8, v69
	v_mul_u32_u24_e32 v4, 0x300, v4
	v_lshlrev_b32_e32 v4, 2, v4
	v_lshl_add_u64 v[80:81], v[24:25], 0, v[4:5]
	v_or_b32_e32 v4, s8, v70
	v_mul_u32_u24_e32 v4, 0x300, v4
	v_lshlrev_b32_e32 v4, 2, v4
	v_lshl_add_u64 v[82:83], v[24:25], 0, v[4:5]
	v_or_b32_e32 v4, s8, v71
	v_mul_u32_u24_e32 v4, 0x300, v4
	v_lshlrev_b32_e32 v4, 2, v4
	v_lshl_add_u64 v[24:25], v[24:25], 0, v[4:5]
	global_load_dword v4, v[26:27], off nt
	global_load_dword v84, v[28:29], off nt
	global_load_dword v85, v[30:31], off nt
	global_load_dword v108, v[32:33], off nt
	global_load_dword v109, v[78:79], off nt
	global_load_dword v110, v[80:81], off nt
	global_load_dword v111, v[82:83], off nt
	global_load_dword v112, v[24:25], off nt
	v_add_u32_e32 v24, v35, v36
	s_waitcnt vmcnt(0)
; #define LAS __attribute__((address_space(3)))
; __device__ __forceinline__ unsigned cvtpk(float lo, float hi) { typedef __bf16 bf2 __attribute__((ext_vector_type(2))); f32x2 v = {lo, hi}; bf2 b = __builtin_convertvector(v, bf2); return __builtin_bit_cast(unsigned, b); }
; __device__ __forceinline__ int wrow_map(int mode, int n) {
;     if (mode == 1) { const int hd = n / 96, w = n % 96; return w < 64 ? hd * 64 + w : 512 + hd * 32 + 2 * ((w - 64) & 15) + ((w - 64) >> 4); }
; __device__ __forceinline__ void transpose_item(const float* W, int K, int N, bf16_t* WT, int mode, LAS float* scr, int item, int lane) {
;     ...
;     for (int i = 0; i < 32; ++i) { const int kk = 2 * i + (lane >> 5); scr[kk * 33 + (lane & 31)] = W[(size_t)(k0 + kk) * N + n0 + (lane & 31)]; }
;     asm volatile("s_waitcnt lgkmcnt(0)" ::: "memory");
;     const int c = lane & 7;
; #pragma unroll
;     for (int j = 0; j < 4; ++j) { const int n = (lane >> 3) + 8 * j; const LAS float* s = scr + (8 * c) * 33 + n;
;         u32x4 o; o.x = cvtpk(s[0 * 33], s[1 * 33]); o.y = cvtpk(s[2 * 33], s[3 * 33]); o.z = cvtpk(s[4 * 33], s[5 * 33]); o.w = cvtpk(s[6 * 33], s[7 * 33]);
;         *(u32x4*)(WT + (size_t)wrow_map(mode, n0 + n) * K + k0 + 8 * c) = o; }
;     asm volatile("s_waitcnt lgkmcnt(0)" ::: "memory");
	ds_write2_b32 v24, v23, v77 offset1:66
	ds_write2_b32 v24, v86, v87 offset0:132 offset1:198
	v_add_u32_e32 v23, 0x400, v24
	ds_write2_b32 v23, v88, v89 offset0:8 offset1:74
	v_add_u32_e32 v23, v35, v43
	ds_write2_b32 v23, v90, v91 offset1:66
	ds_write2_b32 v23, v92, v93 offset0:132 offset1:198
	v_add_u32_e32 v23, 0x400, v23
	ds_write2_b32 v23, v94, v95 offset0:8 offset1:74
	v_add_u32_e32 v23, v35, v50
	ds_write2_b32 v23, v96, v97 offset1:66
	ds_write2_b32 v23, v98, v99 offset0:132 offset1:198
	v_add_u32_e32 v23, 0x400, v23
	s_mulk_i32 s36, 0xab
	s_bfe_u32 s39, s36, 0x70009
	ds_write2_b32 v23, v100, v101 offset0:8 offset1:74
	v_add_u32_e32 v23, v35, v57
	ds_write2_b32 v23, v102, v103 offset1:66
	ds_write2_b32 v23, v104, v105 offset0:132 offset1:198
	v_add_u32_e32 v23, 0x400, v23
	ds_write2_b32 v23, v106, v107 offset0:8 offset1:74
	v_add_u32_e32 v23, v35, v64
	ds_write2_b32 v23, v4, v84 offset1:66
	ds_write2_b32 v23, v85, v108 offset0:132 offset1:198
	v_add_u32_e32 v4, 0x400, v23
	ds_write2_b32 v4, v109, v110 offset0:8 offset1:74
	ds_write2_b32 v4, v111, v112 offset0:140 offset1:206
	s_waitcnt lgkmcnt(0)
	ds_read2_b32 v[26:27], v73 offset1:33
	ds_read2_b32 v[28:29], v73 offset0:66 offset1:99
	ds_read2_b32 v[30:31], v73 offset0:132 offset1:165
	ds_read2_b32 v[32:33], v73 offset0:198 offset1:231
	v_or_b32_e32 v4, s38, v72
	v_mul_hi_u32 v23, v4, s45
	v_mul_u32_u24_e32 v23, 0x60, v23
	v_sub_u32_e32 v23, v4, v23
	v_cmp_lt_u32_e32 vcc, 63, v23
	s_and_saveexec_b64 s[36:37], vcc
	s_xor_b64 s[36:37], exec, s[36:37]
	v_subrev_u32_e32 v4, 64, v23
	v_lshlrev_b32_e32 v23, 1, v23
	v_and_b32_e32 v23, 14, v23
	v_lshrrev_b32_e32 v4, 4, v4
	v_lshl_or_b32 v23, s39, 5, v23
	v_add3_u32 v4, v4, v23, s46
	s_andn2_saveexec_b64 s[36:37], s[36:37]
	v_lshl_or_b32 v4, s39, 6, v23
	s_or_b64 exec, exec, s[36:37]
	s_lshl_b32 s8, s8, 1
	v_lshl_add_u64 v[24:25], v[16:17], 0, s[8:9]
	s_waitcnt lgkmcnt(3)
	v_cvt_pk_bf16_f32 v26, v26, v27
	s_waitcnt lgkmcnt(2)
	v_cvt_pk_bf16_f32 v27, v28, v29
	s_waitcnt lgkmcnt(1)
	v_cvt_pk_bf16_f32 v28, v30, v31
	v_lshlrev_b64 v[30:31], 9, v[4:5]
	s_waitcnt lgkmcnt(0)
	v_cvt_pk_bf16_f32 v29, v32, v33
	v_lshl_add_u64 v[30:31], v[24:25], 0, v[30:31]
	global_store_dwordx4 v[30:31], v[26:29], off
	ds_read2_b32 v[26:27], v73 offset0:8 offset1:41
	ds_read2_b32 v[28:29], v73 offset0:74 offset1:107
	ds_read2_b32 v[30:31], v73 offset0:140 offset1:173
	ds_read2_b32 v[32:33], v73 offset0:206 offset1:239
	v_or_b32_e32 v4, s38, v74
	v_mul_hi_u32 v23, v4, s45
	v_mul_u32_u24_e32 v23, 0x60, v23
	v_sub_u32_e32 v23, v4, v23
	v_cmp_lt_u32_e32 vcc, 63, v23
	s_and_saveexec_b64 s[36:37], vcc
	s_xor_b64 s[36:37], exec, s[36:37]
	v_subrev_u32_e32 v4, 64, v23
	v_lshlrev_b32_e32 v23, 1, v23
	v_and_b32_e32 v23, 30, v23
	v_lshrrev_b32_e32 v4, 4, v4
	v_lshl_or_b32 v23, s39, 5, v23
	v_add3_u32 v4, v4, v23, s46
	s_andn2_saveexec_b64 s[36:37], s[36:37]
	v_lshl_or_b32 v4, s39, 6, v23
	s_or_b64 exec, exec, s[36:37]
	s_waitcnt lgkmcnt(3)
	v_cvt_pk_bf16_f32 v26, v26, v27
	s_waitcnt lgkmcnt(2)
	v_cvt_pk_bf16_f32 v27, v28, v29
	s_waitcnt lgkmcnt(1)
	v_cvt_pk_bf16_f32 v28, v30, v31
	v_lshlrev_b64 v[30:31], 9, v[4:5]
	s_waitcnt lgkmcnt(0)
	v_cvt_pk_bf16_f32 v29, v32, v33
	v_lshl_add_u64 v[30:31], v[24:25], 0, v[30:31]
	global_store_dwordx4 v[30:31], v[26:29], off
	ds_read2_b32 v[26:27], v73 offset0:16 offset1:49
	ds_read2_b32 v[28:29], v73 offset0:82 offset1:115
	ds_read2_b32 v[30:31], v73 offset0:148 offset1:181
	ds_read2_b32 v[32:33], v73 offset0:214 offset1:247
	v_or_b32_e32 v4, s38, v75
	v_mul_hi_u32 v23, v4, s45
	v_mul_u32_u24_e32 v23, 0x60, v23
	v_sub_u32_e32 v23, v4, v23
	v_cmp_lt_u32_e32 vcc, 63, v23
	s_and_saveexec_b64 s[36:37], vcc
	s_xor_b64 s[36:37], exec, s[36:37]
	v_subrev_u32_e32 v4, 64, v23
	v_lshlrev_b32_e32 v23, 1, v23
	v_and_b32_e32 v23, 14, v23
	v_lshrrev_b32_e32 v4, 4, v4
	v_lshl_or_b32 v23, s39, 5, v23
	v_add3_u32 v4, v4, v23, s46
	s_andn2_saveexec_b64 s[36:37], s[36:37]
	v_lshl_or_b32 v4, s39, 6, v23
	s_or_b64 exec, exec, s[36:37]
	s_waitcnt lgkmcnt(3)
	v_cvt_pk_bf16_f32 v26, v26, v27
	s_waitcnt lgkmcnt(2)
	v_cvt_pk_bf16_f32 v27, v28, v29
	s_waitcnt lgkmcnt(1)
	v_cvt_pk_bf16_f32 v28, v30, v31
	v_lshlrev_b64 v[30:31], 9, v[4:5]
	s_waitcnt lgkmcnt(0)
	v_cvt_pk_bf16_f32 v29, v32, v33
	v_lshl_add_u64 v[30:31], v[24:25], 0, v[30:31]
	global_store_dwordx4 v[30:31], v[26:29], off
	ds_read2_b32 v[26:27], v73 offset0:24 offset1:57
	ds_read2_b32 v[28:29], v73 offset0:90 offset1:123
	ds_read2_b32 v[30:31], v73 offset0:156 offset1:189
	ds_read2_b32 v[32:33], v73 offset0:222 offset1:255
	v_or_b32_e32 v4, s38, v76
	v_mul_hi_u32 v23, v4, s45
	v_mul_u32_u24_e32 v23, 0x60, v23
	v_sub_u32_e32 v23, v4, v23
	v_cmp_lt_u32_e32 vcc, 63, v23
	s_and_saveexec_b64 s[36:37], vcc
	s_xor_b64 s[36:37], exec, s[36:37]
	v_subrev_u32_e32 v4, 64, v23
	v_lshlrev_b32_e32 v23, 1, v23
	v_and_b32_e32 v23, 30, v23
	v_lshrrev_b32_e32 v4, 4, v4
	v_lshl_or_b32 v23, s39, 5, v23
	v_add3_u32 v4, v4, v23, s46
	s_andn2_saveexec_b64 s[36:37], s[36:37]
	v_lshl_or_b32 v4, s39, 6, v23
	s_or_b64 exec, exec, s[36:37]
	s_waitcnt lgkmcnt(3)
	v_cvt_pk_bf16_f32 v26, v26, v27
	s_waitcnt lgkmcnt(2)
	v_cvt_pk_bf16_f32 v27, v28, v29
	s_waitcnt lgkmcnt(1)
	v_cvt_pk_bf16_f32 v28, v30, v31
	v_lshlrev_b64 v[30:31], 9, v[4:5]
	s_waitcnt lgkmcnt(0)
	v_cvt_pk_bf16_f32 v29, v32, v33
	v_lshl_add_u64 v[24:25], v[24:25], 0, v[30:31]
	global_store_dwordx4 v[24:25], v[26:29], off
	s_waitcnt lgkmcnt(0)

; #define LAS __attribute__((address_space(3)))
; __device__ __forceinline__ void transpose_item(const float* W, int K, int N, bf16_t* WT, int mode, LAS float* scr, int item, int lane) {
;     const int nblk = N / 32, kb = item / nblk, nb = item % nblk, k0 = 64 * kb, n0 = 32 * nb;
; #pragma unroll
;     for (int i = 0; i < 32; ++i) { const int kk = 2 * i + (lane >> 5); scr[kk * 33 + (lane & 31)] = W[(size_t)(k0 + kk) * N + n0 + (lane & 31)]; }
; __device__ __forceinline__ void convert_weights(PPtr P, int li, LAS unsigned char* lds, int gw, int NGW, int wave, int lane) {
;     ...
;         if (r < I_GATE) { transpose_item(P->in[6] + (size_t)li * 1024 * 4096, 1024, 4096, Wb + W_GATE, 0, scr, r, lane); continue; } r -= I_GATE;
.LBB0_1488:
	s_andn2_b64 vcc, exec, s[36:37]
	s_cbranch_vccnz .LBB0_1490
	s_load_dwordx2 s[38:39], s[6:7], 0x30
	s_add_i32 s8, s48, 0xfffff9b0
	s_add_i32 s36, s41, 0xffff3600
	s_lshr_b32 s8, s8, 1
	s_and_b32 s36, s36, 0xfe0
	s_and_b32 s8, s8, 0x7fc0
	s_lshl_b32 s37, s36, 2
	s_waitcnt lgkmcnt(0)
	s_add_u32 s38, s38, s37
	s_addc_u32 s39, s39, 0
	v_lshlrev_b32_e32 v4, 2, v2
	v_lshl_add_u64 v[24:25], s[38:39], 0, v[4:5]
	v_or_b32_e32 v4, s8, v3
	v_lshl_add_u64 v[24:25], v[24:25], 0, s[10:11]
	v_lshlrev_b32_e32 v4, 14, v4
	v_lshl_add_u64 v[26:27], v[24:25], 0, v[4:5]
	v_or_b32_e32 v4, s8, v37
	v_lshlrev_b32_e32 v4, 14, v4
	v_lshl_add_u64 v[28:29], v[24:25], 0, v[4:5]
	v_or_b32_e32 v4, s8, v38
	v_lshlrev_b32_e32 v4, 14, v4
	v_lshl_add_u64 v[30:31], v[24:25], 0, v[4:5]
	v_or_b32_e32 v4, s8, v39
	v_lshlrev_b32_e32 v4, 14, v4
	v_lshl_add_u64 v[32:33], v[24:25], 0, v[4:5]
	v_or_b32_e32 v4, s8, v40
	v_lshlrev_b32_e32 v4, 14, v4
	v_lshl_add_u64 v[78:79], v[24:25], 0, v[4:5]
	v_or_b32_e32 v4, s8, v41
	v_lshlrev_b32_e32 v4, 14, v4
	v_lshl_add_u64 v[80:81], v[24:25], 0, v[4:5]
	v_or_b32_e32 v4, s8, v42
	v_lshlrev_b32_e32 v4, 14, v4
	v_lshl_add_u64 v[82:83], v[24:25], 0, v[4:5]
	v_or_b32_e32 v4, s8, v44
	v_lshlrev_b32_e32 v4, 14, v4
	v_lshl_add_u64 v[84:85], v[24:25], 0, v[4:5]
	v_or_b32_e32 v4, s8, v45
	v_lshlrev_b32_e32 v4, 14, v4
	global_load_dword v23, v[26:27], off nt
	global_load_dword v77, v[28:29], off nt
	global_load_dword v86, v[30:31], off nt
	global_load_dword v87, v[32:33], off nt
	global_load_dword v88, v[78:79], off nt
	global_load_dword v89, v[80:81], off nt
	global_load_dword v90, v[82:83], off nt
	global_load_dword v91, v[84:85], off nt
	v_lshl_add_u64 v[26:27], v[24:25], 0, v[4:5]
	v_or_b32_e32 v4, s8, v46
	v_lshlrev_b32_e32 v4, 14, v4
	v_lshl_add_u64 v[28:29], v[24:25], 0, v[4:5]
	v_or_b32_e32 v4, s8, v47
	v_lshlrev_b32_e32 v4, 14, v4
	v_lshl_add_u64 v[30:31], v[24:25], 0, v[4:5]
	v_or_b32_e32 v4, s8, v48
	v_lshlrev_b32_e32 v4, 14, v4
	v_lshl_add_u64 v[32:33], v[24:25], 0, v[4:5]
	v_or_b32_e32 v4, s8, v49
	v_lshlrev_b32_e32 v4, 14, v4
	v_lshl_add_u64 v[78:79], v[24:25], 0, v[4:5]
	v_or_b32_e32 v4, s8, v51
	v_lshlrev_b32_e32 v4, 14, v4
	v_lshl_add_u64 v[80:81], v[24:25], 0, v[4:5]
	v_or_b32_e32 v4, s8, v52
	v_lshlrev_b32_e32 v4, 14, v4
	v_lshl_add_u64 v[82:83], v[24:25], 0, v[4:5]
	v_or_b32_e32 v4, s8, v53
	v_lshlrev_b32_e32 v4, 14, v4
	v_lshl_add_u64 v[84:85], v[24:25], 0, v[4:5]
	v_or_b32_e32 v4, s8, v54
	v_lshlrev_b32_e32 v4, 14, v4
	global_load_dword v92, v[26:27], off nt
	global_load_dword v93, v[28:29], off nt
	global_load_dword v94, v[30:31], off nt
	global_load_dword v95, v[32:33], off nt
	global_load_dword v96, v[78:79], off nt
	global_load_dword v97, v[80:81], off nt
	global_load_dword v98, v[82:83], off nt
	global_load_dword v99, v[84:85], off nt
	v_lshl_add_u64 v[26:27], v[24:25], 0, v[4:5]
	v_or_b32_e32 v4, s8, v55
	v_lshlrev_b32_e32 v4, 14, v4
	v_lshl_add_u64 v[28:29], v[24:25], 0, v[4:5]
	v_or_b32_e32 v4, s8, v56
	v_lshlrev_b32_e32 v4, 14, v4
	v_lshl_add_u64 v[30:31], v[24:25], 0, v[4:5]
	v_or_b32_e32 v4, s8, v58
	v_lshlrev_b32_e32 v4, 14, v4
	v_lshl_add_u64 v[32:33], v[24:25], 0, v[4:5]
	v_or_b32_e32 v4, s8, v59
	v_lshlrev_b32_e32 v4, 14, v4
	v_lshl_add_u64 v[78:79], v[24:25], 0, v[4:5]
	v_or_b32_e32 v4, s8, v60
	v_lshlrev_b32_e32 v4, 14, v4
	v_lshl_add_u64 v[80:81], v[24:25], 0, v[4:5]
	v_or_b32_e32 v4, s8, v61
	v_lshlrev_b32_e32 v4, 14, v4
	v_lshl_add_u64 v[82:83], v[24:25], 0, v[4:5]
	v_or_b32_e32 v4, s8, v62
	v_lshlrev_b32_e32 v4, 14, v4
	v_lshl_add_u64 v[84:85], v[24:25], 0, v[4:5]
	v_or_b32_e32 v4, s8, v63
	v_lshlrev_b32_e32 v4, 14, v4
	global_load_dword v100, v[26:27], off nt
	global_load_dword v101, v[28:29], off nt
	global_load_dword v102, v[30:31], off nt
	global_load_dword v103, v[32:33], off nt
	global_load_dword v104, v[78:79], off nt
	global_load_dword v105, v[80:81], off nt
	global_load_dword v106, v[82:83], off nt
	global_load_dword v107, v[84:85], off nt
	v_lshl_add_u64 v[26:27], v[24:25], 0, v[4:5]
	v_or_b32_e32 v4, s8, v65
	v_lshlrev_b32_e32 v4, 14, v4
	v_lshl_add_u64 v[28:29], v[24:25], 0, v[4:5]
	v_or_b32_e32 v4, s8, v66
	v_lshlrev_b32_e32 v4, 14, v4
	v_lshl_add_u64 v[30:31], v[24:25], 0, v[4:5]
	v_or_b32_e32 v4, s8, v67
	v_lshlrev_b32_e32 v4, 14, v4
	v_lshl_add_u64 v[32:33], v[24:25], 0, v[4:5]
	v_or_b32_e32 v4, s8, v68
	v_lshlrev_b32_e32 v4, 14, v4
	v_lshl_add_u64 v[78:79], v[24:25], 0, v[4:5]
	v_or_b32_e32 v4, s8, v69
	v_lshlrev_b32_e32 v4, 14, v4
	v_lshl_add_u64 v[80:81], v[24:25], 0, v[4:5]
	v_or_b32_e32 v4, s8, v70
	v_lshlrev_b32_e32 v4, 14, v4
	v_lshl_add_u64 v[82:83], v[24:25], 0, v[4:5]
	v_or_b32_e32 v4, s8, v71
	v_lshlrev_b32_e32 v4, 14, v4
	v_lshl_add_u64 v[24:25], v[24:25], 0, v[4:5]
	global_load_dword v4, v[26:27], off nt
	global_load_dword v84, v[28:29], off nt
	global_load_dword v85, v[30:31], off nt
	global_load_dword v108, v[32:33], off nt
	global_load_dword v109, v[78:79], off nt
	global_load_dword v110, v[80:81], off nt
	global_load_dword v111, v[82:83], off nt
	global_load_dword v112, v[24:25], off nt
	v_add_u32_e32 v24, v35, v36
	s_waitcnt vmcnt(0)
; #define LAS __attribute__((address_space(3)))
; __device__ __forceinline__ unsigned cvtpk(float lo, float hi) { typedef __bf16 bf2 __attribute__((ext_vector_type(2))); f32x2 v = {lo, hi}; bf2 b = __builtin_convertvector(v, bf2); return __builtin_bit_cast(unsigned, b); }
; __device__ __forceinline__ void transpose_item(const float* W, int K, int N, bf16_t* WT, int mode, LAS float* scr, int item, int lane) {
;     ...
;     for (int i = 0; i < 32; ++i) { const int kk = 2 * i + (lane >> 5); scr[kk * 33 + (lane & 31)] = W[(size_t)(k0 + kk) * N + n0 + (lane & 31)]; }
;     asm volatile("s_waitcnt lgkmcnt(0)" ::: "memory");
;     const int c = lane & 7;
; #pragma unroll
;     for (int j = 0; j < 4; ++j) { const int n = (lane >> 3) + 8 * j; const LAS float* s = scr + (8 * c) * 33 + n;
;         u32x4 o; o.x = cvtpk(s[0 * 33], s[1 * 33]); o.y = cvtpk(s[2 * 33], s[3 * 33]); o.z = cvtpk(s[4 * 33], s[5 * 33]); o.w = cvtpk(s[6 * 33], s[7 * 33]);
;         *(u32x4*)(WT + (size_t)wrow_map(mode, n0 + n) * K + k0 + 8 * c) = o; }
;     asm volatile("s_waitcnt lgkmcnt(0)" ::: "memory");
	ds_write2_b32 v24, v23, v77 offset1:66
	ds_write2_b32 v24, v86, v87 offset0:132 offset1:198
	v_add_u32_e32 v23, 0x400, v24
	ds_write2_b32 v23, v88, v89 offset0:8 offset1:74
	v_add_u32_e32 v23, v35, v43
	ds_write2_b32 v23, v90, v91 offset1:66
	ds_write2_b32 v23, v92, v93 offset0:132 offset1:198
	v_add_u32_e32 v23, 0x400, v23
	ds_write2_b32 v23, v94, v95 offset0:8 offset1:74
	v_add_u32_e32 v23, v35, v50
	ds_write2_b32 v23, v96, v97 offset1:66
	ds_write2_b32 v23, v98, v99 offset0:132 offset1:198
	v_add_u32_e32 v23, 0x400, v23
	s_lshl_b32 s8, s8, 1
	v_lshl_add_u64 v[88:89], v[18:19], 0, s[8:9]
	ds_write2_b32 v23, v100, v101 offset0:8 offset1:74
	v_add_u32_e32 v23, v35, v57
	ds_write2_b32 v23, v102, v103 offset1:66
	ds_write2_b32 v23, v104, v105 offset0:132 offset1:198
	v_add_u32_e32 v23, 0x400, v23
	ds_write2_b32 v23, v106, v107 offset0:8 offset1:74
	v_add_u32_e32 v23, v35, v64
	ds_write2_b32 v23, v4, v84 offset1:66
	ds_write2_b32 v23, v85, v108 offset0:132 offset1:198
	v_add_u32_e32 v4, 0x400, v23
	ds_write2_b32 v4, v109, v110 offset0:8 offset1:74
	ds_write2_b32 v4, v111, v112 offset0:140 offset1:206
	s_waitcnt lgkmcnt(0)
	ds_read2_b32 v[28:29], v73 offset0:33 offset1:41
	ds_read2_b32 v[30:31], v73 offset1:8
	ds_read2_b32 v[32:33], v73 offset0:66 offset1:74
	ds_read2_b32 v[78:79], v73 offset0:99 offset1:107
	ds_read2_b32 v[80:81], v73 offset0:132 offset1:140
	ds_read2_b32 v[82:83], v73 offset0:165 offset1:173
	ds_read2_b32 v[84:85], v73 offset0:198 offset1:206
	ds_read2_b32 v[86:87], v73 offset0:231 offset1:239
	v_or_b32_e32 v4, s36, v72
	v_lshlrev_b32_e32 v4, 11, v4
	s_waitcnt lgkmcnt(6)
	v_cvt_pk_bf16_f32 v24, v30, v28
	s_waitcnt lgkmcnt(4)
	v_cvt_pk_bf16_f32 v25, v32, v78
	s_waitcnt lgkmcnt(2)
	v_cvt_pk_bf16_f32 v26, v80, v82
	s_waitcnt lgkmcnt(0)
	v_cvt_pk_bf16_f32 v27, v84, v86
	v_lshl_add_u64 v[90:91], v[88:89], 0, v[4:5]
	global_store_dwordx4 v[90:91], v[24:27], off
	v_or_b32_e32 v4, s36, v74
	v_lshlrev_b32_e32 v4, 11, v4
	v_cvt_pk_bf16_f32 v24, v31, v29
	v_cvt_pk_bf16_f32 v25, v33, v79
	v_cvt_pk_bf16_f32 v26, v81, v83
	v_cvt_pk_bf16_f32 v27, v85, v87
	ds_read2_b32 v[30:31], v73 offset0:49 offset1:57
	ds_read2_b32 v[32:33], v73 offset0:16 offset1:24
	ds_read2_b32 v[78:79], v73 offset0:82 offset1:90
	ds_read2_b32 v[80:81], v73 offset0:115 offset1:123
	ds_read2_b32 v[82:83], v73 offset0:148 offset1:156
	ds_read2_b32 v[84:85], v73 offset0:181 offset1:189
	ds_read2_b32 v[86:87], v73 offset0:214 offset1:222
	ds_read2_b32 v[90:91], v73 offset0:247 offset1:255
	v_lshl_add_u64 v[28:29], v[88:89], 0, v[4:5]
	v_or_b32_e32 v4, s36, v75
	v_lshlrev_b32_e32 v4, 11, v4
	global_store_dwordx4 v[28:29], v[24:27], off
	v_lshl_add_u64 v[28:29], v[88:89], 0, v[4:5]
	v_or_b32_e32 v4, s36, v76
	s_waitcnt lgkmcnt(6)
	v_cvt_pk_bf16_f32 v24, v32, v30
	s_waitcnt lgkmcnt(4)
	v_cvt_pk_bf16_f32 v25, v78, v80
	s_waitcnt lgkmcnt(2)
	v_cvt_pk_bf16_f32 v26, v82, v84
	s_waitcnt lgkmcnt(0)
	v_cvt_pk_bf16_f32 v27, v86, v90
	v_lshlrev_b32_e32 v4, 11, v4
	global_store_dwordx4 v[28:29], v[24:27], off
	v_lshl_add_u64 v[28:29], v[88:89], 0, v[4:5]
	s_nop 0
	v_cvt_pk_bf16_f32 v24, v33, v31
	v_cvt_pk_bf16_f32 v25, v79, v81
	v_cvt_pk_bf16_f32 v26, v83, v85
	v_cvt_pk_bf16_f32 v27, v87, v91
	global_store_dwordx4 v[28:29], v[24:27], off
	s_waitcnt lgkmcnt(0)

; #define LAS __attribute__((address_space(3)))
; __device__ __forceinline__ void transpose_item(const float* W, int K, int N, bf16_t* WT, int mode, LAS float* scr, int item, int lane) {
;     const int nblk = N / 32, kb = item / nblk, nb = item % nblk, k0 = 64 * kb, n0 = 32 * nb;
; #pragma unroll
;     for (int i = 0; i < 32; ++i) { const int kk = 2 * i + (lane >> 5); scr[kk * 33 + (lane & 31)] = W[(size_t)(k0 + kk) * N + n0 + (lane & 31)]; }
; __device__ __forceinline__ void convert_weights(PPtr P, int li, LAS unsigned char* lds, int gw, int NGW, int wave, int lane) {
;     ...
;         if (r < I_IN) { transpose_item(P->in[5] + (size_t)li * 1024 * 3232, 1024, 3232, Wb + W_IN, 0, scr, r, lane); continue; } r -= I_IN;
.LBB0_1491:
	s_andn2_b64 vcc, exec, s[36:37]
	s_cbranch_vccnz .LBB0_1444
	s_mul_hi_i32 s8, s48, 0x288df0cb
	s_lshr_b32 s36, s8, 31
	s_ashr_i32 s8, s8, 4
	s_load_dwordx2 s[50:51], s[6:7], 0x28
	s_add_i32 s8, s8, s36
	s_lshl_b32 s38, s8, 6
	s_mulk_i32 s8, 0xf360
	s_add_i32 s36, s41, s8
	s_ashr_i32 s37, s36, 31
	s_lshl_b64 s[52:53], s[36:37], 2
	s_waitcnt lgkmcnt(0)
	s_add_u32 s50, s50, s52
	s_addc_u32 s51, s51, s53
	v_lshlrev_b32_e32 v4, 2, v2
	v_lshl_add_u64 v[24:25], s[50:51], 0, v[4:5]
	v_lshl_add_u64 v[24:25], v[24:25], 0, s[34:35]
	v_or_b32_e32 v4, s38, v3
	v_mad_i64_i32 v[26:27], s[50:51], v4, s47, v[24:25]
	v_or_b32_e32 v4, s38, v37
	v_mad_i64_i32 v[28:29], s[50:51], v4, s47, v[24:25]
	v_or_b32_e32 v4, s38, v38
	v_mad_i64_i32 v[30:31], s[50:51], v4, s47, v[24:25]
	v_or_b32_e32 v4, s38, v39
	v_mad_i64_i32 v[32:33], s[50:51], v4, s47, v[24:25]
	v_or_b32_e32 v4, s38, v40
	v_mad_i64_i32 v[78:79], s[50:51], v4, s47, v[24:25]
	v_or_b32_e32 v4, s38, v41
	v_mad_i64_i32 v[80:81], s[50:51], v4, s47, v[24:25]
	v_or_b32_e32 v4, s38, v42
	v_mad_i64_i32 v[82:83], s[50:51], v4, s47, v[24:25]
	v_or_b32_e32 v4, s38, v44
	v_mad_i64_i32 v[84:85], s[50:51], v4, s47, v[24:25]
	global_load_dword v4, v[26:27], off nt
	global_load_dword v23, v[28:29], off nt
	global_load_dword v77, v[30:31], off nt
	global_load_dword v86, v[32:33], off nt
	global_load_dword v87, v[78:79], off nt
	global_load_dword v88, v[80:81], off nt
	global_load_dword v89, v[82:83], off nt
	global_load_dword v90, v[84:85], off nt
	v_or_b32_e32 v26, s38, v45
	v_mad_i64_i32 v[26:27], s[50:51], v26, s47, v[24:25]
	v_or_b32_e32 v28, s38, v46
	v_or_b32_e32 v30, s38, v47
	v_or_b32_e32 v32, s38, v48
	v_or_b32_e32 v78, s38, v49
	v_or_b32_e32 v80, s38, v51
	v_or_b32_e32 v82, s38, v52
	v_or_b32_e32 v84, s38, v53
	v_mad_i64_i32 v[28:29], s[50:51], v28, s47, v[24:25]
	v_mad_i64_i32 v[30:31], s[50:51], v30, s47, v[24:25]
	v_mad_i64_i32 v[32:33], s[50:51], v32, s47, v[24:25]
	v_mad_i64_i32 v[78:79], s[50:51], v78, s47, v[24:25]
	v_mad_i64_i32 v[80:81], s[50:51], v80, s47, v[24:25]
	v_mad_i64_i32 v[82:83], s[50:51], v82, s47, v[24:25]
	v_mad_i64_i32 v[84:85], s[50:51], v84, s47, v[24:25]
	global_load_dword v91, v[26:27], off nt
	global_load_dword v92, v[28:29], off nt
	global_load_dword v93, v[30:31], off nt
	global_load_dword v94, v[32:33], off nt
	global_load_dword v95, v[78:79], off nt
	global_load_dword v96, v[80:81], off nt
	global_load_dword v97, v[82:83], off nt
	global_load_dword v98, v[84:85], off nt
	v_or_b32_e32 v26, s38, v54
	v_mad_i64_i32 v[26:27], s[50:51], v26, s47, v[24:25]
	v_or_b32_e32 v28, s38, v55
	v_or_b32_e32 v30, s38, v56
	v_or_b32_e32 v32, s38, v58
	v_or_b32_e32 v78, s38, v59
	v_or_b32_e32 v80, s38, v60
	v_or_b32_e32 v82, s38, v61
	v_or_b32_e32 v84, s38, v62
	v_mad_i64_i32 v[28:29], s[50:51], v28, s47, v[24:25]
	v_mad_i64_i32 v[30:31], s[50:51], v30, s47, v[24:25]
	v_mad_i64_i32 v[32:33], s[50:51], v32, s47, v[24:25]
	v_mad_i64_i32 v[78:79], s[50:51], v78, s47, v[24:25]
	v_mad_i64_i32 v[80:81], s[50:51], v80, s47, v[24:25]
	v_mad_i64_i32 v[82:83], s[50:51], v82, s47, v[24:25]
	v_mad_i64_i32 v[84:85], s[50:51], v84, s47, v[24:25]
	global_load_dword v99, v[26:27], off nt
	global_load_dword v100, v[28:29], off nt
	global_load_dword v101, v[30:31], off nt
	global_load_dword v102, v[32:33], off nt
	global_load_dword v103, v[78:79], off nt
	global_load_dword v104, v[80:81], off nt
	global_load_dword v105, v[82:83], off nt
	global_load_dword v106, v[84:85], off nt
	v_or_b32_e32 v26, s38, v63
	v_mad_i64_i32 v[26:27], s[50:51], v26, s47, v[24:25]
	v_or_b32_e32 v28, s38, v65
	v_or_b32_e32 v30, s38, v66
	v_or_b32_e32 v32, s38, v67
	v_or_b32_e32 v78, s38, v68
	v_or_b32_e32 v80, s38, v69
	v_or_b32_e32 v82, s38, v70
	v_or_b32_e32 v84, s38, v71
	v_mad_i64_i32 v[28:29], s[50:51], v28, s47, v[24:25]
	v_mad_i64_i32 v[30:31], s[50:51], v30, s47, v[24:25]
	v_mad_i64_i32 v[32:33], s[50:51], v32, s47, v[24:25]
	v_mad_i64_i32 v[78:79], s[50:51], v78, s47, v[24:25]
	v_mad_i64_i32 v[80:81], s[50:51], v80, s47, v[24:25]
	v_mad_i64_i32 v[82:83], s[50:51], v82, s47, v[24:25]
	v_mad_i64_i32 v[24:25], s[50:51], v84, s47, v[24:25]
	global_load_dword v84, v[26:27], off nt
	global_load_dword v85, v[28:29], off nt
	global_load_dword v107, v[30:31], off nt
	global_load_dword v108, v[32:33], off nt
	global_load_dword v109, v[78:79], off nt
	global_load_dword v110, v[80:81], off nt
	global_load_dword v111, v[82:83], off nt
	global_load_dword v112, v[24:25], off nt
	v_add_u32_e32 v24, v35, v36
	s_waitcnt vmcnt(0)
; #define LAS __attribute__((address_space(3)))
; __device__ __forceinline__ unsigned cvtpk(float lo, float hi) { typedef __bf16 bf2 __attribute__((ext_vector_type(2))); f32x2 v = {lo, hi}; bf2 b = __builtin_convertvector(v, bf2); return __builtin_bit_cast(unsigned, b); }
; __device__ __forceinline__ void transpose_item(const float* W, int K, int N, bf16_t* WT, int mode, LAS float* scr, int item, int lane) {
;     ...
;     for (int i = 0; i < 32; ++i) { const int kk = 2 * i + (lane >> 5); scr[kk * 33 + (lane & 31)] = W[(size_t)(k0 + kk) * N + n0 + (lane & 31)]; }
;     asm volatile("s_waitcnt lgkmcnt(0)" ::: "memory");
;     const int c = lane & 7;
; #pragma unroll
;     for (int j = 0; j < 4; ++j) { const int n = (lane >> 3) + 8 * j; const LAS float* s = scr + (8 * c) * 33 + n;
;         u32x4 o; o.x = cvtpk(s[0 * 33], s[1 * 33]); o.y = cvtpk(s[2 * 33], s[3 * 33]); o.z = cvtpk(s[4 * 33], s[5 * 33]); o.w = cvtpk(s[6 * 33], s[7 * 33]);
;         *(u32x4*)(WT + (size_t)wrow_map(mode, n0 + n) * K + k0 + 8 * c) = o; }
;     asm volatile("s_waitcnt lgkmcnt(0)" ::: "memory");
; __device__ __forceinline__ void convert_weights(PPtr P, int li, LAS unsigned char* lds, int gw, int NGW, int wave, int lane) {
;     ...
;     for (int it = gw; it < NIT; it += NGW) {
	ds_write2_b32 v24, v4, v23 offset1:66
	ds_write2_b32 v24, v77, v86 offset0:132 offset1:198
	v_add_u32_e32 v4, 0x400, v24
	ds_write2_b32 v4, v87, v88 offset0:8 offset1:74
	v_add_u32_e32 v4, v35, v43
	ds_write2_b32 v4, v89, v90 offset1:66
	ds_write2_b32 v4, v91, v92 offset0:132 offset1:198
	v_add_u32_e32 v4, 0x400, v4
	ds_write2_b32 v4, v93, v94 offset0:8 offset1:74
	v_add_u32_e32 v4, v35, v50
	ds_write2_b32 v4, v95, v96 offset1:66
	ds_write2_b32 v4, v97, v98 offset0:132 offset1:198
	v_add_u32_e32 v4, 0x400, v4
	v_add_u32_e32 v90, s36, v72
	s_ashr_i32 s39, s38, 31
	v_ashrrev_i32_e32 v91, 31, v90
	v_lshl_add_u64 v[88:89], s[38:39], 1, v[20:21]
	v_lshlrev_b64 v[92:93], 11, v[90:91]
	v_lshl_add_u64 v[92:93], v[88:89], 0, v[92:93]
	ds_write2_b32 v4, v99, v100 offset0:8 offset1:74
	v_add_u32_e32 v4, v35, v57
	ds_write2_b32 v4, v101, v102 offset1:66
	ds_write2_b32 v4, v103, v104 offset0:132 offset1:198
	v_add_u32_e32 v4, 0x400, v4
	ds_write2_b32 v4, v105, v106 offset0:8 offset1:74
	v_add_u32_e32 v4, v35, v64
	ds_write2_b32 v4, v84, v85 offset1:66
	ds_write2_b32 v4, v107, v108 offset0:132 offset1:198
	v_add_u32_e32 v4, 0x400, v4
	ds_write2_b32 v4, v109, v110 offset0:8 offset1:74
	ds_write2_b32 v4, v111, v112 offset0:140 offset1:206
	s_waitcnt lgkmcnt(0)
	ds_read2_b32 v[28:29], v73 offset0:33 offset1:41
	ds_read2_b32 v[30:31], v73 offset1:8
	ds_read2_b32 v[32:33], v73 offset0:66 offset1:74
	ds_read2_b32 v[78:79], v73 offset0:99 offset1:107
	ds_read2_b32 v[80:81], v73 offset0:132 offset1:140
	ds_read2_b32 v[82:83], v73 offset0:165 offset1:173
	ds_read2_b32 v[84:85], v73 offset0:198 offset1:206
	ds_read2_b32 v[86:87], v73 offset0:231 offset1:239
	s_waitcnt lgkmcnt(6)
	v_cvt_pk_bf16_f32 v24, v30, v28
	s_waitcnt lgkmcnt(4)
	v_cvt_pk_bf16_f32 v25, v32, v78
	s_waitcnt lgkmcnt(2)
	v_cvt_pk_bf16_f32 v26, v80, v82
	v_add_u32_e32 v28, 8, v90
	s_waitcnt lgkmcnt(0)
	v_cvt_pk_bf16_f32 v27, v84, v86
	global_store_dwordx4 v[92:93], v[24:27], off
	s_nop 1
	v_cvt_pk_bf16_f32 v24, v31, v29
	v_ashrrev_i32_e32 v29, 31, v28
	v_cvt_pk_bf16_f32 v25, v33, v79
	v_cvt_pk_bf16_f32 v26, v81, v83
	v_cvt_pk_bf16_f32 v27, v85, v87
	v_lshlrev_b64 v[28:29], 11, v[28:29]
	ds_read2_b32 v[30:31], v73 offset0:49 offset1:57
	ds_read2_b32 v[32:33], v73 offset0:16 offset1:24
	ds_read2_b32 v[78:79], v73 offset0:82 offset1:90
	ds_read2_b32 v[80:81], v73 offset0:115 offset1:123
	ds_read2_b32 v[82:83], v73 offset0:148 offset1:156
	ds_read2_b32 v[84:85], v73 offset0:181 offset1:189
	ds_read2_b32 v[86:87], v73 offset0:214 offset1:222
	ds_read2_b32 v[92:93], v73 offset0:247 offset1:255
	v_lshl_add_u64 v[28:29], v[88:89], 0, v[28:29]
	global_store_dwordx4 v[28:29], v[24:27], off
	v_add_u32_e32 v28, 16, v90
	v_ashrrev_i32_e32 v29, 31, v28
	v_lshlrev_b64 v[28:29], 11, v[28:29]
	s_waitcnt lgkmcnt(6)
	v_cvt_pk_bf16_f32 v24, v32, v30
	s_waitcnt lgkmcnt(4)
	v_cvt_pk_bf16_f32 v25, v78, v80
	s_waitcnt lgkmcnt(2)
	v_cvt_pk_bf16_f32 v26, v82, v84
	s_waitcnt lgkmcnt(0)
	v_cvt_pk_bf16_f32 v27, v86, v92
	v_lshl_add_u64 v[28:29], v[88:89], 0, v[28:29]
	global_store_dwordx4 v[28:29], v[24:27], off
	v_add_u32_e32 v28, 24, v90
	v_ashrrev_i32_e32 v29, 31, v28
	v_lshlrev_b64 v[28:29], 11, v[28:29]
	v_cvt_pk_bf16_f32 v24, v33, v31
	v_cvt_pk_bf16_f32 v25, v79, v81
	v_cvt_pk_bf16_f32 v26, v83, v85
	v_cvt_pk_bf16_f32 v27, v87, v93
	v_lshl_add_u64 v[28:29], v[88:89], 0, v[28:29]
	global_store_dwordx4 v[28:29], v[24:27], off
	s_waitcnt lgkmcnt(0)
	s_branch .LBB0_1444
